# MFMAs of each block reordered so the two k-steps of an accumulator are adjacent (SrcC forwarding), on top of classes 1:3 + peel + conv fast path + P0 row rebalance
# speedup vs baseline: 1.0119x; 1.0119x over previous
.LBB0_243:
	s_lshl_b32 s24, s12, 20
	s_and_b32 s24, s24, 0xff00000
	v_readlane_b32 s36, v248, 22
	v_readlane_b32 s37, v248, 23
	s_add_u32 s24, s36, s24
	s_addc_u32 s35, s37, 0
	s_lshr_b32 s36, s12, 13
	s_and_b32 s36, s36, 0x7ff80
	s_add_u32 s54, s24, s36
	s_addc_u32 s55, s35, 0
	s_lshl_b32 s24, s12, 12
	s_and_b32 s24, s24, 0xff00000
	v_readlane_b32 s38, v248, 24
	v_readlane_b32 s39, v248, 25
	s_add_u32 s24, s38, s24
	s_addc_u32 s35, s39, 0
	s_add_u32 s70, s24, s36
	s_addc_u32 s71, s35, 0
	s_cmp_lt_i32 s1, 1
	v_cmp_gt_i64_e64 s[72:73], s[12:13], -1
	s_cbranch_scc1 .LBB0_253
	s_and_b64 s[12:13], s[72:73], exec
	s_cselect_b32 s24, s55, s5
	s_cselect_b32 s35, s54, s4
	s_cselect_b32 s36, s71, s3
	s_cselect_b32 s37, s70, s2
	s_add_i32 s38, s1, -2
	s_add_u32 s4, s4, 0x80080
	s_addc_u32 s5, s5, 0
	s_add_u32 s39, s2, 0x100
	s_addc_u32 s40, s3, 0
	s_mov_b32 s2, 0
	v_add_u32_e32 v138, s29, v183
	ds_read_b128 v[144:147], v138
	ds_read_b128 v[148:151], v138 offset:1024
	ds_read_b128 v[152:155], v138 offset:2048
	ds_read_b128 v[156:159], v138 offset:3072
	v_add_u32_e32 v138, s34, v183
	ds_read_b128 v[160:163], v138
	ds_read_b128 v[164:167], v138 offset:1024
	ds_read_b128 v[186:189], v138 offset:2048
	ds_read_b128 v[190:193], v138 offset:3072
	s_add_i32 s41, s2, 2
	s_add_u32 s3, s4, 0xfff80080
	s_addc_u32 s12, s5, -1
	s_cmp_eq_u32 s38, s2
	s_cselect_b32 s2, s37, s39
	s_cselect_b32 s13, s24, s12
	s_cselect_b32 s12, s35, s3
	s_cselect_b32 s3, s36, s40
	v_lshl_add_u64 v[228:229], s[4:5], 0, v[140:141]
	s_add_i32 m0, s17, 0xc000
	ds_read_b128 v[194:197], v185
	ds_read_b128 v[198:201], v185 offset:1024
	ds_read_b128 v[202:205], v185 offset:2048
	ds_read_b128 v[208:211], v185 offset:3072
	ds_read_b128 v[212:215], v185 offset:4096
	ds_read_b128 v[216:219], v185 offset:5120
	ds_read_b128 v[220:223], v185 offset:6144
	ds_read_b128 v[224:227], v185 offset:7168
	global_load_lds_dwordx4 v[228:229], off
	v_lshl_add_u64 v[228:229], s[4:5], 0, v[142:143]
	s_add_i32 m0, s17, 0xe000
	s_nop 0
	global_load_lds_dwordx4 v[228:229], off
	s_waitcnt vmcnt(8)
	s_waitcnt lgkmcnt(0)
	s_barrier
	s_setprio 1
	s_waitcnt lgkmcnt(0)
	v_mfma_i32_16x16x64_i8 v[126:129], v[144:147], v[194:197], 0
	v_mfma_i32_16x16x64_i8 v[126:129], v[148:151], v[198:201], v[126:129]
	v_mfma_i32_16x16x64_i8 v[122:125], v[152:155], v[194:197], 0
	v_mfma_i32_16x16x64_i8 v[122:125], v[156:159], v[198:201], v[122:125]
	v_mfma_i32_16x16x64_i8 v[118:121], v[144:147], v[202:205], 0
	v_mfma_i32_16x16x64_i8 v[118:121], v[148:151], v[208:211], v[118:121]
	v_mfma_i32_16x16x64_i8 v[114:117], v[152:155], v[202:205], 0
	v_mfma_i32_16x16x64_i8 v[114:117], v[156:159], v[208:211], v[114:117]
	v_mfma_i32_16x16x64_i8 v[110:113], v[144:147], v[212:215], 0
	v_mfma_i32_16x16x64_i8 v[110:113], v[148:151], v[216:219], v[110:113]
	v_mfma_i32_16x16x64_i8 v[106:109], v[152:155], v[212:215], 0
	v_mfma_i32_16x16x64_i8 v[106:109], v[156:159], v[216:219], v[106:109]
	v_mfma_i32_16x16x64_i8 v[102:105], v[144:147], v[220:223], 0
	v_mfma_i32_16x16x64_i8 v[102:105], v[148:151], v[224:227], v[102:105]
	v_mfma_i32_16x16x64_i8 v[98:101], v[152:155], v[220:223], 0
	v_mfma_i32_16x16x64_i8 v[98:101], v[156:159], v[224:227], v[98:101]
	s_setprio 0
	s_setprio 1
	v_mfma_i32_16x16x64_i8 v[94:97], v[160:163], v[194:197], 0
	v_mfma_i32_16x16x64_i8 v[94:97], v[164:167], v[198:201], v[94:97]
	v_mfma_i32_16x16x64_i8 v[90:93], v[186:189], v[194:197], 0
	v_mfma_i32_16x16x64_i8 v[90:93], v[190:193], v[198:201], v[90:93]
	v_mfma_i32_16x16x64_i8 v[86:89], v[160:163], v[202:205], 0
	v_mfma_i32_16x16x64_i8 v[86:89], v[164:167], v[208:211], v[86:89]
	v_mfma_i32_16x16x64_i8 v[82:85], v[186:189], v[202:205], 0
	v_mfma_i32_16x16x64_i8 v[82:85], v[190:193], v[208:211], v[82:85]
	v_mfma_i32_16x16x64_i8 v[78:81], v[160:163], v[212:215], 0
	v_mfma_i32_16x16x64_i8 v[78:81], v[164:167], v[216:219], v[78:81]
	v_mfma_i32_16x16x64_i8 v[74:77], v[186:189], v[212:215], 0
	v_mfma_i32_16x16x64_i8 v[74:77], v[190:193], v[216:219], v[74:77]
	v_mfma_i32_16x16x64_i8 v[70:73], v[160:163], v[220:223], 0
	v_mfma_i32_16x16x64_i8 v[70:73], v[164:167], v[224:227], v[70:73]
	v_mfma_i32_16x16x64_i8 v[66:69], v[186:189], v[220:223], 0
	v_mfma_i32_16x16x64_i8 v[66:69], v[190:193], v[224:227], v[66:69]
	s_setprio 0
	s_barrier
	s_add_i32 s42, s29, s16
	v_lshl_add_u64 v[228:229], s[2:3], 0, v[132:133]
	s_mov_b32 m0, s42
	ds_read_b128 v[194:197], v185 offset:16384
	ds_read_b128 v[198:201], v185 offset:17408
	ds_read_b128 v[202:205], v185 offset:18432
	ds_read_b128 v[208:211], v185 offset:19456
	ds_read_b128 v[212:215], v185 offset:20480
	ds_read_b128 v[216:219], v185 offset:21504
	ds_read_b128 v[220:223], v185 offset:22528
	ds_read_b128 v[224:227], v185 offset:23552
	global_load_lds_dwordx4 v[228:229], off
	s_add_i32 m0, s42, 0x2000
	s_add_u32 s42, s2, 0x80000
	v_lshl_add_u64 v[230:231], s[2:3], 0, v[136:137]
	s_addc_u32 s43, s3, 0
	s_add_i32 s44, s34, s16
	global_load_lds_dwordx4 v[230:231], off
	v_lshl_add_u64 v[232:233], s[42:43], 0, v[132:133]
	s_mov_b32 m0, s44
	v_lshl_add_u64 v[234:235], s[12:13], 0, v[134:135]
	global_load_lds_dwordx4 v[232:233], off
	v_lshl_add_u64 v[232:233], s[42:43], 0, v[136:137]
	s_add_i32 m0, s44, 0x2000
	s_nop 0
	global_load_lds_dwordx4 v[232:233], off
	v_lshl_add_u64 v[232:233], s[12:13], 0, v[130:131]
	s_mov_b32 m0, s17
	s_nop 0
	global_load_lds_dwordx4 v[232:233], off
	s_mov_b32 m0, s18
	s_nop 0
	global_load_lds_dwordx4 v[234:235], off
	s_waitcnt vmcnt(8)
	s_waitcnt lgkmcnt(0)
	s_barrier
	s_setprio 1
	s_waitcnt lgkmcnt(0)
	v_mfma_i32_16x16x64_i8 v[62:65], v[144:147], v[194:197], 0
	v_mfma_i32_16x16x64_i8 v[62:65], v[148:151], v[198:201], v[62:65]
	v_mfma_i32_16x16x64_i8 v[58:61], v[152:155], v[194:197], 0
	v_mfma_i32_16x16x64_i8 v[58:61], v[156:159], v[198:201], v[58:61]
	v_mfma_i32_16x16x64_i8 v[54:57], v[144:147], v[202:205], 0
	v_mfma_i32_16x16x64_i8 v[54:57], v[148:151], v[208:211], v[54:57]
	v_mfma_i32_16x16x64_i8 v[50:53], v[152:155], v[202:205], 0
	v_mfma_i32_16x16x64_i8 v[50:53], v[156:159], v[208:211], v[50:53]
	v_mfma_i32_16x16x64_i8 v[46:49], v[144:147], v[212:215], 0
	v_mfma_i32_16x16x64_i8 v[46:49], v[148:151], v[216:219], v[46:49]
	v_mfma_i32_16x16x64_i8 v[42:45], v[152:155], v[212:215], 0
	v_mfma_i32_16x16x64_i8 v[42:45], v[156:159], v[216:219], v[42:45]
	v_mfma_i32_16x16x64_i8 v[38:41], v[144:147], v[220:223], 0
	v_mfma_i32_16x16x64_i8 v[38:41], v[148:151], v[224:227], v[38:41]
	v_mfma_i32_16x16x64_i8 v[34:37], v[152:155], v[220:223], 0
	v_mfma_i32_16x16x64_i8 v[34:37], v[156:159], v[224:227], v[34:37]
	s_setprio 0
	s_setprio 1
	v_mfma_i32_16x16x64_i8 v[30:33], v[160:163], v[194:197], 0
	v_mfma_i32_16x16x64_i8 v[30:33], v[164:167], v[198:201], v[30:33]
	v_mfma_i32_16x16x64_i8 v[26:29], v[186:189], v[194:197], 0
	v_mfma_i32_16x16x64_i8 v[26:29], v[190:193], v[198:201], v[26:29]
	v_mfma_i32_16x16x64_i8 v[22:25], v[160:163], v[202:205], 0
	v_mfma_i32_16x16x64_i8 v[22:25], v[164:167], v[208:211], v[22:25]
	v_mfma_i32_16x16x64_i8 v[18:21], v[186:189], v[202:205], 0
	v_mfma_i32_16x16x64_i8 v[18:21], v[190:193], v[208:211], v[18:21]
	v_mfma_i32_16x16x64_i8 v[14:17], v[160:163], v[212:215], 0
	v_mfma_i32_16x16x64_i8 v[14:17], v[164:167], v[216:219], v[14:17]
	v_mfma_i32_16x16x64_i8 v[10:13], v[186:189], v[212:215], 0
	v_mfma_i32_16x16x64_i8 v[10:13], v[190:193], v[216:219], v[10:13]
	v_mfma_i32_16x16x64_i8 v[6:9], v[160:163], v[220:223], 0
	v_mfma_i32_16x16x64_i8 v[6:9], v[164:167], v[224:227], v[6:9]
	v_mfma_i32_16x16x64_i8 v[2:5], v[186:189], v[220:223], 0
	v_mfma_i32_16x16x64_i8 v[2:5], v[190:193], v[224:227], v[2:5]
	s_setprio 0
	s_barrier
	s_add_i32 s42, 0, 0x18000
	v_add_u32_e32 v138, s42, v183
	s_add_i32 s43, 0, 0x1c000
	ds_read_b128 v[144:147], v138
	ds_read_b128 v[148:151], v138 offset:1024
	ds_read_b128 v[152:155], v138 offset:2048
	ds_read_b128 v[156:159], v138 offset:3072
	v_add_u32_e32 v138, s43, v183
	ds_read_b128 v[160:163], v138
	ds_read_b128 v[164:167], v138 offset:1024
	ds_read_b128 v[186:189], v138 offset:2048
	ds_read_b128 v[190:193], v138 offset:3072
	s_add_u32 s12, s12, 0x80000
	s_addc_u32 s13, s13, 0
	s_mov_b32 m0, s19
	v_lshl_add_u64 v[236:237], s[12:13], 0, v[130:131]
	ds_read_b128 v[194:197], v185 offset:32768
	ds_read_b128 v[198:201], v185 offset:33792
	ds_read_b128 v[202:205], v185 offset:34816
	ds_read_b128 v[208:211], v185 offset:35840
	ds_read_b128 v[212:215], v185 offset:36864
	ds_read_b128 v[216:219], v185 offset:37888
	ds_read_b128 v[220:223], v185 offset:38912
	ds_read_b128 v[224:227], v185 offset:39936
	global_load_lds_dwordx4 v[236:237], off
	v_lshl_add_u64 v[236:237], s[12:13], 0, v[134:135]
	s_mov_b32 m0, s20
	s_nop 0
	global_load_lds_dwordx4 v[236:237], off
	s_waitcnt vmcnt(8)
	s_waitcnt lgkmcnt(0)
	s_barrier
	s_setprio 1
	s_waitcnt lgkmcnt(0)
	v_mfma_i32_16x16x64_i8 v[126:129], v[144:147], v[194:197], v[126:129]
	v_mfma_i32_16x16x64_i8 v[126:129], v[148:151], v[198:201], v[126:129]
	v_mfma_i32_16x16x64_i8 v[122:125], v[152:155], v[194:197], v[122:125]
	v_mfma_i32_16x16x64_i8 v[122:125], v[156:159], v[198:201], v[122:125]
	v_mfma_i32_16x16x64_i8 v[118:121], v[144:147], v[202:205], v[118:121]
	v_mfma_i32_16x16x64_i8 v[118:121], v[148:151], v[208:211], v[118:121]
	v_mfma_i32_16x16x64_i8 v[114:117], v[152:155], v[202:205], v[114:117]
	v_mfma_i32_16x16x64_i8 v[114:117], v[156:159], v[208:211], v[114:117]
	v_mfma_i32_16x16x64_i8 v[110:113], v[144:147], v[212:215], v[110:113]
	v_mfma_i32_16x16x64_i8 v[110:113], v[148:151], v[216:219], v[110:113]
	v_mfma_i32_16x16x64_i8 v[106:109], v[152:155], v[212:215], v[106:109]
	v_mfma_i32_16x16x64_i8 v[106:109], v[156:159], v[216:219], v[106:109]
	v_mfma_i32_16x16x64_i8 v[102:105], v[144:147], v[220:223], v[102:105]
	v_mfma_i32_16x16x64_i8 v[102:105], v[148:151], v[224:227], v[102:105]
	v_mfma_i32_16x16x64_i8 v[98:101], v[152:155], v[220:223], v[98:101]
	v_mfma_i32_16x16x64_i8 v[98:101], v[156:159], v[224:227], v[98:101]
	s_setprio 0
	s_setprio 1
	v_mfma_i32_16x16x64_i8 v[94:97], v[160:163], v[194:197], v[94:97]
	v_mfma_i32_16x16x64_i8 v[94:97], v[164:167], v[198:201], v[94:97]
	v_mfma_i32_16x16x64_i8 v[90:93], v[186:189], v[194:197], v[90:93]
	v_mfma_i32_16x16x64_i8 v[90:93], v[190:193], v[198:201], v[90:93]
	v_mfma_i32_16x16x64_i8 v[86:89], v[160:163], v[202:205], v[86:89]
	v_mfma_i32_16x16x64_i8 v[86:89], v[164:167], v[208:211], v[86:89]
	v_mfma_i32_16x16x64_i8 v[82:85], v[186:189], v[202:205], v[82:85]
	v_mfma_i32_16x16x64_i8 v[82:85], v[190:193], v[208:211], v[82:85]
	v_mfma_i32_16x16x64_i8 v[78:81], v[160:163], v[212:215], v[78:81]
	v_mfma_i32_16x16x64_i8 v[78:81], v[164:167], v[216:219], v[78:81]
	v_mfma_i32_16x16x64_i8 v[74:77], v[186:189], v[212:215], v[74:77]
	v_mfma_i32_16x16x64_i8 v[74:77], v[190:193], v[216:219], v[74:77]
	v_mfma_i32_16x16x64_i8 v[70:73], v[160:163], v[220:223], v[70:73]
	v_mfma_i32_16x16x64_i8 v[70:73], v[164:167], v[224:227], v[70:73]
	v_mfma_i32_16x16x64_i8 v[66:69], v[186:189], v[220:223], v[66:69]
	v_mfma_i32_16x16x64_i8 v[66:69], v[190:193], v[224:227], v[66:69]
	s_setprio 0
	s_barrier
	s_add_i32 s12, s42, s16
	v_lshl_add_u64 v[228:229], v[228:229], 0, s[10:11]
	s_mov_b32 m0, s12
	ds_read_b128 v[194:197], v185 offset:49152
	ds_read_b128 v[198:201], v185 offset:50176
	ds_read_b128 v[202:205], v185 offset:51200
	ds_read_b128 v[208:211], v185 offset:52224
	ds_read_b128 v[212:215], v185 offset:53248
	ds_read_b128 v[216:219], v185 offset:54272
	ds_read_b128 v[220:223], v185 offset:55296
	ds_read_b128 v[224:227], v185 offset:56320
	global_load_lds_dwordx4 v[228:229], off
	s_add_i32 m0, s12, 0x2000
	s_add_u32 s2, s2, 0x80080
	v_lshl_add_u64 v[228:229], v[230:231], 0, s[10:11]
	s_addc_u32 s3, s3, 0
	s_add_i32 s12, s43, s16
	global_load_lds_dwordx4 v[228:229], off
	v_lshl_add_u64 v[228:229], s[2:3], 0, v[132:133]
	s_mov_b32 m0, s12
	s_nop 0
	global_load_lds_dwordx4 v[228:229], off
	v_lshl_add_u64 v[228:229], s[2:3], 0, v[136:137]
	s_add_i32 m0, s12, 0x2000
	s_nop 0
	global_load_lds_dwordx4 v[228:229], off
	v_lshl_add_u64 v[228:229], v[232:233], 0, s[10:11]
	s_mov_b32 m0, s22
	s_nop 0
	global_load_lds_dwordx4 v[228:229], off
	v_lshl_add_u64 v[228:229], v[234:235], 0, s[10:11]
	s_mov_b32 m0, s23
	s_nop 0
	global_load_lds_dwordx4 v[228:229], off
	s_waitcnt vmcnt(8)
	s_waitcnt lgkmcnt(0)
	s_barrier
	s_setprio 1
	s_waitcnt lgkmcnt(0)
	v_mfma_i32_16x16x64_i8 v[62:65], v[144:147], v[194:197], v[62:65]
	v_mfma_i32_16x16x64_i8 v[62:65], v[148:151], v[198:201], v[62:65]
	v_mfma_i32_16x16x64_i8 v[58:61], v[152:155], v[194:197], v[58:61]
	v_mfma_i32_16x16x64_i8 v[58:61], v[156:159], v[198:201], v[58:61]
	v_mfma_i32_16x16x64_i8 v[54:57], v[144:147], v[202:205], v[54:57]
	v_mfma_i32_16x16x64_i8 v[54:57], v[148:151], v[208:211], v[54:57]
	v_mfma_i32_16x16x64_i8 v[50:53], v[152:155], v[202:205], v[50:53]
	v_mfma_i32_16x16x64_i8 v[50:53], v[156:159], v[208:211], v[50:53]
	v_mfma_i32_16x16x64_i8 v[46:49], v[144:147], v[212:215], v[46:49]
	v_mfma_i32_16x16x64_i8 v[46:49], v[148:151], v[216:219], v[46:49]
	v_mfma_i32_16x16x64_i8 v[42:45], v[152:155], v[212:215], v[42:45]
	v_mfma_i32_16x16x64_i8 v[42:45], v[156:159], v[216:219], v[42:45]
	v_mfma_i32_16x16x64_i8 v[38:41], v[144:147], v[220:223], v[38:41]
	v_mfma_i32_16x16x64_i8 v[38:41], v[148:151], v[224:227], v[38:41]
	v_mfma_i32_16x16x64_i8 v[34:37], v[152:155], v[220:223], v[34:37]
	v_mfma_i32_16x16x64_i8 v[34:37], v[156:159], v[224:227], v[34:37]
	s_setprio 0
	s_setprio 1
	v_mfma_i32_16x16x64_i8 v[30:33], v[160:163], v[194:197], v[30:33]
	v_mfma_i32_16x16x64_i8 v[30:33], v[164:167], v[198:201], v[30:33]
	v_mfma_i32_16x16x64_i8 v[26:29], v[186:189], v[194:197], v[26:29]
	v_mfma_i32_16x16x64_i8 v[26:29], v[190:193], v[198:201], v[26:29]
	v_mfma_i32_16x16x64_i8 v[22:25], v[160:163], v[202:205], v[22:25]
	v_mfma_i32_16x16x64_i8 v[22:25], v[164:167], v[208:211], v[22:25]
	v_mfma_i32_16x16x64_i8 v[18:21], v[186:189], v[202:205], v[18:21]
	v_mfma_i32_16x16x64_i8 v[18:21], v[190:193], v[208:211], v[18:21]
	v_mfma_i32_16x16x64_i8 v[14:17], v[160:163], v[212:215], v[14:17]
	v_mfma_i32_16x16x64_i8 v[14:17], v[164:167], v[216:219], v[14:17]
	v_mfma_i32_16x16x64_i8 v[10:13], v[186:189], v[212:215], v[10:13]
	v_mfma_i32_16x16x64_i8 v[10:13], v[190:193], v[216:219], v[10:13]
	v_mfma_i32_16x16x64_i8 v[6:9], v[160:163], v[220:223], v[6:9]
	v_mfma_i32_16x16x64_i8 v[6:9], v[164:167], v[224:227], v[6:9]
	v_mfma_i32_16x16x64_i8 v[2:5], v[186:189], v[220:223], v[2:5]
	v_mfma_i32_16x16x64_i8 v[2:5], v[190:193], v[224:227], v[2:5]
	s_setprio 0
	s_barrier
	s_add_u32 s4, s4, 0x100
	s_addc_u32 s5, s5, 0
	s_add_u32 s39, s39, 0x100
	s_addc_u32 s40, s40, 0
	s_cmp_ge_i32 s41, s1
	s_mov_b32 s2, s41
	s_cbranch_scc1 .Lkpeel_exit_0
.LBB0_245:
	v_add_u32_e32 v138, s29, v183
	ds_read_b128 v[144:147], v138
	ds_read_b128 v[148:151], v138 offset:1024
	ds_read_b128 v[152:155], v138 offset:2048
	ds_read_b128 v[156:159], v138 offset:3072
	v_add_u32_e32 v138, s34, v183
	ds_read_b128 v[160:163], v138
	ds_read_b128 v[164:167], v138 offset:1024
	ds_read_b128 v[186:189], v138 offset:2048
	ds_read_b128 v[190:193], v138 offset:3072
	s_add_i32 s41, s2, 2
	s_add_u32 s3, s4, 0xfff80080
	s_addc_u32 s12, s5, -1
	s_cmp_eq_u32 s38, s2
	s_cselect_b32 s2, s37, s39
	s_cselect_b32 s13, s24, s12
	s_cselect_b32 s12, s35, s3
	s_cselect_b32 s3, s36, s40
	v_lshl_add_u64 v[228:229], s[4:5], 0, v[140:141]
	s_add_i32 m0, s17, 0xc000
	ds_read_b128 v[194:197], v185
	ds_read_b128 v[198:201], v185 offset:1024
	ds_read_b128 v[202:205], v185 offset:2048
	ds_read_b128 v[208:211], v185 offset:3072
	ds_read_b128 v[212:215], v185 offset:4096
	ds_read_b128 v[216:219], v185 offset:5120
	ds_read_b128 v[220:223], v185 offset:6144
	ds_read_b128 v[224:227], v185 offset:7168
	global_load_lds_dwordx4 v[228:229], off
	v_lshl_add_u64 v[228:229], s[4:5], 0, v[142:143]
	s_add_i32 m0, s17, 0xe000
	s_nop 0
	global_load_lds_dwordx4 v[228:229], off
	s_waitcnt vmcnt(8)
	s_waitcnt lgkmcnt(0)
	s_barrier
	s_setprio 1
	s_waitcnt lgkmcnt(0)
	v_mfma_i32_16x16x64_i8 v[126:129], v[144:147], v[194:197], v[126:129]
	v_mfma_i32_16x16x64_i8 v[126:129], v[148:151], v[198:201], v[126:129]
	v_mfma_i32_16x16x64_i8 v[122:125], v[152:155], v[194:197], v[122:125]
	v_mfma_i32_16x16x64_i8 v[122:125], v[156:159], v[198:201], v[122:125]
	v_mfma_i32_16x16x64_i8 v[118:121], v[144:147], v[202:205], v[118:121]
	v_mfma_i32_16x16x64_i8 v[118:121], v[148:151], v[208:211], v[118:121]
	v_mfma_i32_16x16x64_i8 v[114:117], v[152:155], v[202:205], v[114:117]
	v_mfma_i32_16x16x64_i8 v[114:117], v[156:159], v[208:211], v[114:117]
	v_mfma_i32_16x16x64_i8 v[110:113], v[144:147], v[212:215], v[110:113]
	v_mfma_i32_16x16x64_i8 v[110:113], v[148:151], v[216:219], v[110:113]
	v_mfma_i32_16x16x64_i8 v[106:109], v[152:155], v[212:215], v[106:109]
	v_mfma_i32_16x16x64_i8 v[106:109], v[156:159], v[216:219], v[106:109]
	v_mfma_i32_16x16x64_i8 v[102:105], v[144:147], v[220:223], v[102:105]
	v_mfma_i32_16x16x64_i8 v[102:105], v[148:151], v[224:227], v[102:105]
	v_mfma_i32_16x16x64_i8 v[98:101], v[152:155], v[220:223], v[98:101]
	v_mfma_i32_16x16x64_i8 v[98:101], v[156:159], v[224:227], v[98:101]
	s_setprio 0
	s_setprio 1
	v_mfma_i32_16x16x64_i8 v[94:97], v[160:163], v[194:197], v[94:97]
	v_mfma_i32_16x16x64_i8 v[94:97], v[164:167], v[198:201], v[94:97]
	v_mfma_i32_16x16x64_i8 v[90:93], v[186:189], v[194:197], v[90:93]
	v_mfma_i32_16x16x64_i8 v[90:93], v[190:193], v[198:201], v[90:93]
	v_mfma_i32_16x16x64_i8 v[86:89], v[160:163], v[202:205], v[86:89]
	v_mfma_i32_16x16x64_i8 v[86:89], v[164:167], v[208:211], v[86:89]
	v_mfma_i32_16x16x64_i8 v[82:85], v[186:189], v[202:205], v[82:85]
	v_mfma_i32_16x16x64_i8 v[82:85], v[190:193], v[208:211], v[82:85]
	v_mfma_i32_16x16x64_i8 v[78:81], v[160:163], v[212:215], v[78:81]
	v_mfma_i32_16x16x64_i8 v[78:81], v[164:167], v[216:219], v[78:81]
	v_mfma_i32_16x16x64_i8 v[74:77], v[186:189], v[212:215], v[74:77]
	v_mfma_i32_16x16x64_i8 v[74:77], v[190:193], v[216:219], v[74:77]
	v_mfma_i32_16x16x64_i8 v[70:73], v[160:163], v[220:223], v[70:73]
	v_mfma_i32_16x16x64_i8 v[70:73], v[164:167], v[224:227], v[70:73]
	v_mfma_i32_16x16x64_i8 v[66:69], v[186:189], v[220:223], v[66:69]
	v_mfma_i32_16x16x64_i8 v[66:69], v[190:193], v[224:227], v[66:69]
	s_setprio 0
	s_barrier
	s_add_i32 s42, s29, s16
	v_lshl_add_u64 v[228:229], s[2:3], 0, v[132:133]
	s_mov_b32 m0, s42
	ds_read_b128 v[194:197], v185 offset:16384
	ds_read_b128 v[198:201], v185 offset:17408
	ds_read_b128 v[202:205], v185 offset:18432
	ds_read_b128 v[208:211], v185 offset:19456
	ds_read_b128 v[212:215], v185 offset:20480
	ds_read_b128 v[216:219], v185 offset:21504
	ds_read_b128 v[220:223], v185 offset:22528
	ds_read_b128 v[224:227], v185 offset:23552
	global_load_lds_dwordx4 v[228:229], off
	s_add_i32 m0, s42, 0x2000
	s_add_u32 s42, s2, 0x80000
	v_lshl_add_u64 v[230:231], s[2:3], 0, v[136:137]
	s_addc_u32 s43, s3, 0
	s_add_i32 s44, s34, s16
	global_load_lds_dwordx4 v[230:231], off
	v_lshl_add_u64 v[232:233], s[42:43], 0, v[132:133]
	s_mov_b32 m0, s44
	v_lshl_add_u64 v[234:235], s[12:13], 0, v[134:135]
	global_load_lds_dwordx4 v[232:233], off
	v_lshl_add_u64 v[232:233], s[42:43], 0, v[136:137]
	s_add_i32 m0, s44, 0x2000
	s_nop 0
	global_load_lds_dwordx4 v[232:233], off
	v_lshl_add_u64 v[232:233], s[12:13], 0, v[130:131]
	s_mov_b32 m0, s17
	s_nop 0
	global_load_lds_dwordx4 v[232:233], off
	s_mov_b32 m0, s18
	s_nop 0
	global_load_lds_dwordx4 v[234:235], off
	s_waitcnt vmcnt(8)
	s_waitcnt lgkmcnt(0)
	s_barrier
	s_setprio 1
	s_waitcnt lgkmcnt(0)
	v_mfma_i32_16x16x64_i8 v[62:65], v[144:147], v[194:197], v[62:65]
	v_mfma_i32_16x16x64_i8 v[62:65], v[148:151], v[198:201], v[62:65]
	v_mfma_i32_16x16x64_i8 v[58:61], v[152:155], v[194:197], v[58:61]
	v_mfma_i32_16x16x64_i8 v[58:61], v[156:159], v[198:201], v[58:61]
	v_mfma_i32_16x16x64_i8 v[54:57], v[144:147], v[202:205], v[54:57]
	v_mfma_i32_16x16x64_i8 v[54:57], v[148:151], v[208:211], v[54:57]
	v_mfma_i32_16x16x64_i8 v[50:53], v[152:155], v[202:205], v[50:53]
	v_mfma_i32_16x16x64_i8 v[50:53], v[156:159], v[208:211], v[50:53]
	v_mfma_i32_16x16x64_i8 v[46:49], v[144:147], v[212:215], v[46:49]
	v_mfma_i32_16x16x64_i8 v[46:49], v[148:151], v[216:219], v[46:49]
	v_mfma_i32_16x16x64_i8 v[42:45], v[152:155], v[212:215], v[42:45]
	v_mfma_i32_16x16x64_i8 v[42:45], v[156:159], v[216:219], v[42:45]
	v_mfma_i32_16x16x64_i8 v[38:41], v[144:147], v[220:223], v[38:41]
	v_mfma_i32_16x16x64_i8 v[38:41], v[148:151], v[224:227], v[38:41]
	v_mfma_i32_16x16x64_i8 v[34:37], v[152:155], v[220:223], v[34:37]
	v_mfma_i32_16x16x64_i8 v[34:37], v[156:159], v[224:227], v[34:37]
	s_setprio 0
	s_setprio 1
	v_mfma_i32_16x16x64_i8 v[30:33], v[160:163], v[194:197], v[30:33]
	v_mfma_i32_16x16x64_i8 v[30:33], v[164:167], v[198:201], v[30:33]
	v_mfma_i32_16x16x64_i8 v[26:29], v[186:189], v[194:197], v[26:29]
	v_mfma_i32_16x16x64_i8 v[26:29], v[190:193], v[198:201], v[26:29]
	v_mfma_i32_16x16x64_i8 v[22:25], v[160:163], v[202:205], v[22:25]
	v_mfma_i32_16x16x64_i8 v[22:25], v[164:167], v[208:211], v[22:25]
	v_mfma_i32_16x16x64_i8 v[18:21], v[186:189], v[202:205], v[18:21]
	v_mfma_i32_16x16x64_i8 v[18:21], v[190:193], v[208:211], v[18:21]
	v_mfma_i32_16x16x64_i8 v[14:17], v[160:163], v[212:215], v[14:17]
	v_mfma_i32_16x16x64_i8 v[14:17], v[164:167], v[216:219], v[14:17]
	v_mfma_i32_16x16x64_i8 v[10:13], v[186:189], v[212:215], v[10:13]
	v_mfma_i32_16x16x64_i8 v[10:13], v[190:193], v[216:219], v[10:13]
	v_mfma_i32_16x16x64_i8 v[6:9], v[160:163], v[220:223], v[6:9]
	v_mfma_i32_16x16x64_i8 v[6:9], v[164:167], v[224:227], v[6:9]
	v_mfma_i32_16x16x64_i8 v[2:5], v[186:189], v[220:223], v[2:5]
	v_mfma_i32_16x16x64_i8 v[2:5], v[190:193], v[224:227], v[2:5]
	s_setprio 0
	s_barrier
	s_add_i32 s42, 0, 0x18000
	v_add_u32_e32 v138, s42, v183
	s_add_i32 s43, 0, 0x1c000
	ds_read_b128 v[144:147], v138
	ds_read_b128 v[148:151], v138 offset:1024
	ds_read_b128 v[152:155], v138 offset:2048
	ds_read_b128 v[156:159], v138 offset:3072
	v_add_u32_e32 v138, s43, v183
	ds_read_b128 v[160:163], v138
	ds_read_b128 v[164:167], v138 offset:1024
	ds_read_b128 v[186:189], v138 offset:2048
	ds_read_b128 v[190:193], v138 offset:3072
	s_add_u32 s12, s12, 0x80000
	s_addc_u32 s13, s13, 0
	s_mov_b32 m0, s19
	v_lshl_add_u64 v[236:237], s[12:13], 0, v[130:131]
	ds_read_b128 v[194:197], v185 offset:32768
	ds_read_b128 v[198:201], v185 offset:33792
	ds_read_b128 v[202:205], v185 offset:34816
	ds_read_b128 v[208:211], v185 offset:35840
	ds_read_b128 v[212:215], v185 offset:36864
	ds_read_b128 v[216:219], v185 offset:37888
	ds_read_b128 v[220:223], v185 offset:38912
	ds_read_b128 v[224:227], v185 offset:39936
	global_load_lds_dwordx4 v[236:237], off
	v_lshl_add_u64 v[236:237], s[12:13], 0, v[134:135]
	s_mov_b32 m0, s20
	s_nop 0
	global_load_lds_dwordx4 v[236:237], off
	s_waitcnt vmcnt(8)
	s_waitcnt lgkmcnt(0)
	s_barrier
	s_setprio 1
	s_waitcnt lgkmcnt(0)
	v_mfma_i32_16x16x64_i8 v[126:129], v[144:147], v[194:197], v[126:129]
	v_mfma_i32_16x16x64_i8 v[126:129], v[148:151], v[198:201], v[126:129]
	v_mfma_i32_16x16x64_i8 v[122:125], v[152:155], v[194:197], v[122:125]
	v_mfma_i32_16x16x64_i8 v[122:125], v[156:159], v[198:201], v[122:125]
	v_mfma_i32_16x16x64_i8 v[118:121], v[144:147], v[202:205], v[118:121]
	v_mfma_i32_16x16x64_i8 v[118:121], v[148:151], v[208:211], v[118:121]
	v_mfma_i32_16x16x64_i8 v[114:117], v[152:155], v[202:205], v[114:117]
	v_mfma_i32_16x16x64_i8 v[114:117], v[156:159], v[208:211], v[114:117]
	v_mfma_i32_16x16x64_i8 v[110:113], v[144:147], v[212:215], v[110:113]
	v_mfma_i32_16x16x64_i8 v[110:113], v[148:151], v[216:219], v[110:113]
	v_mfma_i32_16x16x64_i8 v[106:109], v[152:155], v[212:215], v[106:109]
	v_mfma_i32_16x16x64_i8 v[106:109], v[156:159], v[216:219], v[106:109]
	v_mfma_i32_16x16x64_i8 v[102:105], v[144:147], v[220:223], v[102:105]
	v_mfma_i32_16x16x64_i8 v[102:105], v[148:151], v[224:227], v[102:105]
	v_mfma_i32_16x16x64_i8 v[98:101], v[152:155], v[220:223], v[98:101]
	v_mfma_i32_16x16x64_i8 v[98:101], v[156:159], v[224:227], v[98:101]
	s_setprio 0
	s_setprio 1
	v_mfma_i32_16x16x64_i8 v[94:97], v[160:163], v[194:197], v[94:97]
	v_mfma_i32_16x16x64_i8 v[94:97], v[164:167], v[198:201], v[94:97]
	v_mfma_i32_16x16x64_i8 v[90:93], v[186:189], v[194:197], v[90:93]
	v_mfma_i32_16x16x64_i8 v[90:93], v[190:193], v[198:201], v[90:93]
	v_mfma_i32_16x16x64_i8 v[86:89], v[160:163], v[202:205], v[86:89]
	v_mfma_i32_16x16x64_i8 v[86:89], v[164:167], v[208:211], v[86:89]
	v_mfma_i32_16x16x64_i8 v[82:85], v[186:189], v[202:205], v[82:85]
	v_mfma_i32_16x16x64_i8 v[82:85], v[190:193], v[208:211], v[82:85]
	v_mfma_i32_16x16x64_i8 v[78:81], v[160:163], v[212:215], v[78:81]
	v_mfma_i32_16x16x64_i8 v[78:81], v[164:167], v[216:219], v[78:81]
	v_mfma_i32_16x16x64_i8 v[74:77], v[186:189], v[212:215], v[74:77]
	v_mfma_i32_16x16x64_i8 v[74:77], v[190:193], v[216:219], v[74:77]
	v_mfma_i32_16x16x64_i8 v[70:73], v[160:163], v[220:223], v[70:73]
	v_mfma_i32_16x16x64_i8 v[70:73], v[164:167], v[224:227], v[70:73]
	v_mfma_i32_16x16x64_i8 v[66:69], v[186:189], v[220:223], v[66:69]
	v_mfma_i32_16x16x64_i8 v[66:69], v[190:193], v[224:227], v[66:69]
	s_setprio 0
	s_barrier
	s_add_i32 s12, s42, s16
	v_lshl_add_u64 v[228:229], v[228:229], 0, s[10:11]
	s_mov_b32 m0, s12
	ds_read_b128 v[194:197], v185 offset:49152
	ds_read_b128 v[198:201], v185 offset:50176
	ds_read_b128 v[202:205], v185 offset:51200
	ds_read_b128 v[208:211], v185 offset:52224
	ds_read_b128 v[212:215], v185 offset:53248
	ds_read_b128 v[216:219], v185 offset:54272
	ds_read_b128 v[220:223], v185 offset:55296
	ds_read_b128 v[224:227], v185 offset:56320
	global_load_lds_dwordx4 v[228:229], off
	s_add_i32 m0, s12, 0x2000
	s_add_u32 s2, s2, 0x80080
	v_lshl_add_u64 v[228:229], v[230:231], 0, s[10:11]
	s_addc_u32 s3, s3, 0
	s_add_i32 s12, s43, s16
	global_load_lds_dwordx4 v[228:229], off
	v_lshl_add_u64 v[228:229], s[2:3], 0, v[132:133]
	s_mov_b32 m0, s12
	s_nop 0
	global_load_lds_dwordx4 v[228:229], off
	v_lshl_add_u64 v[228:229], s[2:3], 0, v[136:137]
	s_add_i32 m0, s12, 0x2000
	s_nop 0
	global_load_lds_dwordx4 v[228:229], off
	v_lshl_add_u64 v[228:229], v[232:233], 0, s[10:11]
	s_mov_b32 m0, s22
	s_nop 0
	global_load_lds_dwordx4 v[228:229], off
	v_lshl_add_u64 v[228:229], v[234:235], 0, s[10:11]
	s_mov_b32 m0, s23
	s_nop 0
	global_load_lds_dwordx4 v[228:229], off
	s_waitcnt vmcnt(8)
	s_waitcnt lgkmcnt(0)
	s_barrier
	s_setprio 1
	s_waitcnt lgkmcnt(0)
	v_mfma_i32_16x16x64_i8 v[62:65], v[144:147], v[194:197], v[62:65]
	v_mfma_i32_16x16x64_i8 v[62:65], v[148:151], v[198:201], v[62:65]
	v_mfma_i32_16x16x64_i8 v[58:61], v[152:155], v[194:197], v[58:61]
	v_mfma_i32_16x16x64_i8 v[58:61], v[156:159], v[198:201], v[58:61]
	v_mfma_i32_16x16x64_i8 v[54:57], v[144:147], v[202:205], v[54:57]
	v_mfma_i32_16x16x64_i8 v[54:57], v[148:151], v[208:211], v[54:57]
	v_mfma_i32_16x16x64_i8 v[50:53], v[152:155], v[202:205], v[50:53]
	v_mfma_i32_16x16x64_i8 v[50:53], v[156:159], v[208:211], v[50:53]
	v_mfma_i32_16x16x64_i8 v[46:49], v[144:147], v[212:215], v[46:49]
	v_mfma_i32_16x16x64_i8 v[46:49], v[148:151], v[216:219], v[46:49]
	v_mfma_i32_16x16x64_i8 v[42:45], v[152:155], v[212:215], v[42:45]
	v_mfma_i32_16x16x64_i8 v[42:45], v[156:159], v[216:219], v[42:45]
	v_mfma_i32_16x16x64_i8 v[38:41], v[144:147], v[220:223], v[38:41]
	v_mfma_i32_16x16x64_i8 v[38:41], v[148:151], v[224:227], v[38:41]
	v_mfma_i32_16x16x64_i8 v[34:37], v[152:155], v[220:223], v[34:37]
	v_mfma_i32_16x16x64_i8 v[34:37], v[156:159], v[224:227], v[34:37]
	s_setprio 0
	s_setprio 1
	v_mfma_i32_16x16x64_i8 v[30:33], v[160:163], v[194:197], v[30:33]
	v_mfma_i32_16x16x64_i8 v[30:33], v[164:167], v[198:201], v[30:33]
	v_mfma_i32_16x16x64_i8 v[26:29], v[186:189], v[194:197], v[26:29]
	v_mfma_i32_16x16x64_i8 v[26:29], v[190:193], v[198:201], v[26:29]
	v_mfma_i32_16x16x64_i8 v[22:25], v[160:163], v[202:205], v[22:25]
	v_mfma_i32_16x16x64_i8 v[22:25], v[164:167], v[208:211], v[22:25]
	v_mfma_i32_16x16x64_i8 v[18:21], v[186:189], v[202:205], v[18:21]
	v_mfma_i32_16x16x64_i8 v[18:21], v[190:193], v[208:211], v[18:21]
	v_mfma_i32_16x16x64_i8 v[14:17], v[160:163], v[212:215], v[14:17]
	v_mfma_i32_16x16x64_i8 v[14:17], v[164:167], v[216:219], v[14:17]
	v_mfma_i32_16x16x64_i8 v[10:13], v[186:189], v[212:215], v[10:13]
	v_mfma_i32_16x16x64_i8 v[10:13], v[190:193], v[216:219], v[10:13]
	v_mfma_i32_16x16x64_i8 v[6:9], v[160:163], v[220:223], v[6:9]
	v_mfma_i32_16x16x64_i8 v[6:9], v[164:167], v[224:227], v[6:9]
	v_mfma_i32_16x16x64_i8 v[2:5], v[186:189], v[220:223], v[2:5]
	v_mfma_i32_16x16x64_i8 v[2:5], v[190:193], v[224:227], v[2:5]
	s_setprio 0
	s_barrier
	s_add_u32 s4, s4, 0x100
	s_addc_u32 s5, s5, 0
	s_add_u32 s39, s39, 0x100
	s_addc_u32 s40, s40, 0
	s_cmp_ge_i32 s41, s1
	s_mov_b32 s2, s41
	s_cbranch_scc0 .LBB0_245

.LBB0_265:
	s_lshl_b32 s10, s8, 21
	s_and_b32 s10, s10, 0x1fe00000
	v_readlane_b32 s40, v248, 20
	v_readlane_b32 s41, v248, 21
	s_add_u32 s10, s40, s10
	s_addc_u32 s33, s41, 0
	s_lshr_b32 s39, s8, 13
	s_and_b32 s39, s39, 0x7ff80
	s_add_u32 s70, s10, s39
	s_addc_u32 s71, s33, 0
	s_lshl_b32 s10, s8, 13
	s_and_b32 s10, s10, 0x1fe00000
	v_readlane_b32 s40, v248, 18
	v_readlane_b32 s41, v248, 19
	s_add_u32 s10, s40, s10
	s_addc_u32 s33, s41, 0
	s_add_u32 s72, s10, s39
	s_addc_u32 s73, s33, 0
	s_cmp_lt_i32 s1, 1
	v_cmp_gt_i64_e64 s[74:75], s[8:9], -1
	s_cbranch_scc1 .LBB0_324
	s_and_b64 s[8:9], s[74:75], exec
	s_cselect_b32 s10, s71, s5
	s_cselect_b32 s33, s70, s4
	s_cselect_b32 s39, s73, s3
	s_cselect_b32 s40, s72, s2
	s_add_i32 s41, s1, -2
	s_add_u32 s4, s4, 0x100080
	s_addc_u32 s5, s5, 0
	s_add_u32 s42, s2, 0x100
	s_addc_u32 s43, s3, 0
	s_mov_b32 s2, 0
	ds_read_b128 v[148:151], v145
	ds_read_b128 v[152:155], v145 offset:1024
	ds_read_b128 v[156:159], v145 offset:2048
	ds_read_b128 v[160:163], v145 offset:3072
	ds_read_b128 v[164:167], v146
	ds_read_b128 v[168:171], v146 offset:1024
	ds_read_b128 v[172:175], v146 offset:2048
	ds_read_b128 v[176:179], v146 offset:3072
	s_add_i32 s44, s2, 2
	s_add_u32 s3, s4, 0xfff00080
	s_addc_u32 s8, s5, -1
	s_cmp_eq_u32 s41, s2
	s_cselect_b32 s2, s40, s42
	s_cselect_b32 s9, s10, s8
	s_cselect_b32 s8, s33, s3
	s_cselect_b32 s3, s39, s43
	v_lshl_add_u64 v[204:205], s[4:5], 0, v[138:139]
	s_add_i32 m0, s16, 0xc000
	ds_read_b128 v[180:183], v147
	ds_read_b128 v[184:187], v147 offset:1024
	ds_read_b128 v[188:191], v147 offset:2048
	ds_read_b128 v[192:195], v147 offset:3072
	ds_read_b128 v[196:199], v147 offset:4096
	ds_read_b128 v[200:203], v147 offset:5120
	ds_read_b128 v[208:211], v147 offset:6144
	ds_read_b128 v[212:215], v147 offset:7168
	global_load_lds_dwordx4 v[204:205], off
	v_lshl_add_u64 v[204:205], s[4:5], 0, v[140:141]
	s_add_i32 m0, s16, 0xe000
	s_nop 0
	global_load_lds_dwordx4 v[204:205], off
	s_waitcnt vmcnt(8)
	s_waitcnt lgkmcnt(0)
	s_barrier
	s_setprio 1
	s_waitcnt lgkmcnt(0)
	v_mfma_f32_16x16x32_bf16 v[122:125], v[148:151], v[180:183], 0
	v_mfma_f32_16x16x32_bf16 v[122:125], v[152:155], v[184:187], v[122:125]
	v_mfma_f32_16x16x32_bf16 v[118:121], v[156:159], v[180:183], 0
	v_mfma_f32_16x16x32_bf16 v[118:121], v[160:163], v[184:187], v[118:121]
	v_mfma_f32_16x16x32_bf16 v[110:113], v[148:151], v[188:191], 0
	v_mfma_f32_16x16x32_bf16 v[110:113], v[152:155], v[192:195], v[110:113]
	v_mfma_f32_16x16x32_bf16 v[102:105], v[156:159], v[188:191], 0
	v_mfma_f32_16x16x32_bf16 v[102:105], v[160:163], v[192:195], v[102:105]
	v_mfma_f32_16x16x32_bf16 v[94:97], v[148:151], v[196:199], 0
	v_mfma_f32_16x16x32_bf16 v[94:97], v[152:155], v[200:203], v[94:97]
	v_mfma_f32_16x16x32_bf16 v[86:89], v[156:159], v[196:199], 0
	v_mfma_f32_16x16x32_bf16 v[86:89], v[160:163], v[200:203], v[86:89]
	v_mfma_f32_16x16x32_bf16 v[78:81], v[148:151], v[208:211], 0
	v_mfma_f32_16x16x32_bf16 v[78:81], v[152:155], v[212:215], v[78:81]
	v_mfma_f32_16x16x32_bf16 v[70:73], v[156:159], v[208:211], 0
	v_mfma_f32_16x16x32_bf16 v[70:73], v[160:163], v[212:215], v[70:73]
	s_setprio 0
	s_setprio 1
	v_mfma_f32_16x16x32_bf16 v[126:129], v[164:167], v[180:183], 0
	v_mfma_f32_16x16x32_bf16 v[126:129], v[168:171], v[184:187], v[126:129]
	v_mfma_f32_16x16x32_bf16 v[114:117], v[172:175], v[180:183], 0
	v_mfma_f32_16x16x32_bf16 v[114:117], v[176:179], v[184:187], v[114:117]
	v_mfma_f32_16x16x32_bf16 v[106:109], v[164:167], v[188:191], 0
	v_mfma_f32_16x16x32_bf16 v[106:109], v[168:171], v[192:195], v[106:109]
	v_mfma_f32_16x16x32_bf16 v[98:101], v[172:175], v[188:191], 0
	v_mfma_f32_16x16x32_bf16 v[98:101], v[176:179], v[192:195], v[98:101]
	v_mfma_f32_16x16x32_bf16 v[90:93], v[164:167], v[196:199], 0
	v_mfma_f32_16x16x32_bf16 v[90:93], v[168:171], v[200:203], v[90:93]
	v_mfma_f32_16x16x32_bf16 v[82:85], v[172:175], v[196:199], 0
	v_mfma_f32_16x16x32_bf16 v[82:85], v[176:179], v[200:203], v[82:85]
	v_mfma_f32_16x16x32_bf16 v[74:77], v[164:167], v[208:211], 0
	v_mfma_f32_16x16x32_bf16 v[74:77], v[168:171], v[212:215], v[74:77]
	v_mfma_f32_16x16x32_bf16 v[66:69], v[172:175], v[208:211], 0
	v_mfma_f32_16x16x32_bf16 v[66:69], v[176:179], v[212:215], v[66:69]
	s_setprio 0
	s_barrier
	s_add_i32 s45, s36, s13
	v_lshl_add_u64 v[204:205], s[2:3], 0, v[132:133]
	s_mov_b32 m0, s45
	ds_read_b128 v[180:183], v147 offset:16384
	ds_read_b128 v[184:187], v147 offset:17408
	ds_read_b128 v[188:191], v147 offset:18432
	ds_read_b128 v[192:195], v147 offset:19456
	ds_read_b128 v[196:199], v147 offset:20480
	ds_read_b128 v[200:203], v147 offset:21504
	ds_read_b128 v[208:211], v147 offset:22528
	ds_read_b128 v[212:215], v147 offset:23552
	global_load_lds_dwordx4 v[204:205], off
	s_add_i32 m0, s45, 0x2000
	s_add_u32 s46, s2, 0x100000
	v_lshl_add_u64 v[216:217], s[2:3], 0, v[136:137]
	s_addc_u32 s47, s3, 0
	s_add_i32 s45, s37, s13
	global_load_lds_dwordx4 v[216:217], off
	v_lshl_add_u64 v[218:219], s[46:47], 0, v[132:133]
	s_mov_b32 m0, s45
	v_lshl_add_u64 v[220:221], s[8:9], 0, v[134:135]
	global_load_lds_dwordx4 v[218:219], off
	v_lshl_add_u64 v[218:219], s[46:47], 0, v[136:137]
	s_add_i32 m0, s45, 0x2000
	s_nop 0
	global_load_lds_dwordx4 v[218:219], off
	v_lshl_add_u64 v[218:219], s[8:9], 0, v[130:131]
	s_mov_b32 m0, s16
	s_nop 0
	global_load_lds_dwordx4 v[218:219], off
	s_mov_b32 m0, s17
	s_nop 0
	global_load_lds_dwordx4 v[220:221], off
	s_waitcnt vmcnt(8)
	s_waitcnt lgkmcnt(0)
	s_barrier
	s_setprio 1
	s_waitcnt lgkmcnt(0)
	v_mfma_f32_16x16x32_bf16 v[62:65], v[148:151], v[180:183], 0
	v_mfma_f32_16x16x32_bf16 v[62:65], v[152:155], v[184:187], v[62:65]
	v_mfma_f32_16x16x32_bf16 v[54:57], v[156:159], v[180:183], 0
	v_mfma_f32_16x16x32_bf16 v[54:57], v[160:163], v[184:187], v[54:57]
	v_mfma_f32_16x16x32_bf16 v[46:49], v[148:151], v[188:191], 0
	v_mfma_f32_16x16x32_bf16 v[46:49], v[152:155], v[192:195], v[46:49]
	v_mfma_f32_16x16x32_bf16 v[38:41], v[156:159], v[188:191], 0
	v_mfma_f32_16x16x32_bf16 v[38:41], v[160:163], v[192:195], v[38:41]
	v_mfma_f32_16x16x32_bf16 v[30:33], v[148:151], v[196:199], 0
	v_mfma_f32_16x16x32_bf16 v[30:33], v[152:155], v[200:203], v[30:33]
	v_mfma_f32_16x16x32_bf16 v[22:25], v[156:159], v[196:199], 0
	v_mfma_f32_16x16x32_bf16 v[22:25], v[160:163], v[200:203], v[22:25]
	v_mfma_f32_16x16x32_bf16 v[14:17], v[148:151], v[208:211], 0
	v_mfma_f32_16x16x32_bf16 v[14:17], v[152:155], v[212:215], v[14:17]
	v_mfma_f32_16x16x32_bf16 v[6:9], v[156:159], v[208:211], 0
	v_mfma_f32_16x16x32_bf16 v[6:9], v[160:163], v[212:215], v[6:9]
	s_setprio 0
	s_setprio 1
	v_mfma_f32_16x16x32_bf16 v[58:61], v[164:167], v[180:183], 0
	v_mfma_f32_16x16x32_bf16 v[58:61], v[168:171], v[184:187], v[58:61]
	v_mfma_f32_16x16x32_bf16 v[50:53], v[172:175], v[180:183], 0
	v_mfma_f32_16x16x32_bf16 v[50:53], v[176:179], v[184:187], v[50:53]
	v_mfma_f32_16x16x32_bf16 v[42:45], v[164:167], v[188:191], 0
	v_mfma_f32_16x16x32_bf16 v[42:45], v[168:171], v[192:195], v[42:45]
	v_mfma_f32_16x16x32_bf16 v[34:37], v[172:175], v[188:191], 0
	v_mfma_f32_16x16x32_bf16 v[34:37], v[176:179], v[192:195], v[34:37]
	v_mfma_f32_16x16x32_bf16 v[26:29], v[164:167], v[196:199], 0
	v_mfma_f32_16x16x32_bf16 v[26:29], v[168:171], v[200:203], v[26:29]
	v_mfma_f32_16x16x32_bf16 v[18:21], v[172:175], v[196:199], 0
	v_mfma_f32_16x16x32_bf16 v[18:21], v[176:179], v[200:203], v[18:21]
	v_mfma_f32_16x16x32_bf16 v[10:13], v[164:167], v[208:211], 0
	v_mfma_f32_16x16x32_bf16 v[10:13], v[168:171], v[212:215], v[10:13]
	v_mfma_f32_16x16x32_bf16 v[2:5], v[172:175], v[208:211], 0
	v_mfma_f32_16x16x32_bf16 v[2:5], v[176:179], v[212:215], v[2:5]
	s_setprio 0
	s_barrier
	s_add_i32 s45, 0, 0x18000
	s_add_i32 s46, 0, 0x1c000
	v_add_u32_e32 v160, s45, v1
	v_add_u32_e32 v176, s46, v1
	ds_read_b128 v[148:151], v160
	ds_read_b128 v[152:155], v160 offset:1024
	ds_read_b128 v[156:159], v160 offset:2048
	ds_read_b128 v[160:163], v160 offset:3072
	ds_read_b128 v[164:167], v176
	ds_read_b128 v[168:171], v176 offset:1024
	ds_read_b128 v[172:175], v176 offset:2048
	ds_read_b128 v[176:179], v176 offset:3072
	s_add_u32 s8, s8, 0x100000
	s_addc_u32 s9, s9, 0
	s_mov_b32 m0, s18
	v_lshl_add_u64 v[222:223], s[8:9], 0, v[130:131]
	ds_read_b128 v[180:183], v147 offset:32768
	ds_read_b128 v[184:187], v147 offset:33792
	ds_read_b128 v[188:191], v147 offset:34816
	ds_read_b128 v[192:195], v147 offset:35840
	ds_read_b128 v[196:199], v147 offset:36864
	ds_read_b128 v[200:203], v147 offset:37888
	ds_read_b128 v[208:211], v147 offset:38912
	ds_read_b128 v[212:215], v147 offset:39936
	global_load_lds_dwordx4 v[222:223], off
	v_lshl_add_u64 v[222:223], s[8:9], 0, v[134:135]
	s_mov_b32 m0, s19
	s_nop 0
	global_load_lds_dwordx4 v[222:223], off
	s_waitcnt vmcnt(8)
	s_waitcnt lgkmcnt(0)
	s_barrier
	s_setprio 1
	s_waitcnt lgkmcnt(0)
	v_mfma_f32_16x16x32_bf16 v[122:125], v[148:151], v[180:183], v[122:125]
	v_mfma_f32_16x16x32_bf16 v[122:125], v[152:155], v[184:187], v[122:125]
	v_mfma_f32_16x16x32_bf16 v[118:121], v[156:159], v[180:183], v[118:121]
	v_mfma_f32_16x16x32_bf16 v[118:121], v[160:163], v[184:187], v[118:121]
	v_mfma_f32_16x16x32_bf16 v[110:113], v[148:151], v[188:191], v[110:113]
	v_mfma_f32_16x16x32_bf16 v[110:113], v[152:155], v[192:195], v[110:113]
	v_mfma_f32_16x16x32_bf16 v[102:105], v[156:159], v[188:191], v[102:105]
	v_mfma_f32_16x16x32_bf16 v[102:105], v[160:163], v[192:195], v[102:105]
	v_mfma_f32_16x16x32_bf16 v[94:97], v[148:151], v[196:199], v[94:97]
	v_mfma_f32_16x16x32_bf16 v[94:97], v[152:155], v[200:203], v[94:97]
	v_mfma_f32_16x16x32_bf16 v[86:89], v[156:159], v[196:199], v[86:89]
	v_mfma_f32_16x16x32_bf16 v[86:89], v[160:163], v[200:203], v[86:89]
	v_mfma_f32_16x16x32_bf16 v[78:81], v[148:151], v[208:211], v[78:81]
	v_mfma_f32_16x16x32_bf16 v[78:81], v[152:155], v[212:215], v[78:81]
	v_mfma_f32_16x16x32_bf16 v[70:73], v[156:159], v[208:211], v[70:73]
	v_mfma_f32_16x16x32_bf16 v[70:73], v[160:163], v[212:215], v[70:73]
	s_setprio 0
	s_setprio 1
	v_mfma_f32_16x16x32_bf16 v[126:129], v[164:167], v[180:183], v[126:129]
	v_mfma_f32_16x16x32_bf16 v[126:129], v[168:171], v[184:187], v[126:129]
	v_mfma_f32_16x16x32_bf16 v[114:117], v[172:175], v[180:183], v[114:117]
	v_mfma_f32_16x16x32_bf16 v[114:117], v[176:179], v[184:187], v[114:117]
	v_mfma_f32_16x16x32_bf16 v[106:109], v[164:167], v[188:191], v[106:109]
	v_mfma_f32_16x16x32_bf16 v[106:109], v[168:171], v[192:195], v[106:109]
	v_mfma_f32_16x16x32_bf16 v[98:101], v[172:175], v[188:191], v[98:101]
	v_mfma_f32_16x16x32_bf16 v[98:101], v[176:179], v[192:195], v[98:101]
	v_mfma_f32_16x16x32_bf16 v[90:93], v[164:167], v[196:199], v[90:93]
	v_mfma_f32_16x16x32_bf16 v[90:93], v[168:171], v[200:203], v[90:93]
	v_mfma_f32_16x16x32_bf16 v[82:85], v[172:175], v[196:199], v[82:85]
	v_mfma_f32_16x16x32_bf16 v[82:85], v[176:179], v[200:203], v[82:85]
	v_mfma_f32_16x16x32_bf16 v[74:77], v[164:167], v[208:211], v[74:77]
	v_mfma_f32_16x16x32_bf16 v[74:77], v[168:171], v[212:215], v[74:77]
	v_mfma_f32_16x16x32_bf16 v[66:69], v[172:175], v[208:211], v[66:69]
	v_mfma_f32_16x16x32_bf16 v[66:69], v[176:179], v[212:215], v[66:69]
	s_setprio 0
	s_barrier
	s_add_i32 s8, s45, s13
	v_lshl_add_u64 v[204:205], v[204:205], 0, s[24:25]
	s_mov_b32 m0, s8
	ds_read_b128 v[180:183], v147 offset:49152
	ds_read_b128 v[184:187], v147 offset:50176
	ds_read_b128 v[188:191], v147 offset:51200
	ds_read_b128 v[192:195], v147 offset:52224
	ds_read_b128 v[196:199], v147 offset:53248
	ds_read_b128 v[200:203], v147 offset:54272
	ds_read_b128 v[208:211], v147 offset:55296
	ds_read_b128 v[212:215], v147 offset:56320
	global_load_lds_dwordx4 v[204:205], off
	s_add_i32 m0, s8, 0x2000
	s_add_u32 s2, s2, 0x100080
	v_lshl_add_u64 v[204:205], v[216:217], 0, s[24:25]
	s_addc_u32 s3, s3, 0
	s_add_i32 s8, s46, s13
	global_load_lds_dwordx4 v[204:205], off
	v_lshl_add_u64 v[204:205], s[2:3], 0, v[132:133]
	s_mov_b32 m0, s8
	s_nop 0
	global_load_lds_dwordx4 v[204:205], off
	v_lshl_add_u64 v[204:205], s[2:3], 0, v[136:137]
	s_add_i32 m0, s8, 0x2000
	s_nop 0
	global_load_lds_dwordx4 v[204:205], off
	v_lshl_add_u64 v[204:205], v[218:219], 0, s[24:25]
	s_mov_b32 m0, s29
	s_nop 0
	global_load_lds_dwordx4 v[204:205], off
	v_lshl_add_u64 v[204:205], v[220:221], 0, s[24:25]
	s_mov_b32 m0, s34
	s_nop 0
	global_load_lds_dwordx4 v[204:205], off
	s_waitcnt vmcnt(8)
	s_waitcnt lgkmcnt(0)
	s_barrier
	s_setprio 1
	s_waitcnt lgkmcnt(0)
	v_mfma_f32_16x16x32_bf16 v[62:65], v[148:151], v[180:183], v[62:65]
	v_mfma_f32_16x16x32_bf16 v[62:65], v[152:155], v[184:187], v[62:65]
	v_mfma_f32_16x16x32_bf16 v[54:57], v[156:159], v[180:183], v[54:57]
	v_mfma_f32_16x16x32_bf16 v[54:57], v[160:163], v[184:187], v[54:57]
	v_mfma_f32_16x16x32_bf16 v[46:49], v[148:151], v[188:191], v[46:49]
	v_mfma_f32_16x16x32_bf16 v[46:49], v[152:155], v[192:195], v[46:49]
	v_mfma_f32_16x16x32_bf16 v[38:41], v[156:159], v[188:191], v[38:41]
	v_mfma_f32_16x16x32_bf16 v[38:41], v[160:163], v[192:195], v[38:41]
	v_mfma_f32_16x16x32_bf16 v[30:33], v[148:151], v[196:199], v[30:33]
	v_mfma_f32_16x16x32_bf16 v[30:33], v[152:155], v[200:203], v[30:33]
	v_mfma_f32_16x16x32_bf16 v[22:25], v[156:159], v[196:199], v[22:25]
	v_mfma_f32_16x16x32_bf16 v[22:25], v[160:163], v[200:203], v[22:25]
	v_mfma_f32_16x16x32_bf16 v[14:17], v[148:151], v[208:211], v[14:17]
	v_mfma_f32_16x16x32_bf16 v[14:17], v[152:155], v[212:215], v[14:17]
	v_mfma_f32_16x16x32_bf16 v[6:9], v[156:159], v[208:211], v[6:9]
	v_mfma_f32_16x16x32_bf16 v[6:9], v[160:163], v[212:215], v[6:9]
	s_setprio 0
	s_setprio 1
	v_mfma_f32_16x16x32_bf16 v[58:61], v[164:167], v[180:183], v[58:61]
	v_mfma_f32_16x16x32_bf16 v[58:61], v[168:171], v[184:187], v[58:61]
	v_mfma_f32_16x16x32_bf16 v[50:53], v[172:175], v[180:183], v[50:53]
	v_mfma_f32_16x16x32_bf16 v[50:53], v[176:179], v[184:187], v[50:53]
	v_mfma_f32_16x16x32_bf16 v[42:45], v[164:167], v[188:191], v[42:45]
	v_mfma_f32_16x16x32_bf16 v[42:45], v[168:171], v[192:195], v[42:45]
	v_mfma_f32_16x16x32_bf16 v[34:37], v[172:175], v[188:191], v[34:37]
	v_mfma_f32_16x16x32_bf16 v[34:37], v[176:179], v[192:195], v[34:37]
	v_mfma_f32_16x16x32_bf16 v[26:29], v[164:167], v[196:199], v[26:29]
	v_mfma_f32_16x16x32_bf16 v[26:29], v[168:171], v[200:203], v[26:29]
	v_mfma_f32_16x16x32_bf16 v[18:21], v[172:175], v[196:199], v[18:21]
	v_mfma_f32_16x16x32_bf16 v[18:21], v[176:179], v[200:203], v[18:21]
	v_mfma_f32_16x16x32_bf16 v[10:13], v[164:167], v[208:211], v[10:13]
	v_mfma_f32_16x16x32_bf16 v[10:13], v[168:171], v[212:215], v[10:13]
	v_mfma_f32_16x16x32_bf16 v[2:5], v[172:175], v[208:211], v[2:5]
	v_mfma_f32_16x16x32_bf16 v[2:5], v[176:179], v[212:215], v[2:5]
	s_setprio 0
	s_barrier
	s_add_u32 s4, s4, 0x100
	s_addc_u32 s5, s5, 0
	s_add_u32 s42, s42, 0x100
	s_addc_u32 s43, s43, 0
	s_cmp_ge_i32 s44, s1
	s_mov_b32 s2, s44
	s_cbranch_scc1 .Lkpeel_exit_1
.LBB0_267:
	ds_read_b128 v[148:151], v145
	ds_read_b128 v[152:155], v145 offset:1024
	ds_read_b128 v[156:159], v145 offset:2048
	ds_read_b128 v[160:163], v145 offset:3072
	ds_read_b128 v[164:167], v146
	ds_read_b128 v[168:171], v146 offset:1024
	ds_read_b128 v[172:175], v146 offset:2048
	ds_read_b128 v[176:179], v146 offset:3072
	s_add_i32 s44, s2, 2
	s_add_u32 s3, s4, 0xfff00080
	s_addc_u32 s8, s5, -1
	s_cmp_eq_u32 s41, s2
	s_cselect_b32 s2, s40, s42
	s_cselect_b32 s9, s10, s8
	s_cselect_b32 s8, s33, s3
	s_cselect_b32 s3, s39, s43
	v_lshl_add_u64 v[204:205], s[4:5], 0, v[138:139]
	s_add_i32 m0, s16, 0xc000
	ds_read_b128 v[180:183], v147
	ds_read_b128 v[184:187], v147 offset:1024
	ds_read_b128 v[188:191], v147 offset:2048
	ds_read_b128 v[192:195], v147 offset:3072
	ds_read_b128 v[196:199], v147 offset:4096
	ds_read_b128 v[200:203], v147 offset:5120
	ds_read_b128 v[208:211], v147 offset:6144
	ds_read_b128 v[212:215], v147 offset:7168
	global_load_lds_dwordx4 v[204:205], off
	v_lshl_add_u64 v[204:205], s[4:5], 0, v[140:141]
	s_add_i32 m0, s16, 0xe000
	s_nop 0
	global_load_lds_dwordx4 v[204:205], off
	s_waitcnt vmcnt(8)
	s_waitcnt lgkmcnt(0)
	s_barrier
	s_setprio 1
	s_waitcnt lgkmcnt(0)
	v_mfma_f32_16x16x32_bf16 v[122:125], v[148:151], v[180:183], v[122:125]
	v_mfma_f32_16x16x32_bf16 v[122:125], v[152:155], v[184:187], v[122:125]
	v_mfma_f32_16x16x32_bf16 v[118:121], v[156:159], v[180:183], v[118:121]
	v_mfma_f32_16x16x32_bf16 v[118:121], v[160:163], v[184:187], v[118:121]
	v_mfma_f32_16x16x32_bf16 v[110:113], v[148:151], v[188:191], v[110:113]
	v_mfma_f32_16x16x32_bf16 v[110:113], v[152:155], v[192:195], v[110:113]
	v_mfma_f32_16x16x32_bf16 v[102:105], v[156:159], v[188:191], v[102:105]
	v_mfma_f32_16x16x32_bf16 v[102:105], v[160:163], v[192:195], v[102:105]
	v_mfma_f32_16x16x32_bf16 v[94:97], v[148:151], v[196:199], v[94:97]
	v_mfma_f32_16x16x32_bf16 v[94:97], v[152:155], v[200:203], v[94:97]
	v_mfma_f32_16x16x32_bf16 v[86:89], v[156:159], v[196:199], v[86:89]
	v_mfma_f32_16x16x32_bf16 v[86:89], v[160:163], v[200:203], v[86:89]
	v_mfma_f32_16x16x32_bf16 v[78:81], v[148:151], v[208:211], v[78:81]
	v_mfma_f32_16x16x32_bf16 v[78:81], v[152:155], v[212:215], v[78:81]
	v_mfma_f32_16x16x32_bf16 v[70:73], v[156:159], v[208:211], v[70:73]
	v_mfma_f32_16x16x32_bf16 v[70:73], v[160:163], v[212:215], v[70:73]
	s_setprio 0
	s_setprio 1
	v_mfma_f32_16x16x32_bf16 v[126:129], v[164:167], v[180:183], v[126:129]
	v_mfma_f32_16x16x32_bf16 v[126:129], v[168:171], v[184:187], v[126:129]
	v_mfma_f32_16x16x32_bf16 v[114:117], v[172:175], v[180:183], v[114:117]
	v_mfma_f32_16x16x32_bf16 v[114:117], v[176:179], v[184:187], v[114:117]
	v_mfma_f32_16x16x32_bf16 v[106:109], v[164:167], v[188:191], v[106:109]
	v_mfma_f32_16x16x32_bf16 v[106:109], v[168:171], v[192:195], v[106:109]
	v_mfma_f32_16x16x32_bf16 v[98:101], v[172:175], v[188:191], v[98:101]
	v_mfma_f32_16x16x32_bf16 v[98:101], v[176:179], v[192:195], v[98:101]
	v_mfma_f32_16x16x32_bf16 v[90:93], v[164:167], v[196:199], v[90:93]
	v_mfma_f32_16x16x32_bf16 v[90:93], v[168:171], v[200:203], v[90:93]
	v_mfma_f32_16x16x32_bf16 v[82:85], v[172:175], v[196:199], v[82:85]
	v_mfma_f32_16x16x32_bf16 v[82:85], v[176:179], v[200:203], v[82:85]
	v_mfma_f32_16x16x32_bf16 v[74:77], v[164:167], v[208:211], v[74:77]
	v_mfma_f32_16x16x32_bf16 v[74:77], v[168:171], v[212:215], v[74:77]
	v_mfma_f32_16x16x32_bf16 v[66:69], v[172:175], v[208:211], v[66:69]
	v_mfma_f32_16x16x32_bf16 v[66:69], v[176:179], v[212:215], v[66:69]
	s_setprio 0
	s_barrier
	s_add_i32 s45, s36, s13
	v_lshl_add_u64 v[204:205], s[2:3], 0, v[132:133]
	s_mov_b32 m0, s45
	ds_read_b128 v[180:183], v147 offset:16384
	ds_read_b128 v[184:187], v147 offset:17408
	ds_read_b128 v[188:191], v147 offset:18432
	ds_read_b128 v[192:195], v147 offset:19456
	ds_read_b128 v[196:199], v147 offset:20480
	ds_read_b128 v[200:203], v147 offset:21504
	ds_read_b128 v[208:211], v147 offset:22528
	ds_read_b128 v[212:215], v147 offset:23552
	global_load_lds_dwordx4 v[204:205], off
	s_add_i32 m0, s45, 0x2000
	s_add_u32 s46, s2, 0x100000
	v_lshl_add_u64 v[216:217], s[2:3], 0, v[136:137]
	s_addc_u32 s47, s3, 0
	s_add_i32 s45, s37, s13
	global_load_lds_dwordx4 v[216:217], off
	v_lshl_add_u64 v[218:219], s[46:47], 0, v[132:133]
	s_mov_b32 m0, s45
	v_lshl_add_u64 v[220:221], s[8:9], 0, v[134:135]
	global_load_lds_dwordx4 v[218:219], off
	v_lshl_add_u64 v[218:219], s[46:47], 0, v[136:137]
	s_add_i32 m0, s45, 0x2000
	s_nop 0
	global_load_lds_dwordx4 v[218:219], off
	v_lshl_add_u64 v[218:219], s[8:9], 0, v[130:131]
	s_mov_b32 m0, s16
	s_nop 0
	global_load_lds_dwordx4 v[218:219], off
	s_mov_b32 m0, s17
	s_nop 0
	global_load_lds_dwordx4 v[220:221], off
	s_waitcnt vmcnt(8)
	s_waitcnt lgkmcnt(0)
	s_barrier
	s_setprio 1
	s_waitcnt lgkmcnt(0)
	v_mfma_f32_16x16x32_bf16 v[62:65], v[148:151], v[180:183], v[62:65]
	v_mfma_f32_16x16x32_bf16 v[62:65], v[152:155], v[184:187], v[62:65]
	v_mfma_f32_16x16x32_bf16 v[54:57], v[156:159], v[180:183], v[54:57]
	v_mfma_f32_16x16x32_bf16 v[54:57], v[160:163], v[184:187], v[54:57]
	v_mfma_f32_16x16x32_bf16 v[46:49], v[148:151], v[188:191], v[46:49]
	v_mfma_f32_16x16x32_bf16 v[46:49], v[152:155], v[192:195], v[46:49]
	v_mfma_f32_16x16x32_bf16 v[38:41], v[156:159], v[188:191], v[38:41]
	v_mfma_f32_16x16x32_bf16 v[38:41], v[160:163], v[192:195], v[38:41]
	v_mfma_f32_16x16x32_bf16 v[30:33], v[148:151], v[196:199], v[30:33]
	v_mfma_f32_16x16x32_bf16 v[30:33], v[152:155], v[200:203], v[30:33]
	v_mfma_f32_16x16x32_bf16 v[22:25], v[156:159], v[196:199], v[22:25]
	v_mfma_f32_16x16x32_bf16 v[22:25], v[160:163], v[200:203], v[22:25]
	v_mfma_f32_16x16x32_bf16 v[14:17], v[148:151], v[208:211], v[14:17]
	v_mfma_f32_16x16x32_bf16 v[14:17], v[152:155], v[212:215], v[14:17]
	v_mfma_f32_16x16x32_bf16 v[6:9], v[156:159], v[208:211], v[6:9]
	v_mfma_f32_16x16x32_bf16 v[6:9], v[160:163], v[212:215], v[6:9]
	s_setprio 0
	s_setprio 1
	v_mfma_f32_16x16x32_bf16 v[58:61], v[164:167], v[180:183], v[58:61]
	v_mfma_f32_16x16x32_bf16 v[58:61], v[168:171], v[184:187], v[58:61]
	v_mfma_f32_16x16x32_bf16 v[50:53], v[172:175], v[180:183], v[50:53]
	v_mfma_f32_16x16x32_bf16 v[50:53], v[176:179], v[184:187], v[50:53]
	v_mfma_f32_16x16x32_bf16 v[42:45], v[164:167], v[188:191], v[42:45]
	v_mfma_f32_16x16x32_bf16 v[42:45], v[168:171], v[192:195], v[42:45]
	v_mfma_f32_16x16x32_bf16 v[34:37], v[172:175], v[188:191], v[34:37]
	v_mfma_f32_16x16x32_bf16 v[34:37], v[176:179], v[192:195], v[34:37]
	v_mfma_f32_16x16x32_bf16 v[26:29], v[164:167], v[196:199], v[26:29]
	v_mfma_f32_16x16x32_bf16 v[26:29], v[168:171], v[200:203], v[26:29]
	v_mfma_f32_16x16x32_bf16 v[18:21], v[172:175], v[196:199], v[18:21]
	v_mfma_f32_16x16x32_bf16 v[18:21], v[176:179], v[200:203], v[18:21]
	v_mfma_f32_16x16x32_bf16 v[10:13], v[164:167], v[208:211], v[10:13]
	v_mfma_f32_16x16x32_bf16 v[10:13], v[168:171], v[212:215], v[10:13]
	v_mfma_f32_16x16x32_bf16 v[2:5], v[172:175], v[208:211], v[2:5]
	v_mfma_f32_16x16x32_bf16 v[2:5], v[176:179], v[212:215], v[2:5]
	s_setprio 0
	s_barrier
	s_add_i32 s45, 0, 0x18000
	s_add_i32 s46, 0, 0x1c000
	v_add_u32_e32 v160, s45, v1
	v_add_u32_e32 v176, s46, v1
	ds_read_b128 v[148:151], v160
	ds_read_b128 v[152:155], v160 offset:1024
	ds_read_b128 v[156:159], v160 offset:2048
	ds_read_b128 v[160:163], v160 offset:3072
	ds_read_b128 v[164:167], v176
	ds_read_b128 v[168:171], v176 offset:1024
	ds_read_b128 v[172:175], v176 offset:2048
	ds_read_b128 v[176:179], v176 offset:3072
	s_add_u32 s8, s8, 0x100000
	s_addc_u32 s9, s9, 0
	s_mov_b32 m0, s18
	v_lshl_add_u64 v[222:223], s[8:9], 0, v[130:131]
	ds_read_b128 v[180:183], v147 offset:32768
	ds_read_b128 v[184:187], v147 offset:33792
	ds_read_b128 v[188:191], v147 offset:34816
	ds_read_b128 v[192:195], v147 offset:35840
	ds_read_b128 v[196:199], v147 offset:36864
	ds_read_b128 v[200:203], v147 offset:37888
	ds_read_b128 v[208:211], v147 offset:38912
	ds_read_b128 v[212:215], v147 offset:39936
	global_load_lds_dwordx4 v[222:223], off
	v_lshl_add_u64 v[222:223], s[8:9], 0, v[134:135]
	s_mov_b32 m0, s19
	s_nop 0
	global_load_lds_dwordx4 v[222:223], off
	s_waitcnt vmcnt(8)
	s_waitcnt lgkmcnt(0)
	s_barrier
	s_setprio 1
	s_waitcnt lgkmcnt(0)
	v_mfma_f32_16x16x32_bf16 v[122:125], v[148:151], v[180:183], v[122:125]
	v_mfma_f32_16x16x32_bf16 v[122:125], v[152:155], v[184:187], v[122:125]
	v_mfma_f32_16x16x32_bf16 v[118:121], v[156:159], v[180:183], v[118:121]
	v_mfma_f32_16x16x32_bf16 v[118:121], v[160:163], v[184:187], v[118:121]
	v_mfma_f32_16x16x32_bf16 v[110:113], v[148:151], v[188:191], v[110:113]
	v_mfma_f32_16x16x32_bf16 v[110:113], v[152:155], v[192:195], v[110:113]
	v_mfma_f32_16x16x32_bf16 v[102:105], v[156:159], v[188:191], v[102:105]
	v_mfma_f32_16x16x32_bf16 v[102:105], v[160:163], v[192:195], v[102:105]
	v_mfma_f32_16x16x32_bf16 v[94:97], v[148:151], v[196:199], v[94:97]
	v_mfma_f32_16x16x32_bf16 v[94:97], v[152:155], v[200:203], v[94:97]
	v_mfma_f32_16x16x32_bf16 v[86:89], v[156:159], v[196:199], v[86:89]
	v_mfma_f32_16x16x32_bf16 v[86:89], v[160:163], v[200:203], v[86:89]
	v_mfma_f32_16x16x32_bf16 v[78:81], v[148:151], v[208:211], v[78:81]
	v_mfma_f32_16x16x32_bf16 v[78:81], v[152:155], v[212:215], v[78:81]
	v_mfma_f32_16x16x32_bf16 v[70:73], v[156:159], v[208:211], v[70:73]
	v_mfma_f32_16x16x32_bf16 v[70:73], v[160:163], v[212:215], v[70:73]
	s_setprio 0
	s_setprio 1
	v_mfma_f32_16x16x32_bf16 v[126:129], v[164:167], v[180:183], v[126:129]
	v_mfma_f32_16x16x32_bf16 v[126:129], v[168:171], v[184:187], v[126:129]
	v_mfma_f32_16x16x32_bf16 v[114:117], v[172:175], v[180:183], v[114:117]
	v_mfma_f32_16x16x32_bf16 v[114:117], v[176:179], v[184:187], v[114:117]
	v_mfma_f32_16x16x32_bf16 v[106:109], v[164:167], v[188:191], v[106:109]
	v_mfma_f32_16x16x32_bf16 v[106:109], v[168:171], v[192:195], v[106:109]
	v_mfma_f32_16x16x32_bf16 v[98:101], v[172:175], v[188:191], v[98:101]
	v_mfma_f32_16x16x32_bf16 v[98:101], v[176:179], v[192:195], v[98:101]
	v_mfma_f32_16x16x32_bf16 v[90:93], v[164:167], v[196:199], v[90:93]
	v_mfma_f32_16x16x32_bf16 v[90:93], v[168:171], v[200:203], v[90:93]
	v_mfma_f32_16x16x32_bf16 v[82:85], v[172:175], v[196:199], v[82:85]
	v_mfma_f32_16x16x32_bf16 v[82:85], v[176:179], v[200:203], v[82:85]
	v_mfma_f32_16x16x32_bf16 v[74:77], v[164:167], v[208:211], v[74:77]
	v_mfma_f32_16x16x32_bf16 v[74:77], v[168:171], v[212:215], v[74:77]
	v_mfma_f32_16x16x32_bf16 v[66:69], v[172:175], v[208:211], v[66:69]
	v_mfma_f32_16x16x32_bf16 v[66:69], v[176:179], v[212:215], v[66:69]
	s_setprio 0
	s_barrier
	s_add_i32 s8, s45, s13
	v_lshl_add_u64 v[204:205], v[204:205], 0, s[24:25]
	s_mov_b32 m0, s8
	ds_read_b128 v[180:183], v147 offset:49152
	ds_read_b128 v[184:187], v147 offset:50176
	ds_read_b128 v[188:191], v147 offset:51200
	ds_read_b128 v[192:195], v147 offset:52224
	ds_read_b128 v[196:199], v147 offset:53248
	ds_read_b128 v[200:203], v147 offset:54272
	ds_read_b128 v[208:211], v147 offset:55296
	ds_read_b128 v[212:215], v147 offset:56320
	global_load_lds_dwordx4 v[204:205], off
	s_add_i32 m0, s8, 0x2000
	s_add_u32 s2, s2, 0x100080
	v_lshl_add_u64 v[204:205], v[216:217], 0, s[24:25]
	s_addc_u32 s3, s3, 0
	s_add_i32 s8, s46, s13
	global_load_lds_dwordx4 v[204:205], off
	v_lshl_add_u64 v[204:205], s[2:3], 0, v[132:133]
	s_mov_b32 m0, s8
	s_nop 0
	global_load_lds_dwordx4 v[204:205], off
	v_lshl_add_u64 v[204:205], s[2:3], 0, v[136:137]
	s_add_i32 m0, s8, 0x2000
	s_nop 0
	global_load_lds_dwordx4 v[204:205], off
	v_lshl_add_u64 v[204:205], v[218:219], 0, s[24:25]
	s_mov_b32 m0, s29
	s_nop 0
	global_load_lds_dwordx4 v[204:205], off
	v_lshl_add_u64 v[204:205], v[220:221], 0, s[24:25]
	s_mov_b32 m0, s34
	s_nop 0
	global_load_lds_dwordx4 v[204:205], off
	s_waitcnt vmcnt(8)
	s_waitcnt lgkmcnt(0)
	s_barrier
	s_setprio 1
	s_waitcnt lgkmcnt(0)
	v_mfma_f32_16x16x32_bf16 v[62:65], v[148:151], v[180:183], v[62:65]
	v_mfma_f32_16x16x32_bf16 v[62:65], v[152:155], v[184:187], v[62:65]
	v_mfma_f32_16x16x32_bf16 v[54:57], v[156:159], v[180:183], v[54:57]
	v_mfma_f32_16x16x32_bf16 v[54:57], v[160:163], v[184:187], v[54:57]
	v_mfma_f32_16x16x32_bf16 v[46:49], v[148:151], v[188:191], v[46:49]
	v_mfma_f32_16x16x32_bf16 v[46:49], v[152:155], v[192:195], v[46:49]
	v_mfma_f32_16x16x32_bf16 v[38:41], v[156:159], v[188:191], v[38:41]
	v_mfma_f32_16x16x32_bf16 v[38:41], v[160:163], v[192:195], v[38:41]
	v_mfma_f32_16x16x32_bf16 v[30:33], v[148:151], v[196:199], v[30:33]
	v_mfma_f32_16x16x32_bf16 v[30:33], v[152:155], v[200:203], v[30:33]
	v_mfma_f32_16x16x32_bf16 v[22:25], v[156:159], v[196:199], v[22:25]
	v_mfma_f32_16x16x32_bf16 v[22:25], v[160:163], v[200:203], v[22:25]
	v_mfma_f32_16x16x32_bf16 v[14:17], v[148:151], v[208:211], v[14:17]
	v_mfma_f32_16x16x32_bf16 v[14:17], v[152:155], v[212:215], v[14:17]
	v_mfma_f32_16x16x32_bf16 v[6:9], v[156:159], v[208:211], v[6:9]
	v_mfma_f32_16x16x32_bf16 v[6:9], v[160:163], v[212:215], v[6:9]
	s_setprio 0
	s_setprio 1
	v_mfma_f32_16x16x32_bf16 v[58:61], v[164:167], v[180:183], v[58:61]
	v_mfma_f32_16x16x32_bf16 v[58:61], v[168:171], v[184:187], v[58:61]
	v_mfma_f32_16x16x32_bf16 v[50:53], v[172:175], v[180:183], v[50:53]
	v_mfma_f32_16x16x32_bf16 v[50:53], v[176:179], v[184:187], v[50:53]
	v_mfma_f32_16x16x32_bf16 v[42:45], v[164:167], v[188:191], v[42:45]
	v_mfma_f32_16x16x32_bf16 v[42:45], v[168:171], v[192:195], v[42:45]
	v_mfma_f32_16x16x32_bf16 v[34:37], v[172:175], v[188:191], v[34:37]
	v_mfma_f32_16x16x32_bf16 v[34:37], v[176:179], v[192:195], v[34:37]
	v_mfma_f32_16x16x32_bf16 v[26:29], v[164:167], v[196:199], v[26:29]
	v_mfma_f32_16x16x32_bf16 v[26:29], v[168:171], v[200:203], v[26:29]
	v_mfma_f32_16x16x32_bf16 v[18:21], v[172:175], v[196:199], v[18:21]
	v_mfma_f32_16x16x32_bf16 v[18:21], v[176:179], v[200:203], v[18:21]
	v_mfma_f32_16x16x32_bf16 v[10:13], v[164:167], v[208:211], v[10:13]
	v_mfma_f32_16x16x32_bf16 v[10:13], v[168:171], v[212:215], v[10:13]
	v_mfma_f32_16x16x32_bf16 v[2:5], v[172:175], v[208:211], v[2:5]
	v_mfma_f32_16x16x32_bf16 v[2:5], v[176:179], v[212:215], v[2:5]
	s_setprio 0
	s_barrier
	s_add_u32 s4, s4, 0x100
	s_addc_u32 s5, s5, 0
	s_add_u32 s42, s42, 0x100
	s_addc_u32 s43, s43, 0
	s_cmp_ge_i32 s44, s1
	s_mov_b32 s2, s44
	s_cbranch_scc0 .LBB0_267

.LBB0_524:
	s_lshl_b32 s0, s26, 20
	s_and_b32 s0, s0, 0xff00000
	s_add_u32 s0, s70, s0
	s_addc_u32 s23, s71, 0
	s_lshr_b32 s22, s26, 13
	s_and_b32 s24, s22, 0x7ff80
	s_add_u32 s22, s0, s24
	s_addc_u32 s23, s23, 0
	s_lshl_b32 s0, s26, 12
	s_and_b32 s0, s0, 0xff00000
	s_add_u32 s0, s30, s0
	s_addc_u32 s25, s31, 0
	s_add_u32 s24, s0, s24
	s_addc_u32 s25, s25, 0
	s_cmp_lt_i32 s37, 1
	v_cmp_gt_i64_e64 s[26:27], s[26:27], -1
	s_cbranch_scc1 .LBB0_546
	s_and_b64 s[40:41], s[26:27], exec
	s_cselect_b32 s0, s23, s39
	s_cselect_b32 s36, s22, s38
	s_cselect_b32 s65, s25, s3
	s_cselect_b32 s66, s24, s2
	s_add_i32 s67, s37, -2
	s_add_u32 s38, s38, 0x80080
	s_addc_u32 s39, s39, 0
	s_add_u32 s68, s2, 0x100
	s_addc_u32 s69, s3, 0
	s_mov_b32 s2, 0
	ds_read_b128 v[148:151], v144
	ds_read_b128 v[152:155], v144 offset:1024
	ds_read_b128 v[156:159], v144 offset:2048
	ds_read_b128 v[160:163], v144 offset:3072
	ds_read_b128 v[164:167], v145
	ds_read_b128 v[168:171], v145 offset:1024
	ds_read_b128 v[172:175], v145 offset:2048
	ds_read_b128 v[176:179], v145 offset:3072
	s_waitcnt lgkmcnt(0)
	s_add_i32 s72, s2, 2
	s_add_u32 s3, s38, 0xfff80080
	s_addc_u32 s40, s39, -1
	s_cmp_eq_u32 s67, s2
	s_cselect_b32 s2, s66, s68
	s_cselect_b32 s41, s0, s40
	s_cselect_b32 s40, s36, s3
	s_cselect_b32 s3, s65, s69
	v_lshl_add_u64 v[204:205], s[38:39], 0, v[138:139]
	s_add_i32 m0, s29, 0xc000
	ds_read_b128 v[180:183], v146
	ds_read_b128 v[184:187], v146 offset:1024
	ds_read_b128 v[188:191], v146 offset:2048
	ds_read_b128 v[192:195], v146 offset:3072
	ds_read_b128 v[196:199], v146 offset:4096
	ds_read_b128 v[200:203], v146 offset:5120
	ds_read_b128 v[208:211], v146 offset:6144
	ds_read_b128 v[212:215], v146 offset:7168
	global_load_lds_dwordx4 v[204:205], off
	v_lshl_add_u64 v[204:205], s[38:39], 0, v[140:141]
	s_add_i32 m0, s29, 0xe000
	s_nop 0
	global_load_lds_dwordx4 v[204:205], off
	s_waitcnt vmcnt(8)
	s_waitcnt lgkmcnt(0)
	s_barrier
	s_setprio 1
	s_waitcnt lgkmcnt(0)
	v_mfma_f32_16x16x32_bf16 v[126:129], v[148:151], v[180:183], 0
	v_mfma_f32_16x16x32_bf16 v[126:129], v[152:155], v[184:187], v[126:129]
	v_mfma_f32_16x16x32_bf16 v[122:125], v[156:159], v[180:183], 0
	v_mfma_f32_16x16x32_bf16 v[122:125], v[160:163], v[184:187], v[122:125]
	v_mfma_f32_16x16x32_bf16 v[110:113], v[148:151], v[188:191], 0
	v_mfma_f32_16x16x32_bf16 v[110:113], v[152:155], v[192:195], v[110:113]
	v_mfma_f32_16x16x32_bf16 v[102:105], v[156:159], v[188:191], 0
	v_mfma_f32_16x16x32_bf16 v[102:105], v[160:163], v[192:195], v[102:105]
	v_mfma_f32_16x16x32_bf16 v[94:97], v[148:151], v[196:199], 0
	v_mfma_f32_16x16x32_bf16 v[94:97], v[152:155], v[200:203], v[94:97]
	v_mfma_f32_16x16x32_bf16 v[86:89], v[156:159], v[196:199], 0
	v_mfma_f32_16x16x32_bf16 v[86:89], v[160:163], v[200:203], v[86:89]
	v_mfma_f32_16x16x32_bf16 v[78:81], v[148:151], v[208:211], 0
	v_mfma_f32_16x16x32_bf16 v[78:81], v[152:155], v[212:215], v[78:81]
	v_mfma_f32_16x16x32_bf16 v[70:73], v[156:159], v[208:211], 0
	v_mfma_f32_16x16x32_bf16 v[70:73], v[160:163], v[212:215], v[70:73]
	s_setprio 0
	s_setprio 1
	v_mfma_f32_16x16x32_bf16 v[118:121], v[164:167], v[180:183], 0
	v_mfma_f32_16x16x32_bf16 v[118:121], v[168:171], v[184:187], v[118:121]
	v_mfma_f32_16x16x32_bf16 v[114:117], v[172:175], v[180:183], 0
	v_mfma_f32_16x16x32_bf16 v[114:117], v[176:179], v[184:187], v[114:117]
	v_mfma_f32_16x16x32_bf16 v[106:109], v[164:167], v[188:191], 0
	v_mfma_f32_16x16x32_bf16 v[106:109], v[168:171], v[192:195], v[106:109]
	v_mfma_f32_16x16x32_bf16 v[98:101], v[172:175], v[188:191], 0
	v_mfma_f32_16x16x32_bf16 v[98:101], v[176:179], v[192:195], v[98:101]
	v_mfma_f32_16x16x32_bf16 v[90:93], v[164:167], v[196:199], 0
	v_mfma_f32_16x16x32_bf16 v[90:93], v[168:171], v[200:203], v[90:93]
	v_mfma_f32_16x16x32_bf16 v[82:85], v[172:175], v[196:199], 0
	v_mfma_f32_16x16x32_bf16 v[82:85], v[176:179], v[200:203], v[82:85]
	v_mfma_f32_16x16x32_bf16 v[74:77], v[164:167], v[208:211], 0
	v_mfma_f32_16x16x32_bf16 v[74:77], v[168:171], v[212:215], v[74:77]
	v_mfma_f32_16x16x32_bf16 v[66:69], v[172:175], v[208:211], 0
	v_mfma_f32_16x16x32_bf16 v[66:69], v[176:179], v[212:215], v[66:69]
	s_setprio 0
	s_barrier
	s_add_i32 s73, s52, s33
	v_lshl_add_u64 v[204:205], s[2:3], 0, v[132:133]
	s_mov_b32 m0, s73
	ds_read_b128 v[180:183], v146 offset:16384
	ds_read_b128 v[184:187], v146 offset:17408
	ds_read_b128 v[188:191], v146 offset:18432
	ds_read_b128 v[192:195], v146 offset:19456
	ds_read_b128 v[196:199], v146 offset:20480
	ds_read_b128 v[200:203], v146 offset:21504
	ds_read_b128 v[208:211], v146 offset:22528
	ds_read_b128 v[212:215], v146 offset:23552
	global_load_lds_dwordx4 v[204:205], off
	s_add_i32 m0, s73, 0x2000
	s_add_u32 s74, s2, 0x80000
	v_lshl_add_u64 v[216:217], s[2:3], 0, v[136:137]
	s_addc_u32 s75, s3, 0
	s_add_i32 s73, s53, s33
	global_load_lds_dwordx4 v[216:217], off
	v_lshl_add_u64 v[218:219], s[74:75], 0, v[132:133]
	s_mov_b32 m0, s73
	v_lshl_add_u64 v[220:221], s[40:41], 0, v[134:135]
	global_load_lds_dwordx4 v[218:219], off
	v_lshl_add_u64 v[218:219], s[74:75], 0, v[136:137]
	s_add_i32 m0, s73, 0x2000
	s_nop 0
	global_load_lds_dwordx4 v[218:219], off
	v_lshl_add_u64 v[218:219], s[40:41], 0, v[130:131]
	s_mov_b32 m0, s29
	s_nop 0
	global_load_lds_dwordx4 v[218:219], off
	s_mov_b32 m0, s35
	s_nop 0
	global_load_lds_dwordx4 v[220:221], off
	s_waitcnt vmcnt(8)
	s_waitcnt lgkmcnt(0)
	s_barrier
	s_setprio 1
	s_waitcnt lgkmcnt(0)
	v_mfma_f32_16x16x32_bf16 v[62:65], v[148:151], v[180:183], 0
	v_mfma_f32_16x16x32_bf16 v[62:65], v[152:155], v[184:187], v[62:65]
	v_mfma_f32_16x16x32_bf16 v[54:57], v[156:159], v[180:183], 0
	v_mfma_f32_16x16x32_bf16 v[54:57], v[160:163], v[184:187], v[54:57]
	v_mfma_f32_16x16x32_bf16 v[46:49], v[148:151], v[188:191], 0
	v_mfma_f32_16x16x32_bf16 v[46:49], v[152:155], v[192:195], v[46:49]
	v_mfma_f32_16x16x32_bf16 v[38:41], v[156:159], v[188:191], 0
	v_mfma_f32_16x16x32_bf16 v[38:41], v[160:163], v[192:195], v[38:41]
	v_mfma_f32_16x16x32_bf16 v[30:33], v[148:151], v[196:199], 0
	v_mfma_f32_16x16x32_bf16 v[30:33], v[152:155], v[200:203], v[30:33]
	v_mfma_f32_16x16x32_bf16 v[22:25], v[156:159], v[196:199], 0
	v_mfma_f32_16x16x32_bf16 v[22:25], v[160:163], v[200:203], v[22:25]
	v_mfma_f32_16x16x32_bf16 v[14:17], v[148:151], v[208:211], 0
	v_mfma_f32_16x16x32_bf16 v[14:17], v[152:155], v[212:215], v[14:17]
	v_mfma_f32_16x16x32_bf16 v[6:9], v[156:159], v[208:211], 0
	v_mfma_f32_16x16x32_bf16 v[6:9], v[160:163], v[212:215], v[6:9]
	s_setprio 0
	s_setprio 1
	v_mfma_f32_16x16x32_bf16 v[58:61], v[164:167], v[180:183], 0
	v_mfma_f32_16x16x32_bf16 v[58:61], v[168:171], v[184:187], v[58:61]
	v_mfma_f32_16x16x32_bf16 v[50:53], v[172:175], v[180:183], 0
	v_mfma_f32_16x16x32_bf16 v[50:53], v[176:179], v[184:187], v[50:53]
	v_mfma_f32_16x16x32_bf16 v[42:45], v[164:167], v[188:191], 0
	v_mfma_f32_16x16x32_bf16 v[42:45], v[168:171], v[192:195], v[42:45]
	v_mfma_f32_16x16x32_bf16 v[34:37], v[172:175], v[188:191], 0
	v_mfma_f32_16x16x32_bf16 v[34:37], v[176:179], v[192:195], v[34:37]
	v_mfma_f32_16x16x32_bf16 v[26:29], v[164:167], v[196:199], 0
	v_mfma_f32_16x16x32_bf16 v[26:29], v[168:171], v[200:203], v[26:29]
	v_mfma_f32_16x16x32_bf16 v[18:21], v[172:175], v[196:199], 0
	v_mfma_f32_16x16x32_bf16 v[18:21], v[176:179], v[200:203], v[18:21]
	v_mfma_f32_16x16x32_bf16 v[10:13], v[164:167], v[208:211], 0
	v_mfma_f32_16x16x32_bf16 v[10:13], v[168:171], v[212:215], v[10:13]
	v_mfma_f32_16x16x32_bf16 v[2:5], v[172:175], v[208:211], 0
	v_mfma_f32_16x16x32_bf16 v[2:5], v[176:179], v[212:215], v[2:5]
	s_setprio 0
	s_barrier
	s_add_i32 s73, 0, 0x18000
	v_add_u32_e32 v147, s73, v142
	s_add_i32 s74, 0, 0x1c000
	ds_read_b128 v[148:151], v147
	ds_read_b128 v[152:155], v147 offset:1024
	ds_read_b128 v[156:159], v147 offset:2048
	ds_read_b128 v[160:163], v147 offset:3072
	v_add_u32_e32 v147, s74, v142
	ds_read_b128 v[164:167], v147
	ds_read_b128 v[168:171], v147 offset:1024
	ds_read_b128 v[172:175], v147 offset:2048
	ds_read_b128 v[176:179], v147 offset:3072
	s_add_u32 s40, s40, 0x80000
	s_addc_u32 s41, s41, 0
	s_mov_b32 m0, s43
	v_lshl_add_u64 v[222:223], s[40:41], 0, v[130:131]
	ds_read_b128 v[180:183], v146 offset:32768
	ds_read_b128 v[184:187], v146 offset:33792
	ds_read_b128 v[188:191], v146 offset:34816
	ds_read_b128 v[192:195], v146 offset:35840
	ds_read_b128 v[196:199], v146 offset:36864
	ds_read_b128 v[200:203], v146 offset:37888
	ds_read_b128 v[208:211], v146 offset:38912
	ds_read_b128 v[212:215], v146 offset:39936
	global_load_lds_dwordx4 v[222:223], off
	v_lshl_add_u64 v[222:223], s[40:41], 0, v[134:135]
	s_mov_b32 m0, s44
	s_nop 0
	global_load_lds_dwordx4 v[222:223], off
	s_waitcnt vmcnt(8)
	s_waitcnt lgkmcnt(0)
	s_barrier
	s_setprio 1
	s_waitcnt lgkmcnt(0)
	v_mfma_f32_16x16x32_bf16 v[126:129], v[148:151], v[180:183], v[126:129]
	v_mfma_f32_16x16x32_bf16 v[126:129], v[152:155], v[184:187], v[126:129]
	v_mfma_f32_16x16x32_bf16 v[122:125], v[156:159], v[180:183], v[122:125]
	v_mfma_f32_16x16x32_bf16 v[122:125], v[160:163], v[184:187], v[122:125]
	v_mfma_f32_16x16x32_bf16 v[110:113], v[148:151], v[188:191], v[110:113]
	v_mfma_f32_16x16x32_bf16 v[110:113], v[152:155], v[192:195], v[110:113]
	v_mfma_f32_16x16x32_bf16 v[102:105], v[156:159], v[188:191], v[102:105]
	v_mfma_f32_16x16x32_bf16 v[102:105], v[160:163], v[192:195], v[102:105]
	v_mfma_f32_16x16x32_bf16 v[94:97], v[148:151], v[196:199], v[94:97]
	v_mfma_f32_16x16x32_bf16 v[94:97], v[152:155], v[200:203], v[94:97]
	v_mfma_f32_16x16x32_bf16 v[86:89], v[156:159], v[196:199], v[86:89]
	v_mfma_f32_16x16x32_bf16 v[86:89], v[160:163], v[200:203], v[86:89]
	v_mfma_f32_16x16x32_bf16 v[78:81], v[148:151], v[208:211], v[78:81]
	v_mfma_f32_16x16x32_bf16 v[78:81], v[152:155], v[212:215], v[78:81]
	v_mfma_f32_16x16x32_bf16 v[70:73], v[156:159], v[208:211], v[70:73]
	v_mfma_f32_16x16x32_bf16 v[70:73], v[160:163], v[212:215], v[70:73]
	s_setprio 0
	s_setprio 1
	v_mfma_f32_16x16x32_bf16 v[118:121], v[164:167], v[180:183], v[118:121]
	v_mfma_f32_16x16x32_bf16 v[118:121], v[168:171], v[184:187], v[118:121]
	v_mfma_f32_16x16x32_bf16 v[114:117], v[172:175], v[180:183], v[114:117]
	v_mfma_f32_16x16x32_bf16 v[114:117], v[176:179], v[184:187], v[114:117]
	v_mfma_f32_16x16x32_bf16 v[106:109], v[164:167], v[188:191], v[106:109]
	v_mfma_f32_16x16x32_bf16 v[106:109], v[168:171], v[192:195], v[106:109]
	v_mfma_f32_16x16x32_bf16 v[98:101], v[172:175], v[188:191], v[98:101]
	v_mfma_f32_16x16x32_bf16 v[98:101], v[176:179], v[192:195], v[98:101]
	v_mfma_f32_16x16x32_bf16 v[90:93], v[164:167], v[196:199], v[90:93]
	v_mfma_f32_16x16x32_bf16 v[90:93], v[168:171], v[200:203], v[90:93]
	v_mfma_f32_16x16x32_bf16 v[82:85], v[172:175], v[196:199], v[82:85]
	v_mfma_f32_16x16x32_bf16 v[82:85], v[176:179], v[200:203], v[82:85]
	v_mfma_f32_16x16x32_bf16 v[74:77], v[164:167], v[208:211], v[74:77]
	v_mfma_f32_16x16x32_bf16 v[74:77], v[168:171], v[212:215], v[74:77]
	v_mfma_f32_16x16x32_bf16 v[66:69], v[172:175], v[208:211], v[66:69]
	v_mfma_f32_16x16x32_bf16 v[66:69], v[176:179], v[212:215], v[66:69]
	s_setprio 0
	s_barrier
	s_add_i32 s40, s73, s33
	v_lshl_add_u64 v[204:205], v[204:205], 0, s[16:17]
	s_mov_b32 m0, s40
	ds_read_b128 v[180:183], v146 offset:49152
	ds_read_b128 v[184:187], v146 offset:50176
	ds_read_b128 v[188:191], v146 offset:51200
	ds_read_b128 v[192:195], v146 offset:52224
	ds_read_b128 v[196:199], v146 offset:53248
	ds_read_b128 v[200:203], v146 offset:54272
	ds_read_b128 v[208:211], v146 offset:55296
	ds_read_b128 v[212:215], v146 offset:56320
	global_load_lds_dwordx4 v[204:205], off
	s_add_i32 m0, s40, 0x2000
	s_add_u32 s2, s2, 0x80080
	v_lshl_add_u64 v[204:205], v[216:217], 0, s[16:17]
	s_addc_u32 s3, s3, 0
	s_add_i32 s40, s74, s33
	global_load_lds_dwordx4 v[204:205], off
	v_lshl_add_u64 v[204:205], s[2:3], 0, v[132:133]
	s_mov_b32 m0, s40
	s_nop 0
	global_load_lds_dwordx4 v[204:205], off
	v_lshl_add_u64 v[204:205], s[2:3], 0, v[136:137]
	s_add_i32 m0, s40, 0x2000
	s_nop 0
	global_load_lds_dwordx4 v[204:205], off
	v_lshl_add_u64 v[204:205], v[218:219], 0, s[16:17]
	s_mov_b32 m0, s46
	s_nop 0
	global_load_lds_dwordx4 v[204:205], off
	v_lshl_add_u64 v[204:205], v[220:221], 0, s[16:17]
	s_mov_b32 m0, s47
	s_nop 0
	global_load_lds_dwordx4 v[204:205], off
	s_waitcnt vmcnt(8)
	s_waitcnt lgkmcnt(0)
	s_barrier
	s_setprio 1
	s_waitcnt lgkmcnt(0)
	v_mfma_f32_16x16x32_bf16 v[62:65], v[148:151], v[180:183], v[62:65]
	v_mfma_f32_16x16x32_bf16 v[62:65], v[152:155], v[184:187], v[62:65]
	v_mfma_f32_16x16x32_bf16 v[54:57], v[156:159], v[180:183], v[54:57]
	v_mfma_f32_16x16x32_bf16 v[54:57], v[160:163], v[184:187], v[54:57]
	v_mfma_f32_16x16x32_bf16 v[46:49], v[148:151], v[188:191], v[46:49]
	v_mfma_f32_16x16x32_bf16 v[46:49], v[152:155], v[192:195], v[46:49]
	v_mfma_f32_16x16x32_bf16 v[38:41], v[156:159], v[188:191], v[38:41]
	v_mfma_f32_16x16x32_bf16 v[38:41], v[160:163], v[192:195], v[38:41]
	v_mfma_f32_16x16x32_bf16 v[30:33], v[148:151], v[196:199], v[30:33]
	v_mfma_f32_16x16x32_bf16 v[30:33], v[152:155], v[200:203], v[30:33]
	v_mfma_f32_16x16x32_bf16 v[22:25], v[156:159], v[196:199], v[22:25]
	v_mfma_f32_16x16x32_bf16 v[22:25], v[160:163], v[200:203], v[22:25]
	v_mfma_f32_16x16x32_bf16 v[14:17], v[148:151], v[208:211], v[14:17]
	v_mfma_f32_16x16x32_bf16 v[14:17], v[152:155], v[212:215], v[14:17]
	v_mfma_f32_16x16x32_bf16 v[6:9], v[156:159], v[208:211], v[6:9]
	v_mfma_f32_16x16x32_bf16 v[6:9], v[160:163], v[212:215], v[6:9]
	s_setprio 0
	s_setprio 1
	v_mfma_f32_16x16x32_bf16 v[58:61], v[164:167], v[180:183], v[58:61]
	v_mfma_f32_16x16x32_bf16 v[58:61], v[168:171], v[184:187], v[58:61]
	v_mfma_f32_16x16x32_bf16 v[50:53], v[172:175], v[180:183], v[50:53]
	v_mfma_f32_16x16x32_bf16 v[50:53], v[176:179], v[184:187], v[50:53]
	v_mfma_f32_16x16x32_bf16 v[42:45], v[164:167], v[188:191], v[42:45]
	v_mfma_f32_16x16x32_bf16 v[42:45], v[168:171], v[192:195], v[42:45]
	v_mfma_f32_16x16x32_bf16 v[34:37], v[172:175], v[188:191], v[34:37]
	v_mfma_f32_16x16x32_bf16 v[34:37], v[176:179], v[192:195], v[34:37]
	v_mfma_f32_16x16x32_bf16 v[26:29], v[164:167], v[196:199], v[26:29]
	v_mfma_f32_16x16x32_bf16 v[26:29], v[168:171], v[200:203], v[26:29]
	v_mfma_f32_16x16x32_bf16 v[18:21], v[172:175], v[196:199], v[18:21]
	v_mfma_f32_16x16x32_bf16 v[18:21], v[176:179], v[200:203], v[18:21]
	v_mfma_f32_16x16x32_bf16 v[10:13], v[164:167], v[208:211], v[10:13]
	v_mfma_f32_16x16x32_bf16 v[10:13], v[168:171], v[212:215], v[10:13]
	v_mfma_f32_16x16x32_bf16 v[2:5], v[172:175], v[208:211], v[2:5]
	v_mfma_f32_16x16x32_bf16 v[2:5], v[176:179], v[212:215], v[2:5]
	s_setprio 0
	s_barrier
	s_add_u32 s38, s38, 0x100
	s_addc_u32 s39, s39, 0
	s_add_u32 s68, s68, 0x100
	s_addc_u32 s69, s69, 0
	s_cmp_ge_i32 s72, s37
	s_mov_b32 s2, s72
	s_cbranch_scc1 .Lkpeel_exit_2
.LBB0_526:
	ds_read_b128 v[148:151], v144
	ds_read_b128 v[152:155], v144 offset:1024
	ds_read_b128 v[156:159], v144 offset:2048
	ds_read_b128 v[160:163], v144 offset:3072
	ds_read_b128 v[164:167], v145
	ds_read_b128 v[168:171], v145 offset:1024
	ds_read_b128 v[172:175], v145 offset:2048
	ds_read_b128 v[176:179], v145 offset:3072
	s_waitcnt lgkmcnt(0)
	s_add_i32 s72, s2, 2
	s_add_u32 s3, s38, 0xfff80080
	s_addc_u32 s40, s39, -1
	s_cmp_eq_u32 s67, s2
	s_cselect_b32 s2, s66, s68
	s_cselect_b32 s41, s0, s40
	s_cselect_b32 s40, s36, s3
	s_cselect_b32 s3, s65, s69
	v_lshl_add_u64 v[204:205], s[38:39], 0, v[138:139]
	s_add_i32 m0, s29, 0xc000
	ds_read_b128 v[180:183], v146
	ds_read_b128 v[184:187], v146 offset:1024
	ds_read_b128 v[188:191], v146 offset:2048
	ds_read_b128 v[192:195], v146 offset:3072
	ds_read_b128 v[196:199], v146 offset:4096
	ds_read_b128 v[200:203], v146 offset:5120
	ds_read_b128 v[208:211], v146 offset:6144
	ds_read_b128 v[212:215], v146 offset:7168
	global_load_lds_dwordx4 v[204:205], off
	v_lshl_add_u64 v[204:205], s[38:39], 0, v[140:141]
	s_add_i32 m0, s29, 0xe000
	s_nop 0
	global_load_lds_dwordx4 v[204:205], off
	s_waitcnt vmcnt(8)
	s_waitcnt lgkmcnt(0)
	s_barrier
	s_setprio 1
	s_waitcnt lgkmcnt(0)
	v_mfma_f32_16x16x32_bf16 v[126:129], v[148:151], v[180:183], v[126:129]
	v_mfma_f32_16x16x32_bf16 v[126:129], v[152:155], v[184:187], v[126:129]
	v_mfma_f32_16x16x32_bf16 v[122:125], v[156:159], v[180:183], v[122:125]
	v_mfma_f32_16x16x32_bf16 v[122:125], v[160:163], v[184:187], v[122:125]
	v_mfma_f32_16x16x32_bf16 v[110:113], v[148:151], v[188:191], v[110:113]
	v_mfma_f32_16x16x32_bf16 v[110:113], v[152:155], v[192:195], v[110:113]
	v_mfma_f32_16x16x32_bf16 v[102:105], v[156:159], v[188:191], v[102:105]
	v_mfma_f32_16x16x32_bf16 v[102:105], v[160:163], v[192:195], v[102:105]
	v_mfma_f32_16x16x32_bf16 v[94:97], v[148:151], v[196:199], v[94:97]
	v_mfma_f32_16x16x32_bf16 v[94:97], v[152:155], v[200:203], v[94:97]
	v_mfma_f32_16x16x32_bf16 v[86:89], v[156:159], v[196:199], v[86:89]
	v_mfma_f32_16x16x32_bf16 v[86:89], v[160:163], v[200:203], v[86:89]
	v_mfma_f32_16x16x32_bf16 v[78:81], v[148:151], v[208:211], v[78:81]
	v_mfma_f32_16x16x32_bf16 v[78:81], v[152:155], v[212:215], v[78:81]
	v_mfma_f32_16x16x32_bf16 v[70:73], v[156:159], v[208:211], v[70:73]
	v_mfma_f32_16x16x32_bf16 v[70:73], v[160:163], v[212:215], v[70:73]
	s_setprio 0
	s_setprio 1
	v_mfma_f32_16x16x32_bf16 v[118:121], v[164:167], v[180:183], v[118:121]
	v_mfma_f32_16x16x32_bf16 v[118:121], v[168:171], v[184:187], v[118:121]
	v_mfma_f32_16x16x32_bf16 v[114:117], v[172:175], v[180:183], v[114:117]
	v_mfma_f32_16x16x32_bf16 v[114:117], v[176:179], v[184:187], v[114:117]
	v_mfma_f32_16x16x32_bf16 v[106:109], v[164:167], v[188:191], v[106:109]
	v_mfma_f32_16x16x32_bf16 v[106:109], v[168:171], v[192:195], v[106:109]
	v_mfma_f32_16x16x32_bf16 v[98:101], v[172:175], v[188:191], v[98:101]
	v_mfma_f32_16x16x32_bf16 v[98:101], v[176:179], v[192:195], v[98:101]
	v_mfma_f32_16x16x32_bf16 v[90:93], v[164:167], v[196:199], v[90:93]
	v_mfma_f32_16x16x32_bf16 v[90:93], v[168:171], v[200:203], v[90:93]
	v_mfma_f32_16x16x32_bf16 v[82:85], v[172:175], v[196:199], v[82:85]
	v_mfma_f32_16x16x32_bf16 v[82:85], v[176:179], v[200:203], v[82:85]
	v_mfma_f32_16x16x32_bf16 v[74:77], v[164:167], v[208:211], v[74:77]
	v_mfma_f32_16x16x32_bf16 v[74:77], v[168:171], v[212:215], v[74:77]
	v_mfma_f32_16x16x32_bf16 v[66:69], v[172:175], v[208:211], v[66:69]
	v_mfma_f32_16x16x32_bf16 v[66:69], v[176:179], v[212:215], v[66:69]
	s_setprio 0
	s_barrier
	s_add_i32 s73, s52, s33
	v_lshl_add_u64 v[204:205], s[2:3], 0, v[132:133]
	s_mov_b32 m0, s73
	ds_read_b128 v[180:183], v146 offset:16384
	ds_read_b128 v[184:187], v146 offset:17408
	ds_read_b128 v[188:191], v146 offset:18432
	ds_read_b128 v[192:195], v146 offset:19456
	ds_read_b128 v[196:199], v146 offset:20480
	ds_read_b128 v[200:203], v146 offset:21504
	ds_read_b128 v[208:211], v146 offset:22528
	ds_read_b128 v[212:215], v146 offset:23552
	global_load_lds_dwordx4 v[204:205], off
	s_add_i32 m0, s73, 0x2000
	s_add_u32 s74, s2, 0x80000
	v_lshl_add_u64 v[216:217], s[2:3], 0, v[136:137]
	s_addc_u32 s75, s3, 0
	s_add_i32 s73, s53, s33
	global_load_lds_dwordx4 v[216:217], off
	v_lshl_add_u64 v[218:219], s[74:75], 0, v[132:133]
	s_mov_b32 m0, s73
	v_lshl_add_u64 v[220:221], s[40:41], 0, v[134:135]
	global_load_lds_dwordx4 v[218:219], off
	v_lshl_add_u64 v[218:219], s[74:75], 0, v[136:137]
	s_add_i32 m0, s73, 0x2000
	s_nop 0
	global_load_lds_dwordx4 v[218:219], off
	v_lshl_add_u64 v[218:219], s[40:41], 0, v[130:131]
	s_mov_b32 m0, s29
	s_nop 0
	global_load_lds_dwordx4 v[218:219], off
	s_mov_b32 m0, s35
	s_nop 0
	global_load_lds_dwordx4 v[220:221], off
	s_waitcnt vmcnt(8)
	s_waitcnt lgkmcnt(0)
	s_barrier
	s_setprio 1
	s_waitcnt lgkmcnt(0)
	v_mfma_f32_16x16x32_bf16 v[62:65], v[148:151], v[180:183], v[62:65]
	v_mfma_f32_16x16x32_bf16 v[62:65], v[152:155], v[184:187], v[62:65]
	v_mfma_f32_16x16x32_bf16 v[54:57], v[156:159], v[180:183], v[54:57]
	v_mfma_f32_16x16x32_bf16 v[54:57], v[160:163], v[184:187], v[54:57]
	v_mfma_f32_16x16x32_bf16 v[46:49], v[148:151], v[188:191], v[46:49]
	v_mfma_f32_16x16x32_bf16 v[46:49], v[152:155], v[192:195], v[46:49]
	v_mfma_f32_16x16x32_bf16 v[38:41], v[156:159], v[188:191], v[38:41]
	v_mfma_f32_16x16x32_bf16 v[38:41], v[160:163], v[192:195], v[38:41]
	v_mfma_f32_16x16x32_bf16 v[30:33], v[148:151], v[196:199], v[30:33]
	v_mfma_f32_16x16x32_bf16 v[30:33], v[152:155], v[200:203], v[30:33]
	v_mfma_f32_16x16x32_bf16 v[22:25], v[156:159], v[196:199], v[22:25]
	v_mfma_f32_16x16x32_bf16 v[22:25], v[160:163], v[200:203], v[22:25]
	v_mfma_f32_16x16x32_bf16 v[14:17], v[148:151], v[208:211], v[14:17]
	v_mfma_f32_16x16x32_bf16 v[14:17], v[152:155], v[212:215], v[14:17]
	v_mfma_f32_16x16x32_bf16 v[6:9], v[156:159], v[208:211], v[6:9]
	v_mfma_f32_16x16x32_bf16 v[6:9], v[160:163], v[212:215], v[6:9]
	s_setprio 0
	s_setprio 1
	v_mfma_f32_16x16x32_bf16 v[58:61], v[164:167], v[180:183], v[58:61]
	v_mfma_f32_16x16x32_bf16 v[58:61], v[168:171], v[184:187], v[58:61]
	v_mfma_f32_16x16x32_bf16 v[50:53], v[172:175], v[180:183], v[50:53]
	v_mfma_f32_16x16x32_bf16 v[50:53], v[176:179], v[184:187], v[50:53]
	v_mfma_f32_16x16x32_bf16 v[42:45], v[164:167], v[188:191], v[42:45]
	v_mfma_f32_16x16x32_bf16 v[42:45], v[168:171], v[192:195], v[42:45]
	v_mfma_f32_16x16x32_bf16 v[34:37], v[172:175], v[188:191], v[34:37]
	v_mfma_f32_16x16x32_bf16 v[34:37], v[176:179], v[192:195], v[34:37]
	v_mfma_f32_16x16x32_bf16 v[26:29], v[164:167], v[196:199], v[26:29]
	v_mfma_f32_16x16x32_bf16 v[26:29], v[168:171], v[200:203], v[26:29]
	v_mfma_f32_16x16x32_bf16 v[18:21], v[172:175], v[196:199], v[18:21]
	v_mfma_f32_16x16x32_bf16 v[18:21], v[176:179], v[200:203], v[18:21]
	v_mfma_f32_16x16x32_bf16 v[10:13], v[164:167], v[208:211], v[10:13]
	v_mfma_f32_16x16x32_bf16 v[10:13], v[168:171], v[212:215], v[10:13]
	v_mfma_f32_16x16x32_bf16 v[2:5], v[172:175], v[208:211], v[2:5]
	v_mfma_f32_16x16x32_bf16 v[2:5], v[176:179], v[212:215], v[2:5]
	s_setprio 0
	s_barrier
	s_add_i32 s73, 0, 0x18000
	v_add_u32_e32 v147, s73, v142
	s_add_i32 s74, 0, 0x1c000
	ds_read_b128 v[148:151], v147
	ds_read_b128 v[152:155], v147 offset:1024
	ds_read_b128 v[156:159], v147 offset:2048
	ds_read_b128 v[160:163], v147 offset:3072
	v_add_u32_e32 v147, s74, v142
	ds_read_b128 v[164:167], v147
	ds_read_b128 v[168:171], v147 offset:1024
	ds_read_b128 v[172:175], v147 offset:2048
	ds_read_b128 v[176:179], v147 offset:3072
	s_add_u32 s40, s40, 0x80000
	s_addc_u32 s41, s41, 0
	s_mov_b32 m0, s43
	v_lshl_add_u64 v[222:223], s[40:41], 0, v[130:131]
	ds_read_b128 v[180:183], v146 offset:32768
	ds_read_b128 v[184:187], v146 offset:33792
	ds_read_b128 v[188:191], v146 offset:34816
	ds_read_b128 v[192:195], v146 offset:35840
	ds_read_b128 v[196:199], v146 offset:36864
	ds_read_b128 v[200:203], v146 offset:37888
	ds_read_b128 v[208:211], v146 offset:38912
	ds_read_b128 v[212:215], v146 offset:39936
	global_load_lds_dwordx4 v[222:223], off
	v_lshl_add_u64 v[222:223], s[40:41], 0, v[134:135]
	s_mov_b32 m0, s44
	s_nop 0
	global_load_lds_dwordx4 v[222:223], off
	s_waitcnt vmcnt(8)
	s_waitcnt lgkmcnt(0)
	s_barrier
	s_setprio 1
	s_waitcnt lgkmcnt(0)
	v_mfma_f32_16x16x32_bf16 v[126:129], v[148:151], v[180:183], v[126:129]
	v_mfma_f32_16x16x32_bf16 v[126:129], v[152:155], v[184:187], v[126:129]
	v_mfma_f32_16x16x32_bf16 v[122:125], v[156:159], v[180:183], v[122:125]
	v_mfma_f32_16x16x32_bf16 v[122:125], v[160:163], v[184:187], v[122:125]
	v_mfma_f32_16x16x32_bf16 v[110:113], v[148:151], v[188:191], v[110:113]
	v_mfma_f32_16x16x32_bf16 v[110:113], v[152:155], v[192:195], v[110:113]
	v_mfma_f32_16x16x32_bf16 v[102:105], v[156:159], v[188:191], v[102:105]
	v_mfma_f32_16x16x32_bf16 v[102:105], v[160:163], v[192:195], v[102:105]
	v_mfma_f32_16x16x32_bf16 v[94:97], v[148:151], v[196:199], v[94:97]
	v_mfma_f32_16x16x32_bf16 v[94:97], v[152:155], v[200:203], v[94:97]
	v_mfma_f32_16x16x32_bf16 v[86:89], v[156:159], v[196:199], v[86:89]
	v_mfma_f32_16x16x32_bf16 v[86:89], v[160:163], v[200:203], v[86:89]
	v_mfma_f32_16x16x32_bf16 v[78:81], v[148:151], v[208:211], v[78:81]
	v_mfma_f32_16x16x32_bf16 v[78:81], v[152:155], v[212:215], v[78:81]
	v_mfma_f32_16x16x32_bf16 v[70:73], v[156:159], v[208:211], v[70:73]
	v_mfma_f32_16x16x32_bf16 v[70:73], v[160:163], v[212:215], v[70:73]
	s_setprio 0
	s_setprio 1
	v_mfma_f32_16x16x32_bf16 v[118:121], v[164:167], v[180:183], v[118:121]
	v_mfma_f32_16x16x32_bf16 v[118:121], v[168:171], v[184:187], v[118:121]
	v_mfma_f32_16x16x32_bf16 v[114:117], v[172:175], v[180:183], v[114:117]
	v_mfma_f32_16x16x32_bf16 v[114:117], v[176:179], v[184:187], v[114:117]
	v_mfma_f32_16x16x32_bf16 v[106:109], v[164:167], v[188:191], v[106:109]
	v_mfma_f32_16x16x32_bf16 v[106:109], v[168:171], v[192:195], v[106:109]
	v_mfma_f32_16x16x32_bf16 v[98:101], v[172:175], v[188:191], v[98:101]
	v_mfma_f32_16x16x32_bf16 v[98:101], v[176:179], v[192:195], v[98:101]
	v_mfma_f32_16x16x32_bf16 v[90:93], v[164:167], v[196:199], v[90:93]
	v_mfma_f32_16x16x32_bf16 v[90:93], v[168:171], v[200:203], v[90:93]
	v_mfma_f32_16x16x32_bf16 v[82:85], v[172:175], v[196:199], v[82:85]
	v_mfma_f32_16x16x32_bf16 v[82:85], v[176:179], v[200:203], v[82:85]
	v_mfma_f32_16x16x32_bf16 v[74:77], v[164:167], v[208:211], v[74:77]
	v_mfma_f32_16x16x32_bf16 v[74:77], v[168:171], v[212:215], v[74:77]
	v_mfma_f32_16x16x32_bf16 v[66:69], v[172:175], v[208:211], v[66:69]
	v_mfma_f32_16x16x32_bf16 v[66:69], v[176:179], v[212:215], v[66:69]
	s_setprio 0
	s_barrier
	s_add_i32 s40, s73, s33
	v_lshl_add_u64 v[204:205], v[204:205], 0, s[16:17]
	s_mov_b32 m0, s40
	ds_read_b128 v[180:183], v146 offset:49152
	ds_read_b128 v[184:187], v146 offset:50176
	ds_read_b128 v[188:191], v146 offset:51200
	ds_read_b128 v[192:195], v146 offset:52224
	ds_read_b128 v[196:199], v146 offset:53248
	ds_read_b128 v[200:203], v146 offset:54272
	ds_read_b128 v[208:211], v146 offset:55296
	ds_read_b128 v[212:215], v146 offset:56320
	global_load_lds_dwordx4 v[204:205], off
	s_add_i32 m0, s40, 0x2000
	s_add_u32 s2, s2, 0x80080
	v_lshl_add_u64 v[204:205], v[216:217], 0, s[16:17]
	s_addc_u32 s3, s3, 0
	s_add_i32 s40, s74, s33
	global_load_lds_dwordx4 v[204:205], off
	v_lshl_add_u64 v[204:205], s[2:3], 0, v[132:133]
	s_mov_b32 m0, s40
	s_nop 0
	global_load_lds_dwordx4 v[204:205], off
	v_lshl_add_u64 v[204:205], s[2:3], 0, v[136:137]
	s_add_i32 m0, s40, 0x2000
	s_nop 0
	global_load_lds_dwordx4 v[204:205], off
	v_lshl_add_u64 v[204:205], v[218:219], 0, s[16:17]
	s_mov_b32 m0, s46
	s_nop 0
	global_load_lds_dwordx4 v[204:205], off
	v_lshl_add_u64 v[204:205], v[220:221], 0, s[16:17]
	s_mov_b32 m0, s47
	s_nop 0
	global_load_lds_dwordx4 v[204:205], off
	s_waitcnt vmcnt(8)
	s_waitcnt lgkmcnt(0)
	s_barrier
	s_setprio 1
	s_waitcnt lgkmcnt(0)
	v_mfma_f32_16x16x32_bf16 v[62:65], v[148:151], v[180:183], v[62:65]
	v_mfma_f32_16x16x32_bf16 v[62:65], v[152:155], v[184:187], v[62:65]
	v_mfma_f32_16x16x32_bf16 v[54:57], v[156:159], v[180:183], v[54:57]
	v_mfma_f32_16x16x32_bf16 v[54:57], v[160:163], v[184:187], v[54:57]
	v_mfma_f32_16x16x32_bf16 v[46:49], v[148:151], v[188:191], v[46:49]
	v_mfma_f32_16x16x32_bf16 v[46:49], v[152:155], v[192:195], v[46:49]
	v_mfma_f32_16x16x32_bf16 v[38:41], v[156:159], v[188:191], v[38:41]
	v_mfma_f32_16x16x32_bf16 v[38:41], v[160:163], v[192:195], v[38:41]
	v_mfma_f32_16x16x32_bf16 v[30:33], v[148:151], v[196:199], v[30:33]
	v_mfma_f32_16x16x32_bf16 v[30:33], v[152:155], v[200:203], v[30:33]
	v_mfma_f32_16x16x32_bf16 v[22:25], v[156:159], v[196:199], v[22:25]
	v_mfma_f32_16x16x32_bf16 v[22:25], v[160:163], v[200:203], v[22:25]
	v_mfma_f32_16x16x32_bf16 v[14:17], v[148:151], v[208:211], v[14:17]
	v_mfma_f32_16x16x32_bf16 v[14:17], v[152:155], v[212:215], v[14:17]
	v_mfma_f32_16x16x32_bf16 v[6:9], v[156:159], v[208:211], v[6:9]
	v_mfma_f32_16x16x32_bf16 v[6:9], v[160:163], v[212:215], v[6:9]
	s_setprio 0
	s_setprio 1
	v_mfma_f32_16x16x32_bf16 v[58:61], v[164:167], v[180:183], v[58:61]
	v_mfma_f32_16x16x32_bf16 v[58:61], v[168:171], v[184:187], v[58:61]
	v_mfma_f32_16x16x32_bf16 v[50:53], v[172:175], v[180:183], v[50:53]
	v_mfma_f32_16x16x32_bf16 v[50:53], v[176:179], v[184:187], v[50:53]
	v_mfma_f32_16x16x32_bf16 v[42:45], v[164:167], v[188:191], v[42:45]
	v_mfma_f32_16x16x32_bf16 v[42:45], v[168:171], v[192:195], v[42:45]
	v_mfma_f32_16x16x32_bf16 v[34:37], v[172:175], v[188:191], v[34:37]
	v_mfma_f32_16x16x32_bf16 v[34:37], v[176:179], v[192:195], v[34:37]
	v_mfma_f32_16x16x32_bf16 v[26:29], v[164:167], v[196:199], v[26:29]
	v_mfma_f32_16x16x32_bf16 v[26:29], v[168:171], v[200:203], v[26:29]
	v_mfma_f32_16x16x32_bf16 v[18:21], v[172:175], v[196:199], v[18:21]
	v_mfma_f32_16x16x32_bf16 v[18:21], v[176:179], v[200:203], v[18:21]
	v_mfma_f32_16x16x32_bf16 v[10:13], v[164:167], v[208:211], v[10:13]
	v_mfma_f32_16x16x32_bf16 v[10:13], v[168:171], v[212:215], v[10:13]
	v_mfma_f32_16x16x32_bf16 v[2:5], v[172:175], v[208:211], v[2:5]
	v_mfma_f32_16x16x32_bf16 v[2:5], v[176:179], v[212:215], v[2:5]
	s_setprio 0
	s_barrier
	s_add_u32 s38, s38, 0x100
	s_addc_u32 s39, s39, 0
	s_add_u32 s68, s68, 0x100
	s_addc_u32 s69, s69, 0
	s_cmp_ge_i32 s72, s37
	s_mov_b32 s2, s72
	s_cbranch_scc0 .LBB0_526

.LBB0_632:
	s_lshl_b32 s11, s26, 20
	s_and_b32 s11, s11, 0xff00000
	v_readlane_b32 s46, v248, 20
	v_readlane_b32 s47, v248, 21
	s_add_u32 s11, s46, s11
	v_cmp_gt_i64_e64 s[0:1], s[26:27], -1
	s_addc_u32 s16, s47, 0
	s_lshr_b32 s27, s26, 13
	s_and_b32 s27, s27, 0x7ff80
	s_add_u32 s76, s11, s27
	s_addc_u32 s77, s16, 0
	s_lshl_b32 s11, s26, 12
	s_and_b32 s11, s11, 0xff00000
	s_add_u32 s11, s60, s11
	s_addc_u32 s16, s61, 0
	s_add_u32 s78, s11, s27
	s_addc_u32 s79, s16, 0
	s_cmp_lt_i32 s17, 1
	s_cbranch_scc1 .LBB0_640
	s_and_b64 s[26:27], s[0:1], exec
	s_cselect_b32 s11, s77, s19
	s_cselect_b32 s16, s76, s18
	s_cselect_b32 s46, s79, s3
	s_cselect_b32 s47, s78, s2
	s_add_i32 s50, s17, -2
	s_add_u32 s18, s18, 0x80080
	s_addc_u32 s19, s19, 0
	s_add_u32 s51, s2, 0x100
	s_addc_u32 s52, s3, 0
	s_mov_b32 s2, 0
	ds_read_b128 v[130:133], v197
	ds_read_b128 v[134:137], v197 offset:1024
	ds_read_b128 v[138:141], v197 offset:2048
	ds_read_b128 v[142:145], v197 offset:3072
	ds_read_b128 v[146:149], v198
	ds_read_b128 v[150:153], v198 offset:1024
	ds_read_b128 v[154:157], v198 offset:2048
	ds_read_b128 v[170:173], v198 offset:3072
	s_add_i32 s53, s2, 2
	s_add_u32 s3, s18, 0xfff80080
	s_addc_u32 s26, s19, -1
	s_cmp_eq_u32 s50, s2
	s_cselect_b32 s2, s47, s51
	s_cselect_b32 s27, s11, s26
	s_cselect_b32 s26, s16, s3
	s_cselect_b32 s3, s46, s52
	v_lshl_add_u64 v[204:205], s[18:19], 0, v[166:167]
	s_add_i32 m0, s13, 0xc000
	ds_read_b128 v[174:177], v199
	ds_read_b128 v[178:181], v199 offset:1024
	ds_read_b128 v[182:185], v199 offset:2048
	ds_read_b128 v[186:189], v199 offset:3072
	ds_read_b128 v[190:193], v199 offset:4096
	ds_read_b128 v[200:203], v199 offset:5120
	ds_read_b128 v[208:211], v199 offset:6144
	ds_read_b128 v[212:215], v199 offset:7168
	global_load_lds_dwordx4 v[204:205], off
	v_lshl_add_u64 v[204:205], s[18:19], 0, v[168:169]
	s_add_i32 m0, s13, 0xe000
	s_nop 0
	global_load_lds_dwordx4 v[204:205], off
	s_waitcnt vmcnt(8)
	s_waitcnt lgkmcnt(0)
	s_barrier
	s_setprio 1
	s_waitcnt lgkmcnt(0)
	v_mfma_f32_16x16x32_bf16 v[122:125], v[130:133], v[174:177], 0
	v_mfma_f32_16x16x32_bf16 v[122:125], v[134:137], v[178:181], v[122:125]
	v_mfma_f32_16x16x32_bf16 v[114:117], v[138:141], v[174:177], 0
	v_mfma_f32_16x16x32_bf16 v[114:117], v[142:145], v[178:181], v[114:117]
	v_mfma_f32_16x16x32_bf16 v[106:109], v[130:133], v[182:185], 0
	v_mfma_f32_16x16x32_bf16 v[106:109], v[134:137], v[186:189], v[106:109]
	v_mfma_f32_16x16x32_bf16 v[98:101], v[138:141], v[182:185], 0
	v_mfma_f32_16x16x32_bf16 v[98:101], v[142:145], v[186:189], v[98:101]
	v_mfma_f32_16x16x32_bf16 v[90:93], v[130:133], v[190:193], 0
	v_mfma_f32_16x16x32_bf16 v[90:93], v[134:137], v[200:203], v[90:93]
	v_mfma_f32_16x16x32_bf16 v[82:85], v[138:141], v[190:193], 0
	v_mfma_f32_16x16x32_bf16 v[82:85], v[142:145], v[200:203], v[82:85]
	v_mfma_f32_16x16x32_bf16 v[74:77], v[130:133], v[208:211], 0
	v_mfma_f32_16x16x32_bf16 v[74:77], v[134:137], v[212:215], v[74:77]
	v_mfma_f32_16x16x32_bf16 v[66:69], v[138:141], v[208:211], 0
	v_mfma_f32_16x16x32_bf16 v[66:69], v[142:145], v[212:215], v[66:69]
	s_setprio 0
	s_setprio 1
	v_mfma_f32_16x16x32_bf16 v[126:129], v[146:149], v[174:177], 0
	v_mfma_f32_16x16x32_bf16 v[126:129], v[150:153], v[178:181], v[126:129]
	v_mfma_f32_16x16x32_bf16 v[118:121], v[154:157], v[174:177], 0
	v_mfma_f32_16x16x32_bf16 v[118:121], v[170:173], v[178:181], v[118:121]
	v_mfma_f32_16x16x32_bf16 v[110:113], v[146:149], v[182:185], 0
	v_mfma_f32_16x16x32_bf16 v[110:113], v[150:153], v[186:189], v[110:113]
	v_mfma_f32_16x16x32_bf16 v[102:105], v[154:157], v[182:185], 0
	v_mfma_f32_16x16x32_bf16 v[102:105], v[170:173], v[186:189], v[102:105]
	v_mfma_f32_16x16x32_bf16 v[94:97], v[146:149], v[190:193], 0
	v_mfma_f32_16x16x32_bf16 v[94:97], v[150:153], v[200:203], v[94:97]
	v_mfma_f32_16x16x32_bf16 v[86:89], v[154:157], v[190:193], 0
	v_mfma_f32_16x16x32_bf16 v[86:89], v[170:173], v[200:203], v[86:89]
	v_mfma_f32_16x16x32_bf16 v[78:81], v[146:149], v[208:211], 0
	v_mfma_f32_16x16x32_bf16 v[78:81], v[150:153], v[212:215], v[78:81]
	v_mfma_f32_16x16x32_bf16 v[70:73], v[154:157], v[208:211], 0
	v_mfma_f32_16x16x32_bf16 v[70:73], v[170:173], v[212:215], v[70:73]
	s_setprio 0
	s_barrier
	s_add_i32 s64, s44, s35
	v_lshl_add_u64 v[204:205], s[2:3], 0, v[160:161]
	s_mov_b32 m0, s64
	ds_read_b128 v[174:177], v199 offset:16384
	ds_read_b128 v[178:181], v199 offset:17408
	ds_read_b128 v[182:185], v199 offset:18432
	ds_read_b128 v[186:189], v199 offset:19456
	ds_read_b128 v[190:193], v199 offset:20480
	ds_read_b128 v[200:203], v199 offset:21504
	ds_read_b128 v[208:211], v199 offset:22528
	ds_read_b128 v[212:215], v199 offset:23552
	global_load_lds_dwordx4 v[204:205], off
	s_add_i32 m0, s64, 0x2000
	s_add_u32 s80, s2, 0x80000
	v_lshl_add_u64 v[216:217], s[2:3], 0, v[164:165]
	s_addc_u32 s81, s3, 0
	s_add_i32 s64, s45, s35
	global_load_lds_dwordx4 v[216:217], off
	v_lshl_add_u64 v[218:219], s[80:81], 0, v[160:161]
	s_mov_b32 m0, s64
	v_lshl_add_u64 v[220:221], s[26:27], 0, v[162:163]
	global_load_lds_dwordx4 v[218:219], off
	v_lshl_add_u64 v[218:219], s[80:81], 0, v[164:165]
	s_add_i32 m0, s64, 0x2000
	s_nop 0
	global_load_lds_dwordx4 v[218:219], off
	v_lshl_add_u64 v[218:219], s[26:27], 0, v[158:159]
	s_mov_b32 m0, s13
	s_nop 0
	global_load_lds_dwordx4 v[218:219], off
	s_mov_b32 m0, s36
	s_nop 0
	global_load_lds_dwordx4 v[220:221], off
	s_waitcnt vmcnt(8)
	s_waitcnt lgkmcnt(0)
	s_barrier
	s_setprio 1
	s_waitcnt lgkmcnt(0)
	v_mfma_f32_16x16x32_bf16 v[58:61], v[130:133], v[174:177], 0
	v_mfma_f32_16x16x32_bf16 v[58:61], v[134:137], v[178:181], v[58:61]
	v_mfma_f32_16x16x32_bf16 v[50:53], v[138:141], v[174:177], 0
	v_mfma_f32_16x16x32_bf16 v[50:53], v[142:145], v[178:181], v[50:53]
	v_mfma_f32_16x16x32_bf16 v[42:45], v[130:133], v[182:185], 0
	v_mfma_f32_16x16x32_bf16 v[42:45], v[134:137], v[186:189], v[42:45]
	v_mfma_f32_16x16x32_bf16 v[34:37], v[138:141], v[182:185], 0
	v_mfma_f32_16x16x32_bf16 v[34:37], v[142:145], v[186:189], v[34:37]
	v_mfma_f32_16x16x32_bf16 v[26:29], v[130:133], v[190:193], 0
	v_mfma_f32_16x16x32_bf16 v[26:29], v[134:137], v[200:203], v[26:29]
	v_mfma_f32_16x16x32_bf16 v[18:21], v[138:141], v[190:193], 0
	v_mfma_f32_16x16x32_bf16 v[18:21], v[142:145], v[200:203], v[18:21]
	v_mfma_f32_16x16x32_bf16 v[10:13], v[130:133], v[208:211], 0
	v_mfma_f32_16x16x32_bf16 v[10:13], v[134:137], v[212:215], v[10:13]
	v_mfma_f32_16x16x32_bf16 v[2:5], v[138:141], v[208:211], 0
	v_mfma_f32_16x16x32_bf16 v[2:5], v[142:145], v[212:215], v[2:5]
	s_setprio 0
	s_setprio 1
	v_mfma_f32_16x16x32_bf16 v[62:65], v[146:149], v[174:177], 0
	v_mfma_f32_16x16x32_bf16 v[62:65], v[150:153], v[178:181], v[62:65]
	v_mfma_f32_16x16x32_bf16 v[54:57], v[154:157], v[174:177], 0
	v_mfma_f32_16x16x32_bf16 v[54:57], v[170:173], v[178:181], v[54:57]
	v_mfma_f32_16x16x32_bf16 v[46:49], v[146:149], v[182:185], 0
	v_mfma_f32_16x16x32_bf16 v[46:49], v[150:153], v[186:189], v[46:49]
	v_mfma_f32_16x16x32_bf16 v[38:41], v[154:157], v[182:185], 0
	v_mfma_f32_16x16x32_bf16 v[38:41], v[170:173], v[186:189], v[38:41]
	v_mfma_f32_16x16x32_bf16 v[30:33], v[146:149], v[190:193], 0
	v_mfma_f32_16x16x32_bf16 v[30:33], v[150:153], v[200:203], v[30:33]
	v_mfma_f32_16x16x32_bf16 v[22:25], v[154:157], v[190:193], 0
	v_mfma_f32_16x16x32_bf16 v[22:25], v[170:173], v[200:203], v[22:25]
	v_mfma_f32_16x16x32_bf16 v[14:17], v[146:149], v[208:211], 0
	v_mfma_f32_16x16x32_bf16 v[14:17], v[150:153], v[212:215], v[14:17]
	v_mfma_f32_16x16x32_bf16 v[6:9], v[154:157], v[208:211], 0
	v_mfma_f32_16x16x32_bf16 v[6:9], v[170:173], v[212:215], v[6:9]
	s_setprio 0
	s_barrier
	s_add_i32 s64, 0, 0x18000
	s_add_i32 s75, 0, 0x1c000
	v_add_u32_e32 v142, s64, v194
	v_add_u32_e32 v170, s75, v194
	ds_read_b128 v[130:133], v142
	ds_read_b128 v[134:137], v142 offset:1024
	ds_read_b128 v[138:141], v142 offset:2048
	ds_read_b128 v[142:145], v142 offset:3072
	ds_read_b128 v[146:149], v170
	ds_read_b128 v[150:153], v170 offset:1024
	ds_read_b128 v[154:157], v170 offset:2048
	ds_read_b128 v[170:173], v170 offset:3072
	s_add_u32 s26, s26, 0x80000
	s_addc_u32 s27, s27, 0
	s_mov_b32 m0, s37
	v_lshl_add_u64 v[222:223], s[26:27], 0, v[158:159]
	ds_read_b128 v[174:177], v199 offset:32768
	ds_read_b128 v[178:181], v199 offset:33792
	ds_read_b128 v[182:185], v199 offset:34816
	ds_read_b128 v[186:189], v199 offset:35840
	ds_read_b128 v[190:193], v199 offset:36864
	ds_read_b128 v[200:203], v199 offset:37888
	ds_read_b128 v[208:211], v199 offset:38912
	ds_read_b128 v[212:215], v199 offset:39936
	global_load_lds_dwordx4 v[222:223], off
	v_lshl_add_u64 v[222:223], s[26:27], 0, v[162:163]
	s_mov_b32 m0, s38
	s_nop 0
	global_load_lds_dwordx4 v[222:223], off
	s_waitcnt vmcnt(8)
	s_waitcnt lgkmcnt(0)
	s_barrier
	s_setprio 1
	s_waitcnt lgkmcnt(0)
	v_mfma_f32_16x16x32_bf16 v[122:125], v[130:133], v[174:177], v[122:125]
	v_mfma_f32_16x16x32_bf16 v[122:125], v[134:137], v[178:181], v[122:125]
	v_mfma_f32_16x16x32_bf16 v[114:117], v[138:141], v[174:177], v[114:117]
	v_mfma_f32_16x16x32_bf16 v[114:117], v[142:145], v[178:181], v[114:117]
	v_mfma_f32_16x16x32_bf16 v[106:109], v[130:133], v[182:185], v[106:109]
	v_mfma_f32_16x16x32_bf16 v[106:109], v[134:137], v[186:189], v[106:109]
	v_mfma_f32_16x16x32_bf16 v[98:101], v[138:141], v[182:185], v[98:101]
	v_mfma_f32_16x16x32_bf16 v[98:101], v[142:145], v[186:189], v[98:101]
	v_mfma_f32_16x16x32_bf16 v[90:93], v[130:133], v[190:193], v[90:93]
	v_mfma_f32_16x16x32_bf16 v[90:93], v[134:137], v[200:203], v[90:93]
	v_mfma_f32_16x16x32_bf16 v[82:85], v[138:141], v[190:193], v[82:85]
	v_mfma_f32_16x16x32_bf16 v[82:85], v[142:145], v[200:203], v[82:85]
	v_mfma_f32_16x16x32_bf16 v[74:77], v[130:133], v[208:211], v[74:77]
	v_mfma_f32_16x16x32_bf16 v[74:77], v[134:137], v[212:215], v[74:77]
	v_mfma_f32_16x16x32_bf16 v[66:69], v[138:141], v[208:211], v[66:69]
	v_mfma_f32_16x16x32_bf16 v[66:69], v[142:145], v[212:215], v[66:69]
	s_setprio 0
	s_setprio 1
	v_mfma_f32_16x16x32_bf16 v[126:129], v[146:149], v[174:177], v[126:129]
	v_mfma_f32_16x16x32_bf16 v[126:129], v[150:153], v[178:181], v[126:129]
	v_mfma_f32_16x16x32_bf16 v[118:121], v[154:157], v[174:177], v[118:121]
	v_mfma_f32_16x16x32_bf16 v[118:121], v[170:173], v[178:181], v[118:121]
	v_mfma_f32_16x16x32_bf16 v[110:113], v[146:149], v[182:185], v[110:113]
	v_mfma_f32_16x16x32_bf16 v[110:113], v[150:153], v[186:189], v[110:113]
	v_mfma_f32_16x16x32_bf16 v[102:105], v[154:157], v[182:185], v[102:105]
	v_mfma_f32_16x16x32_bf16 v[102:105], v[170:173], v[186:189], v[102:105]
	v_mfma_f32_16x16x32_bf16 v[94:97], v[146:149], v[190:193], v[94:97]
	v_mfma_f32_16x16x32_bf16 v[94:97], v[150:153], v[200:203], v[94:97]
	v_mfma_f32_16x16x32_bf16 v[86:89], v[154:157], v[190:193], v[86:89]
	v_mfma_f32_16x16x32_bf16 v[86:89], v[170:173], v[200:203], v[86:89]
	v_mfma_f32_16x16x32_bf16 v[78:81], v[146:149], v[208:211], v[78:81]
	v_mfma_f32_16x16x32_bf16 v[78:81], v[150:153], v[212:215], v[78:81]
	v_mfma_f32_16x16x32_bf16 v[70:73], v[154:157], v[208:211], v[70:73]
	v_mfma_f32_16x16x32_bf16 v[70:73], v[170:173], v[212:215], v[70:73]
	s_setprio 0
	s_barrier
	s_add_i32 s26, s64, s35
	v_lshl_add_u64 v[204:205], v[204:205], 0, s[68:69]
	s_mov_b32 m0, s26
	ds_read_b128 v[174:177], v199 offset:49152
	ds_read_b128 v[178:181], v199 offset:50176
	ds_read_b128 v[182:185], v199 offset:51200
	ds_read_b128 v[186:189], v199 offset:52224
	ds_read_b128 v[190:193], v199 offset:53248
	ds_read_b128 v[200:203], v199 offset:54272
	ds_read_b128 v[208:211], v199 offset:55296
	ds_read_b128 v[212:215], v199 offset:56320
	global_load_lds_dwordx4 v[204:205], off
	s_add_i32 m0, s26, 0x2000
	s_add_u32 s2, s2, 0x80080
	v_lshl_add_u64 v[204:205], v[216:217], 0, s[68:69]
	s_addc_u32 s3, s3, 0
	s_add_i32 s26, s75, s35
	global_load_lds_dwordx4 v[204:205], off
	v_lshl_add_u64 v[204:205], s[2:3], 0, v[160:161]
	s_mov_b32 m0, s26
	s_nop 0
	global_load_lds_dwordx4 v[204:205], off
	v_lshl_add_u64 v[204:205], s[2:3], 0, v[164:165]
	s_add_i32 m0, s26, 0x2000
	s_nop 0
	global_load_lds_dwordx4 v[204:205], off
	v_lshl_add_u64 v[204:205], v[218:219], 0, s[68:69]
	s_mov_b32 m0, s40
	s_nop 0
	global_load_lds_dwordx4 v[204:205], off
	v_lshl_add_u64 v[204:205], v[220:221], 0, s[68:69]
	s_mov_b32 m0, s41
	s_nop 0
	global_load_lds_dwordx4 v[204:205], off
	s_waitcnt vmcnt(8)
	s_waitcnt lgkmcnt(0)
	s_barrier
	s_setprio 1
	s_waitcnt lgkmcnt(0)
	v_mfma_f32_16x16x32_bf16 v[58:61], v[130:133], v[174:177], v[58:61]
	v_mfma_f32_16x16x32_bf16 v[58:61], v[134:137], v[178:181], v[58:61]
	v_mfma_f32_16x16x32_bf16 v[50:53], v[138:141], v[174:177], v[50:53]
	v_mfma_f32_16x16x32_bf16 v[50:53], v[142:145], v[178:181], v[50:53]
	v_mfma_f32_16x16x32_bf16 v[42:45], v[130:133], v[182:185], v[42:45]
	v_mfma_f32_16x16x32_bf16 v[42:45], v[134:137], v[186:189], v[42:45]
	v_mfma_f32_16x16x32_bf16 v[34:37], v[138:141], v[182:185], v[34:37]
	v_mfma_f32_16x16x32_bf16 v[34:37], v[142:145], v[186:189], v[34:37]
	v_mfma_f32_16x16x32_bf16 v[26:29], v[130:133], v[190:193], v[26:29]
	v_mfma_f32_16x16x32_bf16 v[26:29], v[134:137], v[200:203], v[26:29]
	v_mfma_f32_16x16x32_bf16 v[18:21], v[138:141], v[190:193], v[18:21]
	v_mfma_f32_16x16x32_bf16 v[18:21], v[142:145], v[200:203], v[18:21]
	v_mfma_f32_16x16x32_bf16 v[10:13], v[130:133], v[208:211], v[10:13]
	v_mfma_f32_16x16x32_bf16 v[10:13], v[134:137], v[212:215], v[10:13]
	v_mfma_f32_16x16x32_bf16 v[2:5], v[138:141], v[208:211], v[2:5]
	v_mfma_f32_16x16x32_bf16 v[2:5], v[142:145], v[212:215], v[2:5]
	s_setprio 0
	s_setprio 1
	v_mfma_f32_16x16x32_bf16 v[62:65], v[146:149], v[174:177], v[62:65]
	v_mfma_f32_16x16x32_bf16 v[62:65], v[150:153], v[178:181], v[62:65]
	v_mfma_f32_16x16x32_bf16 v[54:57], v[154:157], v[174:177], v[54:57]
	v_mfma_f32_16x16x32_bf16 v[54:57], v[170:173], v[178:181], v[54:57]
	v_mfma_f32_16x16x32_bf16 v[46:49], v[146:149], v[182:185], v[46:49]
	v_mfma_f32_16x16x32_bf16 v[46:49], v[150:153], v[186:189], v[46:49]
	v_mfma_f32_16x16x32_bf16 v[38:41], v[154:157], v[182:185], v[38:41]
	v_mfma_f32_16x16x32_bf16 v[38:41], v[170:173], v[186:189], v[38:41]
	v_mfma_f32_16x16x32_bf16 v[30:33], v[146:149], v[190:193], v[30:33]
	v_mfma_f32_16x16x32_bf16 v[30:33], v[150:153], v[200:203], v[30:33]
	v_mfma_f32_16x16x32_bf16 v[22:25], v[154:157], v[190:193], v[22:25]
	v_mfma_f32_16x16x32_bf16 v[22:25], v[170:173], v[200:203], v[22:25]
	v_mfma_f32_16x16x32_bf16 v[14:17], v[146:149], v[208:211], v[14:17]
	v_mfma_f32_16x16x32_bf16 v[14:17], v[150:153], v[212:215], v[14:17]
	v_mfma_f32_16x16x32_bf16 v[6:9], v[154:157], v[208:211], v[6:9]
	v_mfma_f32_16x16x32_bf16 v[6:9], v[170:173], v[212:215], v[6:9]
	s_setprio 0
	s_barrier
	s_add_u32 s18, s18, 0x100
	s_addc_u32 s19, s19, 0
	s_add_u32 s51, s51, 0x100
	s_addc_u32 s52, s52, 0
	s_cmp_ge_i32 s53, s17
	s_mov_b32 s2, s53
	s_cbranch_scc1 .Lkpeel_exit_3
.LBB0_634:
	ds_read_b128 v[130:133], v197
	ds_read_b128 v[134:137], v197 offset:1024
	ds_read_b128 v[138:141], v197 offset:2048
	ds_read_b128 v[142:145], v197 offset:3072
	ds_read_b128 v[146:149], v198
	ds_read_b128 v[150:153], v198 offset:1024
	ds_read_b128 v[154:157], v198 offset:2048
	ds_read_b128 v[170:173], v198 offset:3072
	s_add_i32 s53, s2, 2
	s_add_u32 s3, s18, 0xfff80080
	s_addc_u32 s26, s19, -1
	s_cmp_eq_u32 s50, s2
	s_cselect_b32 s2, s47, s51
	s_cselect_b32 s27, s11, s26
	s_cselect_b32 s26, s16, s3
	s_cselect_b32 s3, s46, s52
	v_lshl_add_u64 v[204:205], s[18:19], 0, v[166:167]
	s_add_i32 m0, s13, 0xc000
	ds_read_b128 v[174:177], v199
	ds_read_b128 v[178:181], v199 offset:1024
	ds_read_b128 v[182:185], v199 offset:2048
	ds_read_b128 v[186:189], v199 offset:3072
	ds_read_b128 v[190:193], v199 offset:4096
	ds_read_b128 v[200:203], v199 offset:5120
	ds_read_b128 v[208:211], v199 offset:6144
	ds_read_b128 v[212:215], v199 offset:7168
	global_load_lds_dwordx4 v[204:205], off
	v_lshl_add_u64 v[204:205], s[18:19], 0, v[168:169]
	s_add_i32 m0, s13, 0xe000
	s_nop 0
	global_load_lds_dwordx4 v[204:205], off
	s_waitcnt vmcnt(8)
	s_waitcnt lgkmcnt(0)
	s_barrier
	s_setprio 1
	s_waitcnt lgkmcnt(0)
	v_mfma_f32_16x16x32_bf16 v[122:125], v[130:133], v[174:177], v[122:125]
	v_mfma_f32_16x16x32_bf16 v[122:125], v[134:137], v[178:181], v[122:125]
	v_mfma_f32_16x16x32_bf16 v[114:117], v[138:141], v[174:177], v[114:117]
	v_mfma_f32_16x16x32_bf16 v[114:117], v[142:145], v[178:181], v[114:117]
	v_mfma_f32_16x16x32_bf16 v[106:109], v[130:133], v[182:185], v[106:109]
	v_mfma_f32_16x16x32_bf16 v[106:109], v[134:137], v[186:189], v[106:109]
	v_mfma_f32_16x16x32_bf16 v[98:101], v[138:141], v[182:185], v[98:101]
	v_mfma_f32_16x16x32_bf16 v[98:101], v[142:145], v[186:189], v[98:101]
	v_mfma_f32_16x16x32_bf16 v[90:93], v[130:133], v[190:193], v[90:93]
	v_mfma_f32_16x16x32_bf16 v[90:93], v[134:137], v[200:203], v[90:93]
	v_mfma_f32_16x16x32_bf16 v[82:85], v[138:141], v[190:193], v[82:85]
	v_mfma_f32_16x16x32_bf16 v[82:85], v[142:145], v[200:203], v[82:85]
	v_mfma_f32_16x16x32_bf16 v[74:77], v[130:133], v[208:211], v[74:77]
	v_mfma_f32_16x16x32_bf16 v[74:77], v[134:137], v[212:215], v[74:77]
	v_mfma_f32_16x16x32_bf16 v[66:69], v[138:141], v[208:211], v[66:69]
	v_mfma_f32_16x16x32_bf16 v[66:69], v[142:145], v[212:215], v[66:69]
	s_setprio 0
	s_setprio 1
	v_mfma_f32_16x16x32_bf16 v[126:129], v[146:149], v[174:177], v[126:129]
	v_mfma_f32_16x16x32_bf16 v[126:129], v[150:153], v[178:181], v[126:129]
	v_mfma_f32_16x16x32_bf16 v[118:121], v[154:157], v[174:177], v[118:121]
	v_mfma_f32_16x16x32_bf16 v[118:121], v[170:173], v[178:181], v[118:121]
	v_mfma_f32_16x16x32_bf16 v[110:113], v[146:149], v[182:185], v[110:113]
	v_mfma_f32_16x16x32_bf16 v[110:113], v[150:153], v[186:189], v[110:113]
	v_mfma_f32_16x16x32_bf16 v[102:105], v[154:157], v[182:185], v[102:105]
	v_mfma_f32_16x16x32_bf16 v[102:105], v[170:173], v[186:189], v[102:105]
	v_mfma_f32_16x16x32_bf16 v[94:97], v[146:149], v[190:193], v[94:97]
	v_mfma_f32_16x16x32_bf16 v[94:97], v[150:153], v[200:203], v[94:97]
	v_mfma_f32_16x16x32_bf16 v[86:89], v[154:157], v[190:193], v[86:89]
	v_mfma_f32_16x16x32_bf16 v[86:89], v[170:173], v[200:203], v[86:89]
	v_mfma_f32_16x16x32_bf16 v[78:81], v[146:149], v[208:211], v[78:81]
	v_mfma_f32_16x16x32_bf16 v[78:81], v[150:153], v[212:215], v[78:81]
	v_mfma_f32_16x16x32_bf16 v[70:73], v[154:157], v[208:211], v[70:73]
	v_mfma_f32_16x16x32_bf16 v[70:73], v[170:173], v[212:215], v[70:73]
	s_setprio 0
	s_barrier
	s_add_i32 s64, s44, s35
	v_lshl_add_u64 v[204:205], s[2:3], 0, v[160:161]
	s_mov_b32 m0, s64
	ds_read_b128 v[174:177], v199 offset:16384
	ds_read_b128 v[178:181], v199 offset:17408
	ds_read_b128 v[182:185], v199 offset:18432
	ds_read_b128 v[186:189], v199 offset:19456
	ds_read_b128 v[190:193], v199 offset:20480
	ds_read_b128 v[200:203], v199 offset:21504
	ds_read_b128 v[208:211], v199 offset:22528
	ds_read_b128 v[212:215], v199 offset:23552
	global_load_lds_dwordx4 v[204:205], off
	s_add_i32 m0, s64, 0x2000
	s_add_u32 s80, s2, 0x80000
	v_lshl_add_u64 v[216:217], s[2:3], 0, v[164:165]
	s_addc_u32 s81, s3, 0
	s_add_i32 s64, s45, s35
	global_load_lds_dwordx4 v[216:217], off
	v_lshl_add_u64 v[218:219], s[80:81], 0, v[160:161]
	s_mov_b32 m0, s64
	v_lshl_add_u64 v[220:221], s[26:27], 0, v[162:163]
	global_load_lds_dwordx4 v[218:219], off
	v_lshl_add_u64 v[218:219], s[80:81], 0, v[164:165]
	s_add_i32 m0, s64, 0x2000
	s_nop 0
	global_load_lds_dwordx4 v[218:219], off
	v_lshl_add_u64 v[218:219], s[26:27], 0, v[158:159]
	s_mov_b32 m0, s13
	s_nop 0
	global_load_lds_dwordx4 v[218:219], off
	s_mov_b32 m0, s36
	s_nop 0
	global_load_lds_dwordx4 v[220:221], off
	s_waitcnt vmcnt(8)
	s_waitcnt lgkmcnt(0)
	s_barrier
	s_setprio 1
	s_waitcnt lgkmcnt(0)
	v_mfma_f32_16x16x32_bf16 v[58:61], v[130:133], v[174:177], v[58:61]
	v_mfma_f32_16x16x32_bf16 v[58:61], v[134:137], v[178:181], v[58:61]
	v_mfma_f32_16x16x32_bf16 v[50:53], v[138:141], v[174:177], v[50:53]
	v_mfma_f32_16x16x32_bf16 v[50:53], v[142:145], v[178:181], v[50:53]
	v_mfma_f32_16x16x32_bf16 v[42:45], v[130:133], v[182:185], v[42:45]
	v_mfma_f32_16x16x32_bf16 v[42:45], v[134:137], v[186:189], v[42:45]
	v_mfma_f32_16x16x32_bf16 v[34:37], v[138:141], v[182:185], v[34:37]
	v_mfma_f32_16x16x32_bf16 v[34:37], v[142:145], v[186:189], v[34:37]
	v_mfma_f32_16x16x32_bf16 v[26:29], v[130:133], v[190:193], v[26:29]
	v_mfma_f32_16x16x32_bf16 v[26:29], v[134:137], v[200:203], v[26:29]
	v_mfma_f32_16x16x32_bf16 v[18:21], v[138:141], v[190:193], v[18:21]
	v_mfma_f32_16x16x32_bf16 v[18:21], v[142:145], v[200:203], v[18:21]
	v_mfma_f32_16x16x32_bf16 v[10:13], v[130:133], v[208:211], v[10:13]
	v_mfma_f32_16x16x32_bf16 v[10:13], v[134:137], v[212:215], v[10:13]
	v_mfma_f32_16x16x32_bf16 v[2:5], v[138:141], v[208:211], v[2:5]
	v_mfma_f32_16x16x32_bf16 v[2:5], v[142:145], v[212:215], v[2:5]
	s_setprio 0
	s_setprio 1
	v_mfma_f32_16x16x32_bf16 v[62:65], v[146:149], v[174:177], v[62:65]
	v_mfma_f32_16x16x32_bf16 v[62:65], v[150:153], v[178:181], v[62:65]
	v_mfma_f32_16x16x32_bf16 v[54:57], v[154:157], v[174:177], v[54:57]
	v_mfma_f32_16x16x32_bf16 v[54:57], v[170:173], v[178:181], v[54:57]
	v_mfma_f32_16x16x32_bf16 v[46:49], v[146:149], v[182:185], v[46:49]
	v_mfma_f32_16x16x32_bf16 v[46:49], v[150:153], v[186:189], v[46:49]
	v_mfma_f32_16x16x32_bf16 v[38:41], v[154:157], v[182:185], v[38:41]
	v_mfma_f32_16x16x32_bf16 v[38:41], v[170:173], v[186:189], v[38:41]
	v_mfma_f32_16x16x32_bf16 v[30:33], v[146:149], v[190:193], v[30:33]
	v_mfma_f32_16x16x32_bf16 v[30:33], v[150:153], v[200:203], v[30:33]
	v_mfma_f32_16x16x32_bf16 v[22:25], v[154:157], v[190:193], v[22:25]
	v_mfma_f32_16x16x32_bf16 v[22:25], v[170:173], v[200:203], v[22:25]
	v_mfma_f32_16x16x32_bf16 v[14:17], v[146:149], v[208:211], v[14:17]
	v_mfma_f32_16x16x32_bf16 v[14:17], v[150:153], v[212:215], v[14:17]
	v_mfma_f32_16x16x32_bf16 v[6:9], v[154:157], v[208:211], v[6:9]
	v_mfma_f32_16x16x32_bf16 v[6:9], v[170:173], v[212:215], v[6:9]
	s_setprio 0
	s_barrier
	s_add_i32 s64, 0, 0x18000
	s_add_i32 s75, 0, 0x1c000
	v_add_u32_e32 v142, s64, v194
	v_add_u32_e32 v170, s75, v194
	ds_read_b128 v[130:133], v142
	ds_read_b128 v[134:137], v142 offset:1024
	ds_read_b128 v[138:141], v142 offset:2048
	ds_read_b128 v[142:145], v142 offset:3072
	ds_read_b128 v[146:149], v170
	ds_read_b128 v[150:153], v170 offset:1024
	ds_read_b128 v[154:157], v170 offset:2048
	ds_read_b128 v[170:173], v170 offset:3072
	s_add_u32 s26, s26, 0x80000
	s_addc_u32 s27, s27, 0
	s_mov_b32 m0, s37
	v_lshl_add_u64 v[222:223], s[26:27], 0, v[158:159]
	ds_read_b128 v[174:177], v199 offset:32768
	ds_read_b128 v[178:181], v199 offset:33792
	ds_read_b128 v[182:185], v199 offset:34816
	ds_read_b128 v[186:189], v199 offset:35840
	ds_read_b128 v[190:193], v199 offset:36864
	ds_read_b128 v[200:203], v199 offset:37888
	ds_read_b128 v[208:211], v199 offset:38912
	ds_read_b128 v[212:215], v199 offset:39936
	global_load_lds_dwordx4 v[222:223], off
	v_lshl_add_u64 v[222:223], s[26:27], 0, v[162:163]
	s_mov_b32 m0, s38
	s_nop 0
	global_load_lds_dwordx4 v[222:223], off
	s_waitcnt vmcnt(8)
	s_waitcnt lgkmcnt(0)
	s_barrier
	s_setprio 1
	s_waitcnt lgkmcnt(0)
	v_mfma_f32_16x16x32_bf16 v[122:125], v[130:133], v[174:177], v[122:125]
	v_mfma_f32_16x16x32_bf16 v[122:125], v[134:137], v[178:181], v[122:125]
	v_mfma_f32_16x16x32_bf16 v[114:117], v[138:141], v[174:177], v[114:117]
	v_mfma_f32_16x16x32_bf16 v[114:117], v[142:145], v[178:181], v[114:117]
	v_mfma_f32_16x16x32_bf16 v[106:109], v[130:133], v[182:185], v[106:109]
	v_mfma_f32_16x16x32_bf16 v[106:109], v[134:137], v[186:189], v[106:109]
	v_mfma_f32_16x16x32_bf16 v[98:101], v[138:141], v[182:185], v[98:101]
	v_mfma_f32_16x16x32_bf16 v[98:101], v[142:145], v[186:189], v[98:101]
	v_mfma_f32_16x16x32_bf16 v[90:93], v[130:133], v[190:193], v[90:93]
	v_mfma_f32_16x16x32_bf16 v[90:93], v[134:137], v[200:203], v[90:93]
	v_mfma_f32_16x16x32_bf16 v[82:85], v[138:141], v[190:193], v[82:85]
	v_mfma_f32_16x16x32_bf16 v[82:85], v[142:145], v[200:203], v[82:85]
	v_mfma_f32_16x16x32_bf16 v[74:77], v[130:133], v[208:211], v[74:77]
	v_mfma_f32_16x16x32_bf16 v[74:77], v[134:137], v[212:215], v[74:77]
	v_mfma_f32_16x16x32_bf16 v[66:69], v[138:141], v[208:211], v[66:69]
	v_mfma_f32_16x16x32_bf16 v[66:69], v[142:145], v[212:215], v[66:69]
	s_setprio 0
	s_setprio 1
	v_mfma_f32_16x16x32_bf16 v[126:129], v[146:149], v[174:177], v[126:129]
	v_mfma_f32_16x16x32_bf16 v[126:129], v[150:153], v[178:181], v[126:129]
	v_mfma_f32_16x16x32_bf16 v[118:121], v[154:157], v[174:177], v[118:121]
	v_mfma_f32_16x16x32_bf16 v[118:121], v[170:173], v[178:181], v[118:121]
	v_mfma_f32_16x16x32_bf16 v[110:113], v[146:149], v[182:185], v[110:113]
	v_mfma_f32_16x16x32_bf16 v[110:113], v[150:153], v[186:189], v[110:113]
	v_mfma_f32_16x16x32_bf16 v[102:105], v[154:157], v[182:185], v[102:105]
	v_mfma_f32_16x16x32_bf16 v[102:105], v[170:173], v[186:189], v[102:105]
	v_mfma_f32_16x16x32_bf16 v[94:97], v[146:149], v[190:193], v[94:97]
	v_mfma_f32_16x16x32_bf16 v[94:97], v[150:153], v[200:203], v[94:97]
	v_mfma_f32_16x16x32_bf16 v[86:89], v[154:157], v[190:193], v[86:89]
	v_mfma_f32_16x16x32_bf16 v[86:89], v[170:173], v[200:203], v[86:89]
	v_mfma_f32_16x16x32_bf16 v[78:81], v[146:149], v[208:211], v[78:81]
	v_mfma_f32_16x16x32_bf16 v[78:81], v[150:153], v[212:215], v[78:81]
	v_mfma_f32_16x16x32_bf16 v[70:73], v[154:157], v[208:211], v[70:73]
	v_mfma_f32_16x16x32_bf16 v[70:73], v[170:173], v[212:215], v[70:73]
	s_setprio 0
	s_barrier
	s_add_i32 s26, s64, s35
	v_lshl_add_u64 v[204:205], v[204:205], 0, s[68:69]
	s_mov_b32 m0, s26
	ds_read_b128 v[174:177], v199 offset:49152
	ds_read_b128 v[178:181], v199 offset:50176
	ds_read_b128 v[182:185], v199 offset:51200
	ds_read_b128 v[186:189], v199 offset:52224
	ds_read_b128 v[190:193], v199 offset:53248
	ds_read_b128 v[200:203], v199 offset:54272
	ds_read_b128 v[208:211], v199 offset:55296
	ds_read_b128 v[212:215], v199 offset:56320
	global_load_lds_dwordx4 v[204:205], off
	s_add_i32 m0, s26, 0x2000
	s_add_u32 s2, s2, 0x80080
	v_lshl_add_u64 v[204:205], v[216:217], 0, s[68:69]
	s_addc_u32 s3, s3, 0
	s_add_i32 s26, s75, s35
	global_load_lds_dwordx4 v[204:205], off
	v_lshl_add_u64 v[204:205], s[2:3], 0, v[160:161]
	s_mov_b32 m0, s26
	s_nop 0
	global_load_lds_dwordx4 v[204:205], off
	v_lshl_add_u64 v[204:205], s[2:3], 0, v[164:165]
	s_add_i32 m0, s26, 0x2000
	s_nop 0
	global_load_lds_dwordx4 v[204:205], off
	v_lshl_add_u64 v[204:205], v[218:219], 0, s[68:69]
	s_mov_b32 m0, s40
	s_nop 0
	global_load_lds_dwordx4 v[204:205], off
	v_lshl_add_u64 v[204:205], v[220:221], 0, s[68:69]
	s_mov_b32 m0, s41
	s_nop 0
	global_load_lds_dwordx4 v[204:205], off
	s_waitcnt vmcnt(8)
	s_waitcnt lgkmcnt(0)
	s_barrier
	s_setprio 1
	s_waitcnt lgkmcnt(0)
	v_mfma_f32_16x16x32_bf16 v[58:61], v[130:133], v[174:177], v[58:61]
	v_mfma_f32_16x16x32_bf16 v[58:61], v[134:137], v[178:181], v[58:61]
	v_mfma_f32_16x16x32_bf16 v[50:53], v[138:141], v[174:177], v[50:53]
	v_mfma_f32_16x16x32_bf16 v[50:53], v[142:145], v[178:181], v[50:53]
	v_mfma_f32_16x16x32_bf16 v[42:45], v[130:133], v[182:185], v[42:45]
	v_mfma_f32_16x16x32_bf16 v[42:45], v[134:137], v[186:189], v[42:45]
	v_mfma_f32_16x16x32_bf16 v[34:37], v[138:141], v[182:185], v[34:37]
	v_mfma_f32_16x16x32_bf16 v[34:37], v[142:145], v[186:189], v[34:37]
	v_mfma_f32_16x16x32_bf16 v[26:29], v[130:133], v[190:193], v[26:29]
	v_mfma_f32_16x16x32_bf16 v[26:29], v[134:137], v[200:203], v[26:29]
	v_mfma_f32_16x16x32_bf16 v[18:21], v[138:141], v[190:193], v[18:21]
	v_mfma_f32_16x16x32_bf16 v[18:21], v[142:145], v[200:203], v[18:21]
	v_mfma_f32_16x16x32_bf16 v[10:13], v[130:133], v[208:211], v[10:13]
	v_mfma_f32_16x16x32_bf16 v[10:13], v[134:137], v[212:215], v[10:13]
	v_mfma_f32_16x16x32_bf16 v[2:5], v[138:141], v[208:211], v[2:5]
	v_mfma_f32_16x16x32_bf16 v[2:5], v[142:145], v[212:215], v[2:5]
	s_setprio 0
	s_setprio 1
	v_mfma_f32_16x16x32_bf16 v[62:65], v[146:149], v[174:177], v[62:65]
	v_mfma_f32_16x16x32_bf16 v[62:65], v[150:153], v[178:181], v[62:65]
	v_mfma_f32_16x16x32_bf16 v[54:57], v[154:157], v[174:177], v[54:57]
	v_mfma_f32_16x16x32_bf16 v[54:57], v[170:173], v[178:181], v[54:57]
	v_mfma_f32_16x16x32_bf16 v[46:49], v[146:149], v[182:185], v[46:49]
	v_mfma_f32_16x16x32_bf16 v[46:49], v[150:153], v[186:189], v[46:49]
	v_mfma_f32_16x16x32_bf16 v[38:41], v[154:157], v[182:185], v[38:41]
	v_mfma_f32_16x16x32_bf16 v[38:41], v[170:173], v[186:189], v[38:41]
	v_mfma_f32_16x16x32_bf16 v[30:33], v[146:149], v[190:193], v[30:33]
	v_mfma_f32_16x16x32_bf16 v[30:33], v[150:153], v[200:203], v[30:33]
	v_mfma_f32_16x16x32_bf16 v[22:25], v[154:157], v[190:193], v[22:25]
	v_mfma_f32_16x16x32_bf16 v[22:25], v[170:173], v[200:203], v[22:25]
	v_mfma_f32_16x16x32_bf16 v[14:17], v[146:149], v[208:211], v[14:17]
	v_mfma_f32_16x16x32_bf16 v[14:17], v[150:153], v[212:215], v[14:17]
	v_mfma_f32_16x16x32_bf16 v[6:9], v[154:157], v[208:211], v[6:9]
	v_mfma_f32_16x16x32_bf16 v[6:9], v[170:173], v[212:215], v[6:9]
	s_setprio 0
	s_barrier
	s_add_u32 s18, s18, 0x100
	s_addc_u32 s19, s19, 0
	s_add_u32 s51, s51, 0x100
	s_addc_u32 s52, s52, 0
	s_cmp_ge_i32 s53, s17
	s_mov_b32 s2, s53
	s_cbranch_scc0 .LBB0_634

.LBB0_798:
	s_lshl_b32 s0, s26, 21
	s_and_b32 s0, s0, 0x1fe00000
	v_readlane_b32 s22, v248, 22
	v_readlane_b32 s23, v248, 23
	s_add_u32 s0, s22, s0
	s_addc_u32 s23, s23, 0
	s_lshr_b32 s22, s26, 13
	s_and_b32 s24, s22, 0x7ff80
	s_add_u32 s22, s0, s24
	s_addc_u32 s23, s23, 0
	s_lshl_b32 s0, s26, 13
	s_and_b32 s0, s0, 0x1fe00000
	s_add_u32 s0, s82, s0
	s_addc_u32 s25, s83, 0
	s_add_u32 s24, s0, s24
	s_addc_u32 s25, s25, 0
	s_cmp_lt_i32 s35, 1
	v_cmp_gt_i64_e64 s[26:27], s[26:27], -1
	s_cbranch_scc1 .LBB0_820
	s_and_b64 s[38:39], s[26:27], exec
	s_cselect_b32 s0, s23, s37
	s_cselect_b32 s34, s22, s36
	s_cselect_b32 s56, s25, s3
	s_cselect_b32 s57, s24, s2
	s_add_i32 s58, s35, -2
	s_add_u32 s36, s36, 0x100080
	s_addc_u32 s37, s37, 0
	s_add_u32 s59, s2, 0x100
	s_addc_u32 s60, s3, 0
	s_mov_b32 s2, 0
	ds_read_b128 v[148:151], v144
	ds_read_b128 v[152:155], v144 offset:1024
	ds_read_b128 v[156:159], v144 offset:2048
	ds_read_b128 v[160:163], v144 offset:3072
	ds_read_b128 v[164:167], v145
	ds_read_b128 v[168:171], v145 offset:1024
	ds_read_b128 v[172:175], v145 offset:2048
	ds_read_b128 v[176:179], v145 offset:3072
	s_add_i32 s61, s2, 2
	s_add_u32 s3, s36, 0xfff00080
	s_addc_u32 s38, s37, -1
	s_cmp_eq_u32 s58, s2
	s_cselect_b32 s2, s57, s59
	s_cselect_b32 s39, s0, s38
	s_cselect_b32 s38, s34, s3
	s_cselect_b32 s3, s56, s60
	v_lshl_add_u64 v[204:205], s[36:37], 0, v[138:139]
	s_add_i32 m0, s29, 0xc000
	ds_read_b128 v[180:183], v146
	ds_read_b128 v[184:187], v146 offset:1024
	ds_read_b128 v[188:191], v146 offset:2048
	ds_read_b128 v[192:195], v146 offset:3072
	ds_read_b128 v[196:199], v146 offset:4096
	ds_read_b128 v[200:203], v146 offset:5120
	ds_read_b128 v[208:211], v146 offset:6144
	ds_read_b128 v[212:215], v146 offset:7168
	global_load_lds_dwordx4 v[204:205], off
	v_lshl_add_u64 v[204:205], s[36:37], 0, v[140:141]
	s_add_i32 m0, s29, 0xe000
	s_nop 0
	global_load_lds_dwordx4 v[204:205], off
	s_waitcnt vmcnt(8)
	s_waitcnt lgkmcnt(0)
	s_barrier
	s_setprio 1
	s_waitcnt lgkmcnt(0)
	v_mfma_f32_16x16x32_bf16 v[126:129], v[148:151], v[180:183], 0
	v_mfma_f32_16x16x32_bf16 v[126:129], v[152:155], v[184:187], v[126:129]
	v_mfma_f32_16x16x32_bf16 v[122:125], v[156:159], v[180:183], 0
	v_mfma_f32_16x16x32_bf16 v[122:125], v[160:163], v[184:187], v[122:125]
	v_mfma_f32_16x16x32_bf16 v[110:113], v[148:151], v[188:191], 0
	v_mfma_f32_16x16x32_bf16 v[110:113], v[152:155], v[192:195], v[110:113]
	v_mfma_f32_16x16x32_bf16 v[102:105], v[156:159], v[188:191], 0
	v_mfma_f32_16x16x32_bf16 v[102:105], v[160:163], v[192:195], v[102:105]
	v_mfma_f32_16x16x32_bf16 v[94:97], v[148:151], v[196:199], 0
	v_mfma_f32_16x16x32_bf16 v[94:97], v[152:155], v[200:203], v[94:97]
	v_mfma_f32_16x16x32_bf16 v[86:89], v[156:159], v[196:199], 0
	v_mfma_f32_16x16x32_bf16 v[86:89], v[160:163], v[200:203], v[86:89]
	v_mfma_f32_16x16x32_bf16 v[78:81], v[148:151], v[208:211], 0
	v_mfma_f32_16x16x32_bf16 v[78:81], v[152:155], v[212:215], v[78:81]
	v_mfma_f32_16x16x32_bf16 v[70:73], v[156:159], v[208:211], 0
	v_mfma_f32_16x16x32_bf16 v[70:73], v[160:163], v[212:215], v[70:73]
	s_setprio 0
	s_setprio 1
	v_mfma_f32_16x16x32_bf16 v[118:121], v[164:167], v[180:183], 0
	v_mfma_f32_16x16x32_bf16 v[118:121], v[168:171], v[184:187], v[118:121]
	v_mfma_f32_16x16x32_bf16 v[114:117], v[172:175], v[180:183], 0
	v_mfma_f32_16x16x32_bf16 v[114:117], v[176:179], v[184:187], v[114:117]
	v_mfma_f32_16x16x32_bf16 v[106:109], v[164:167], v[188:191], 0
	v_mfma_f32_16x16x32_bf16 v[106:109], v[168:171], v[192:195], v[106:109]
	v_mfma_f32_16x16x32_bf16 v[98:101], v[172:175], v[188:191], 0
	v_mfma_f32_16x16x32_bf16 v[98:101], v[176:179], v[192:195], v[98:101]
	v_mfma_f32_16x16x32_bf16 v[90:93], v[164:167], v[196:199], 0
	v_mfma_f32_16x16x32_bf16 v[90:93], v[168:171], v[200:203], v[90:93]
	v_mfma_f32_16x16x32_bf16 v[82:85], v[172:175], v[196:199], 0
	v_mfma_f32_16x16x32_bf16 v[82:85], v[176:179], v[200:203], v[82:85]
	v_mfma_f32_16x16x32_bf16 v[74:77], v[164:167], v[208:211], 0
	v_mfma_f32_16x16x32_bf16 v[74:77], v[168:171], v[212:215], v[74:77]
	v_mfma_f32_16x16x32_bf16 v[66:69], v[172:175], v[208:211], 0
	v_mfma_f32_16x16x32_bf16 v[66:69], v[176:179], v[212:215], v[66:69]
	s_setprio 0
	s_barrier
	s_add_i32 s64, s50, s33
	v_lshl_add_u64 v[204:205], s[2:3], 0, v[132:133]
	s_mov_b32 m0, s64
	ds_read_b128 v[180:183], v146 offset:16384
	ds_read_b128 v[184:187], v146 offset:17408
	ds_read_b128 v[188:191], v146 offset:18432
	ds_read_b128 v[192:195], v146 offset:19456
	ds_read_b128 v[196:199], v146 offset:20480
	ds_read_b128 v[200:203], v146 offset:21504
	ds_read_b128 v[208:211], v146 offset:22528
	ds_read_b128 v[212:215], v146 offset:23552
	global_load_lds_dwordx4 v[204:205], off
	s_add_i32 m0, s64, 0x2000
	s_add_u32 s64, s2, 0x100000
	v_lshl_add_u64 v[216:217], s[2:3], 0, v[136:137]
	s_addc_u32 s65, s3, 0
	s_add_i32 s66, s51, s33
	global_load_lds_dwordx4 v[216:217], off
	v_lshl_add_u64 v[218:219], s[64:65], 0, v[132:133]
	s_mov_b32 m0, s66
	v_lshl_add_u64 v[220:221], s[38:39], 0, v[134:135]
	global_load_lds_dwordx4 v[218:219], off
	v_lshl_add_u64 v[218:219], s[64:65], 0, v[136:137]
	s_add_i32 m0, s66, 0x2000
	s_nop 0
	global_load_lds_dwordx4 v[218:219], off
	v_lshl_add_u64 v[218:219], s[38:39], 0, v[130:131]
	s_mov_b32 m0, s29
	s_nop 0
	global_load_lds_dwordx4 v[218:219], off
	s_mov_b32 m0, s31
	s_nop 0
	global_load_lds_dwordx4 v[220:221], off
	s_waitcnt vmcnt(8)
	s_waitcnt lgkmcnt(0)
	s_barrier
	s_setprio 1
	s_waitcnt lgkmcnt(0)
	v_mfma_f32_16x16x32_bf16 v[62:65], v[148:151], v[180:183], 0
	v_mfma_f32_16x16x32_bf16 v[62:65], v[152:155], v[184:187], v[62:65]
	v_mfma_f32_16x16x32_bf16 v[54:57], v[156:159], v[180:183], 0
	v_mfma_f32_16x16x32_bf16 v[54:57], v[160:163], v[184:187], v[54:57]
	v_mfma_f32_16x16x32_bf16 v[46:49], v[148:151], v[188:191], 0
	v_mfma_f32_16x16x32_bf16 v[46:49], v[152:155], v[192:195], v[46:49]
	v_mfma_f32_16x16x32_bf16 v[38:41], v[156:159], v[188:191], 0
	v_mfma_f32_16x16x32_bf16 v[38:41], v[160:163], v[192:195], v[38:41]
	v_mfma_f32_16x16x32_bf16 v[30:33], v[148:151], v[196:199], 0
	v_mfma_f32_16x16x32_bf16 v[30:33], v[152:155], v[200:203], v[30:33]
	v_mfma_f32_16x16x32_bf16 v[22:25], v[156:159], v[196:199], 0
	v_mfma_f32_16x16x32_bf16 v[22:25], v[160:163], v[200:203], v[22:25]
	v_mfma_f32_16x16x32_bf16 v[14:17], v[148:151], v[208:211], 0
	v_mfma_f32_16x16x32_bf16 v[14:17], v[152:155], v[212:215], v[14:17]
	v_mfma_f32_16x16x32_bf16 v[6:9], v[156:159], v[208:211], 0
	v_mfma_f32_16x16x32_bf16 v[6:9], v[160:163], v[212:215], v[6:9]
	s_setprio 0
	s_setprio 1
	v_mfma_f32_16x16x32_bf16 v[58:61], v[164:167], v[180:183], 0
	v_mfma_f32_16x16x32_bf16 v[58:61], v[168:171], v[184:187], v[58:61]
	v_mfma_f32_16x16x32_bf16 v[50:53], v[172:175], v[180:183], 0
	v_mfma_f32_16x16x32_bf16 v[50:53], v[176:179], v[184:187], v[50:53]
	v_mfma_f32_16x16x32_bf16 v[42:45], v[164:167], v[188:191], 0
	v_mfma_f32_16x16x32_bf16 v[42:45], v[168:171], v[192:195], v[42:45]
	v_mfma_f32_16x16x32_bf16 v[34:37], v[172:175], v[188:191], 0
	v_mfma_f32_16x16x32_bf16 v[34:37], v[176:179], v[192:195], v[34:37]
	v_mfma_f32_16x16x32_bf16 v[26:29], v[164:167], v[196:199], 0
	v_mfma_f32_16x16x32_bf16 v[26:29], v[168:171], v[200:203], v[26:29]
	v_mfma_f32_16x16x32_bf16 v[18:21], v[172:175], v[196:199], 0
	v_mfma_f32_16x16x32_bf16 v[18:21], v[176:179], v[200:203], v[18:21]
	v_mfma_f32_16x16x32_bf16 v[10:13], v[164:167], v[208:211], 0
	v_mfma_f32_16x16x32_bf16 v[10:13], v[168:171], v[212:215], v[10:13]
	v_mfma_f32_16x16x32_bf16 v[2:5], v[172:175], v[208:211], 0
	v_mfma_f32_16x16x32_bf16 v[2:5], v[176:179], v[212:215], v[2:5]
	s_setprio 0
	s_barrier
	s_add_i32 s64, 0, 0x18000
	v_add_u32_e32 v147, s64, v142
	s_add_i32 s65, 0, 0x1c000
	ds_read_b128 v[148:151], v147
	ds_read_b128 v[152:155], v147 offset:1024
	ds_read_b128 v[156:159], v147 offset:2048
	ds_read_b128 v[160:163], v147 offset:3072
	v_add_u32_e32 v147, s65, v142
	ds_read_b128 v[164:167], v147
	ds_read_b128 v[168:171], v147 offset:1024
	ds_read_b128 v[172:175], v147 offset:2048
	ds_read_b128 v[176:179], v147 offset:3072
	s_add_u32 s38, s38, 0x100000
	s_addc_u32 s39, s39, 0
	s_mov_b32 m0, s41
	v_lshl_add_u64 v[222:223], s[38:39], 0, v[130:131]
	ds_read_b128 v[180:183], v146 offset:32768
	ds_read_b128 v[184:187], v146 offset:33792
	ds_read_b128 v[188:191], v146 offset:34816
	ds_read_b128 v[192:195], v146 offset:35840
	ds_read_b128 v[196:199], v146 offset:36864
	ds_read_b128 v[200:203], v146 offset:37888
	ds_read_b128 v[208:211], v146 offset:38912
	ds_read_b128 v[212:215], v146 offset:39936
	global_load_lds_dwordx4 v[222:223], off
	v_lshl_add_u64 v[222:223], s[38:39], 0, v[134:135]
	s_mov_b32 m0, s42
	s_nop 0
	global_load_lds_dwordx4 v[222:223], off
	s_waitcnt vmcnt(8)
	s_waitcnt lgkmcnt(0)
	s_barrier
	s_setprio 1
	s_waitcnt lgkmcnt(0)
	v_mfma_f32_16x16x32_bf16 v[126:129], v[148:151], v[180:183], v[126:129]
	v_mfma_f32_16x16x32_bf16 v[126:129], v[152:155], v[184:187], v[126:129]
	v_mfma_f32_16x16x32_bf16 v[122:125], v[156:159], v[180:183], v[122:125]
	v_mfma_f32_16x16x32_bf16 v[122:125], v[160:163], v[184:187], v[122:125]
	v_mfma_f32_16x16x32_bf16 v[110:113], v[148:151], v[188:191], v[110:113]
	v_mfma_f32_16x16x32_bf16 v[110:113], v[152:155], v[192:195], v[110:113]
	v_mfma_f32_16x16x32_bf16 v[102:105], v[156:159], v[188:191], v[102:105]
	v_mfma_f32_16x16x32_bf16 v[102:105], v[160:163], v[192:195], v[102:105]
	v_mfma_f32_16x16x32_bf16 v[94:97], v[148:151], v[196:199], v[94:97]
	v_mfma_f32_16x16x32_bf16 v[94:97], v[152:155], v[200:203], v[94:97]
	v_mfma_f32_16x16x32_bf16 v[86:89], v[156:159], v[196:199], v[86:89]
	v_mfma_f32_16x16x32_bf16 v[86:89], v[160:163], v[200:203], v[86:89]
	v_mfma_f32_16x16x32_bf16 v[78:81], v[148:151], v[208:211], v[78:81]
	v_mfma_f32_16x16x32_bf16 v[78:81], v[152:155], v[212:215], v[78:81]
	v_mfma_f32_16x16x32_bf16 v[70:73], v[156:159], v[208:211], v[70:73]
	v_mfma_f32_16x16x32_bf16 v[70:73], v[160:163], v[212:215], v[70:73]
	s_setprio 0
	s_setprio 1
	v_mfma_f32_16x16x32_bf16 v[118:121], v[164:167], v[180:183], v[118:121]
	v_mfma_f32_16x16x32_bf16 v[118:121], v[168:171], v[184:187], v[118:121]
	v_mfma_f32_16x16x32_bf16 v[114:117], v[172:175], v[180:183], v[114:117]
	v_mfma_f32_16x16x32_bf16 v[114:117], v[176:179], v[184:187], v[114:117]
	v_mfma_f32_16x16x32_bf16 v[106:109], v[164:167], v[188:191], v[106:109]
	v_mfma_f32_16x16x32_bf16 v[106:109], v[168:171], v[192:195], v[106:109]
	v_mfma_f32_16x16x32_bf16 v[98:101], v[172:175], v[188:191], v[98:101]
	v_mfma_f32_16x16x32_bf16 v[98:101], v[176:179], v[192:195], v[98:101]
	v_mfma_f32_16x16x32_bf16 v[90:93], v[164:167], v[196:199], v[90:93]
	v_mfma_f32_16x16x32_bf16 v[90:93], v[168:171], v[200:203], v[90:93]
	v_mfma_f32_16x16x32_bf16 v[82:85], v[172:175], v[196:199], v[82:85]
	v_mfma_f32_16x16x32_bf16 v[82:85], v[176:179], v[200:203], v[82:85]
	v_mfma_f32_16x16x32_bf16 v[74:77], v[164:167], v[208:211], v[74:77]
	v_mfma_f32_16x16x32_bf16 v[74:77], v[168:171], v[212:215], v[74:77]
	v_mfma_f32_16x16x32_bf16 v[66:69], v[172:175], v[208:211], v[66:69]
	v_mfma_f32_16x16x32_bf16 v[66:69], v[176:179], v[212:215], v[66:69]
	s_setprio 0
	s_barrier
	s_add_i32 s38, s64, s33
	v_lshl_add_u64 v[204:205], v[204:205], 0, s[16:17]
	s_mov_b32 m0, s38
	ds_read_b128 v[180:183], v146 offset:49152
	ds_read_b128 v[184:187], v146 offset:50176
	ds_read_b128 v[188:191], v146 offset:51200
	ds_read_b128 v[192:195], v146 offset:52224
	ds_read_b128 v[196:199], v146 offset:53248
	ds_read_b128 v[200:203], v146 offset:54272
	ds_read_b128 v[208:211], v146 offset:55296
	ds_read_b128 v[212:215], v146 offset:56320
	global_load_lds_dwordx4 v[204:205], off
	s_add_i32 m0, s38, 0x2000
	s_add_u32 s2, s2, 0x100080
	v_lshl_add_u64 v[204:205], v[216:217], 0, s[16:17]
	s_addc_u32 s3, s3, 0
	s_add_i32 s38, s65, s33
	global_load_lds_dwordx4 v[204:205], off
	v_lshl_add_u64 v[204:205], s[2:3], 0, v[132:133]
	s_mov_b32 m0, s38
	s_nop 0
	global_load_lds_dwordx4 v[204:205], off
	v_lshl_add_u64 v[204:205], s[2:3], 0, v[136:137]
	s_add_i32 m0, s38, 0x2000
	s_nop 0
	global_load_lds_dwordx4 v[204:205], off
	v_lshl_add_u64 v[204:205], v[218:219], 0, s[16:17]
	s_mov_b32 m0, s44
	s_nop 0
	global_load_lds_dwordx4 v[204:205], off
	v_lshl_add_u64 v[204:205], v[220:221], 0, s[16:17]
	s_mov_b32 m0, s45
	s_nop 0
	global_load_lds_dwordx4 v[204:205], off
	s_waitcnt vmcnt(8)
	s_waitcnt lgkmcnt(0)
	s_barrier
	s_setprio 1
	s_waitcnt lgkmcnt(0)
	v_mfma_f32_16x16x32_bf16 v[62:65], v[148:151], v[180:183], v[62:65]
	v_mfma_f32_16x16x32_bf16 v[62:65], v[152:155], v[184:187], v[62:65]
	v_mfma_f32_16x16x32_bf16 v[54:57], v[156:159], v[180:183], v[54:57]
	v_mfma_f32_16x16x32_bf16 v[54:57], v[160:163], v[184:187], v[54:57]
	v_mfma_f32_16x16x32_bf16 v[46:49], v[148:151], v[188:191], v[46:49]
	v_mfma_f32_16x16x32_bf16 v[46:49], v[152:155], v[192:195], v[46:49]
	v_mfma_f32_16x16x32_bf16 v[38:41], v[156:159], v[188:191], v[38:41]
	v_mfma_f32_16x16x32_bf16 v[38:41], v[160:163], v[192:195], v[38:41]
	v_mfma_f32_16x16x32_bf16 v[30:33], v[148:151], v[196:199], v[30:33]
	v_mfma_f32_16x16x32_bf16 v[30:33], v[152:155], v[200:203], v[30:33]
	v_mfma_f32_16x16x32_bf16 v[22:25], v[156:159], v[196:199], v[22:25]
	v_mfma_f32_16x16x32_bf16 v[22:25], v[160:163], v[200:203], v[22:25]
	v_mfma_f32_16x16x32_bf16 v[14:17], v[148:151], v[208:211], v[14:17]
	v_mfma_f32_16x16x32_bf16 v[14:17], v[152:155], v[212:215], v[14:17]
	v_mfma_f32_16x16x32_bf16 v[6:9], v[156:159], v[208:211], v[6:9]
	v_mfma_f32_16x16x32_bf16 v[6:9], v[160:163], v[212:215], v[6:9]
	s_setprio 0
	s_setprio 1
	v_mfma_f32_16x16x32_bf16 v[58:61], v[164:167], v[180:183], v[58:61]
	v_mfma_f32_16x16x32_bf16 v[58:61], v[168:171], v[184:187], v[58:61]
	v_mfma_f32_16x16x32_bf16 v[50:53], v[172:175], v[180:183], v[50:53]
	v_mfma_f32_16x16x32_bf16 v[50:53], v[176:179], v[184:187], v[50:53]
	v_mfma_f32_16x16x32_bf16 v[42:45], v[164:167], v[188:191], v[42:45]
	v_mfma_f32_16x16x32_bf16 v[42:45], v[168:171], v[192:195], v[42:45]
	v_mfma_f32_16x16x32_bf16 v[34:37], v[172:175], v[188:191], v[34:37]
	v_mfma_f32_16x16x32_bf16 v[34:37], v[176:179], v[192:195], v[34:37]
	v_mfma_f32_16x16x32_bf16 v[26:29], v[164:167], v[196:199], v[26:29]
	v_mfma_f32_16x16x32_bf16 v[26:29], v[168:171], v[200:203], v[26:29]
	v_mfma_f32_16x16x32_bf16 v[18:21], v[172:175], v[196:199], v[18:21]
	v_mfma_f32_16x16x32_bf16 v[18:21], v[176:179], v[200:203], v[18:21]
	v_mfma_f32_16x16x32_bf16 v[10:13], v[164:167], v[208:211], v[10:13]
	v_mfma_f32_16x16x32_bf16 v[10:13], v[168:171], v[212:215], v[10:13]
	v_mfma_f32_16x16x32_bf16 v[2:5], v[172:175], v[208:211], v[2:5]
	v_mfma_f32_16x16x32_bf16 v[2:5], v[176:179], v[212:215], v[2:5]
	s_setprio 0
	s_barrier
	s_add_u32 s36, s36, 0x100
	s_addc_u32 s37, s37, 0
	s_add_u32 s59, s59, 0x100
	s_addc_u32 s60, s60, 0
	s_cmp_ge_i32 s61, s35
	s_mov_b32 s2, s61
	s_cbranch_scc1 .Lkpeel_exit_4
.LBB0_800:
	ds_read_b128 v[148:151], v144
	ds_read_b128 v[152:155], v144 offset:1024
	ds_read_b128 v[156:159], v144 offset:2048
	ds_read_b128 v[160:163], v144 offset:3072
	ds_read_b128 v[164:167], v145
	ds_read_b128 v[168:171], v145 offset:1024
	ds_read_b128 v[172:175], v145 offset:2048
	ds_read_b128 v[176:179], v145 offset:3072
	s_add_i32 s61, s2, 2
	s_add_u32 s3, s36, 0xfff00080
	s_addc_u32 s38, s37, -1
	s_cmp_eq_u32 s58, s2
	s_cselect_b32 s2, s57, s59
	s_cselect_b32 s39, s0, s38
	s_cselect_b32 s38, s34, s3
	s_cselect_b32 s3, s56, s60
	v_lshl_add_u64 v[204:205], s[36:37], 0, v[138:139]
	s_add_i32 m0, s29, 0xc000
	ds_read_b128 v[180:183], v146
	ds_read_b128 v[184:187], v146 offset:1024
	ds_read_b128 v[188:191], v146 offset:2048
	ds_read_b128 v[192:195], v146 offset:3072
	ds_read_b128 v[196:199], v146 offset:4096
	ds_read_b128 v[200:203], v146 offset:5120
	ds_read_b128 v[208:211], v146 offset:6144
	ds_read_b128 v[212:215], v146 offset:7168
	global_load_lds_dwordx4 v[204:205], off
	v_lshl_add_u64 v[204:205], s[36:37], 0, v[140:141]
	s_add_i32 m0, s29, 0xe000
	s_nop 0
	global_load_lds_dwordx4 v[204:205], off
	s_waitcnt vmcnt(8)
	s_waitcnt lgkmcnt(0)
	s_barrier
	s_setprio 1
	s_waitcnt lgkmcnt(0)
	v_mfma_f32_16x16x32_bf16 v[126:129], v[148:151], v[180:183], v[126:129]
	v_mfma_f32_16x16x32_bf16 v[126:129], v[152:155], v[184:187], v[126:129]
	v_mfma_f32_16x16x32_bf16 v[122:125], v[156:159], v[180:183], v[122:125]
	v_mfma_f32_16x16x32_bf16 v[122:125], v[160:163], v[184:187], v[122:125]
	v_mfma_f32_16x16x32_bf16 v[110:113], v[148:151], v[188:191], v[110:113]
	v_mfma_f32_16x16x32_bf16 v[110:113], v[152:155], v[192:195], v[110:113]
	v_mfma_f32_16x16x32_bf16 v[102:105], v[156:159], v[188:191], v[102:105]
	v_mfma_f32_16x16x32_bf16 v[102:105], v[160:163], v[192:195], v[102:105]
	v_mfma_f32_16x16x32_bf16 v[94:97], v[148:151], v[196:199], v[94:97]
	v_mfma_f32_16x16x32_bf16 v[94:97], v[152:155], v[200:203], v[94:97]
	v_mfma_f32_16x16x32_bf16 v[86:89], v[156:159], v[196:199], v[86:89]
	v_mfma_f32_16x16x32_bf16 v[86:89], v[160:163], v[200:203], v[86:89]
	v_mfma_f32_16x16x32_bf16 v[78:81], v[148:151], v[208:211], v[78:81]
	v_mfma_f32_16x16x32_bf16 v[78:81], v[152:155], v[212:215], v[78:81]
	v_mfma_f32_16x16x32_bf16 v[70:73], v[156:159], v[208:211], v[70:73]
	v_mfma_f32_16x16x32_bf16 v[70:73], v[160:163], v[212:215], v[70:73]
	s_setprio 0
	s_setprio 1
	v_mfma_f32_16x16x32_bf16 v[118:121], v[164:167], v[180:183], v[118:121]
	v_mfma_f32_16x16x32_bf16 v[118:121], v[168:171], v[184:187], v[118:121]
	v_mfma_f32_16x16x32_bf16 v[114:117], v[172:175], v[180:183], v[114:117]
	v_mfma_f32_16x16x32_bf16 v[114:117], v[176:179], v[184:187], v[114:117]
	v_mfma_f32_16x16x32_bf16 v[106:109], v[164:167], v[188:191], v[106:109]
	v_mfma_f32_16x16x32_bf16 v[106:109], v[168:171], v[192:195], v[106:109]
	v_mfma_f32_16x16x32_bf16 v[98:101], v[172:175], v[188:191], v[98:101]
	v_mfma_f32_16x16x32_bf16 v[98:101], v[176:179], v[192:195], v[98:101]
	v_mfma_f32_16x16x32_bf16 v[90:93], v[164:167], v[196:199], v[90:93]
	v_mfma_f32_16x16x32_bf16 v[90:93], v[168:171], v[200:203], v[90:93]
	v_mfma_f32_16x16x32_bf16 v[82:85], v[172:175], v[196:199], v[82:85]
	v_mfma_f32_16x16x32_bf16 v[82:85], v[176:179], v[200:203], v[82:85]
	v_mfma_f32_16x16x32_bf16 v[74:77], v[164:167], v[208:211], v[74:77]
	v_mfma_f32_16x16x32_bf16 v[74:77], v[168:171], v[212:215], v[74:77]
	v_mfma_f32_16x16x32_bf16 v[66:69], v[172:175], v[208:211], v[66:69]
	v_mfma_f32_16x16x32_bf16 v[66:69], v[176:179], v[212:215], v[66:69]
	s_setprio 0
	s_barrier
	s_add_i32 s64, s50, s33
	v_lshl_add_u64 v[204:205], s[2:3], 0, v[132:133]
	s_mov_b32 m0, s64
	ds_read_b128 v[180:183], v146 offset:16384
	ds_read_b128 v[184:187], v146 offset:17408
	ds_read_b128 v[188:191], v146 offset:18432
	ds_read_b128 v[192:195], v146 offset:19456
	ds_read_b128 v[196:199], v146 offset:20480
	ds_read_b128 v[200:203], v146 offset:21504
	ds_read_b128 v[208:211], v146 offset:22528
	ds_read_b128 v[212:215], v146 offset:23552
	global_load_lds_dwordx4 v[204:205], off
	s_add_i32 m0, s64, 0x2000
	s_add_u32 s64, s2, 0x100000
	v_lshl_add_u64 v[216:217], s[2:3], 0, v[136:137]
	s_addc_u32 s65, s3, 0
	s_add_i32 s66, s51, s33
	global_load_lds_dwordx4 v[216:217], off
	v_lshl_add_u64 v[218:219], s[64:65], 0, v[132:133]
	s_mov_b32 m0, s66
	v_lshl_add_u64 v[220:221], s[38:39], 0, v[134:135]
	global_load_lds_dwordx4 v[218:219], off
	v_lshl_add_u64 v[218:219], s[64:65], 0, v[136:137]
	s_add_i32 m0, s66, 0x2000
	s_nop 0
	global_load_lds_dwordx4 v[218:219], off
	v_lshl_add_u64 v[218:219], s[38:39], 0, v[130:131]
	s_mov_b32 m0, s29
	s_nop 0
	global_load_lds_dwordx4 v[218:219], off
	s_mov_b32 m0, s31
	s_nop 0
	global_load_lds_dwordx4 v[220:221], off
	s_waitcnt vmcnt(8)
	s_waitcnt lgkmcnt(0)
	s_barrier
	s_setprio 1
	s_waitcnt lgkmcnt(0)
	v_mfma_f32_16x16x32_bf16 v[62:65], v[148:151], v[180:183], v[62:65]
	v_mfma_f32_16x16x32_bf16 v[62:65], v[152:155], v[184:187], v[62:65]
	v_mfma_f32_16x16x32_bf16 v[54:57], v[156:159], v[180:183], v[54:57]
	v_mfma_f32_16x16x32_bf16 v[54:57], v[160:163], v[184:187], v[54:57]
	v_mfma_f32_16x16x32_bf16 v[46:49], v[148:151], v[188:191], v[46:49]
	v_mfma_f32_16x16x32_bf16 v[46:49], v[152:155], v[192:195], v[46:49]
	v_mfma_f32_16x16x32_bf16 v[38:41], v[156:159], v[188:191], v[38:41]
	v_mfma_f32_16x16x32_bf16 v[38:41], v[160:163], v[192:195], v[38:41]
	v_mfma_f32_16x16x32_bf16 v[30:33], v[148:151], v[196:199], v[30:33]
	v_mfma_f32_16x16x32_bf16 v[30:33], v[152:155], v[200:203], v[30:33]
	v_mfma_f32_16x16x32_bf16 v[22:25], v[156:159], v[196:199], v[22:25]
	v_mfma_f32_16x16x32_bf16 v[22:25], v[160:163], v[200:203], v[22:25]
	v_mfma_f32_16x16x32_bf16 v[14:17], v[148:151], v[208:211], v[14:17]
	v_mfma_f32_16x16x32_bf16 v[14:17], v[152:155], v[212:215], v[14:17]
	v_mfma_f32_16x16x32_bf16 v[6:9], v[156:159], v[208:211], v[6:9]
	v_mfma_f32_16x16x32_bf16 v[6:9], v[160:163], v[212:215], v[6:9]
	s_setprio 0
	s_setprio 1
	v_mfma_f32_16x16x32_bf16 v[58:61], v[164:167], v[180:183], v[58:61]
	v_mfma_f32_16x16x32_bf16 v[58:61], v[168:171], v[184:187], v[58:61]
	v_mfma_f32_16x16x32_bf16 v[50:53], v[172:175], v[180:183], v[50:53]
	v_mfma_f32_16x16x32_bf16 v[50:53], v[176:179], v[184:187], v[50:53]
	v_mfma_f32_16x16x32_bf16 v[42:45], v[164:167], v[188:191], v[42:45]
	v_mfma_f32_16x16x32_bf16 v[42:45], v[168:171], v[192:195], v[42:45]
	v_mfma_f32_16x16x32_bf16 v[34:37], v[172:175], v[188:191], v[34:37]
	v_mfma_f32_16x16x32_bf16 v[34:37], v[176:179], v[192:195], v[34:37]
	v_mfma_f32_16x16x32_bf16 v[26:29], v[164:167], v[196:199], v[26:29]
	v_mfma_f32_16x16x32_bf16 v[26:29], v[168:171], v[200:203], v[26:29]
	v_mfma_f32_16x16x32_bf16 v[18:21], v[172:175], v[196:199], v[18:21]
	v_mfma_f32_16x16x32_bf16 v[18:21], v[176:179], v[200:203], v[18:21]
	v_mfma_f32_16x16x32_bf16 v[10:13], v[164:167], v[208:211], v[10:13]
	v_mfma_f32_16x16x32_bf16 v[10:13], v[168:171], v[212:215], v[10:13]
	v_mfma_f32_16x16x32_bf16 v[2:5], v[172:175], v[208:211], v[2:5]
	v_mfma_f32_16x16x32_bf16 v[2:5], v[176:179], v[212:215], v[2:5]
	s_setprio 0
	s_barrier
	s_add_i32 s64, 0, 0x18000
	v_add_u32_e32 v147, s64, v142
	s_add_i32 s65, 0, 0x1c000
	ds_read_b128 v[148:151], v147
	ds_read_b128 v[152:155], v147 offset:1024
	ds_read_b128 v[156:159], v147 offset:2048
	ds_read_b128 v[160:163], v147 offset:3072
	v_add_u32_e32 v147, s65, v142
	ds_read_b128 v[164:167], v147
	ds_read_b128 v[168:171], v147 offset:1024
	ds_read_b128 v[172:175], v147 offset:2048
	ds_read_b128 v[176:179], v147 offset:3072
	s_add_u32 s38, s38, 0x100000
	s_addc_u32 s39, s39, 0
	s_mov_b32 m0, s41
	v_lshl_add_u64 v[222:223], s[38:39], 0, v[130:131]
	ds_read_b128 v[180:183], v146 offset:32768
	ds_read_b128 v[184:187], v146 offset:33792
	ds_read_b128 v[188:191], v146 offset:34816
	ds_read_b128 v[192:195], v146 offset:35840
	ds_read_b128 v[196:199], v146 offset:36864
	ds_read_b128 v[200:203], v146 offset:37888
	ds_read_b128 v[208:211], v146 offset:38912
	ds_read_b128 v[212:215], v146 offset:39936
	global_load_lds_dwordx4 v[222:223], off
	v_lshl_add_u64 v[222:223], s[38:39], 0, v[134:135]
	s_mov_b32 m0, s42
	s_nop 0
	global_load_lds_dwordx4 v[222:223], off
	s_waitcnt vmcnt(8)
	s_waitcnt lgkmcnt(0)
	s_barrier
	s_setprio 1
	s_waitcnt lgkmcnt(0)
	v_mfma_f32_16x16x32_bf16 v[126:129], v[148:151], v[180:183], v[126:129]
	v_mfma_f32_16x16x32_bf16 v[126:129], v[152:155], v[184:187], v[126:129]
	v_mfma_f32_16x16x32_bf16 v[122:125], v[156:159], v[180:183], v[122:125]
	v_mfma_f32_16x16x32_bf16 v[122:125], v[160:163], v[184:187], v[122:125]
	v_mfma_f32_16x16x32_bf16 v[110:113], v[148:151], v[188:191], v[110:113]
	v_mfma_f32_16x16x32_bf16 v[110:113], v[152:155], v[192:195], v[110:113]
	v_mfma_f32_16x16x32_bf16 v[102:105], v[156:159], v[188:191], v[102:105]
	v_mfma_f32_16x16x32_bf16 v[102:105], v[160:163], v[192:195], v[102:105]
	v_mfma_f32_16x16x32_bf16 v[94:97], v[148:151], v[196:199], v[94:97]
	v_mfma_f32_16x16x32_bf16 v[94:97], v[152:155], v[200:203], v[94:97]
	v_mfma_f32_16x16x32_bf16 v[86:89], v[156:159], v[196:199], v[86:89]
	v_mfma_f32_16x16x32_bf16 v[86:89], v[160:163], v[200:203], v[86:89]
	v_mfma_f32_16x16x32_bf16 v[78:81], v[148:151], v[208:211], v[78:81]
	v_mfma_f32_16x16x32_bf16 v[78:81], v[152:155], v[212:215], v[78:81]
	v_mfma_f32_16x16x32_bf16 v[70:73], v[156:159], v[208:211], v[70:73]
	v_mfma_f32_16x16x32_bf16 v[70:73], v[160:163], v[212:215], v[70:73]
	s_setprio 0
	s_setprio 1
	v_mfma_f32_16x16x32_bf16 v[118:121], v[164:167], v[180:183], v[118:121]
	v_mfma_f32_16x16x32_bf16 v[118:121], v[168:171], v[184:187], v[118:121]
	v_mfma_f32_16x16x32_bf16 v[114:117], v[172:175], v[180:183], v[114:117]
	v_mfma_f32_16x16x32_bf16 v[114:117], v[176:179], v[184:187], v[114:117]
	v_mfma_f32_16x16x32_bf16 v[106:109], v[164:167], v[188:191], v[106:109]
	v_mfma_f32_16x16x32_bf16 v[106:109], v[168:171], v[192:195], v[106:109]
	v_mfma_f32_16x16x32_bf16 v[98:101], v[172:175], v[188:191], v[98:101]
	v_mfma_f32_16x16x32_bf16 v[98:101], v[176:179], v[192:195], v[98:101]
	v_mfma_f32_16x16x32_bf16 v[90:93], v[164:167], v[196:199], v[90:93]
	v_mfma_f32_16x16x32_bf16 v[90:93], v[168:171], v[200:203], v[90:93]
	v_mfma_f32_16x16x32_bf16 v[82:85], v[172:175], v[196:199], v[82:85]
	v_mfma_f32_16x16x32_bf16 v[82:85], v[176:179], v[200:203], v[82:85]
	v_mfma_f32_16x16x32_bf16 v[74:77], v[164:167], v[208:211], v[74:77]
	v_mfma_f32_16x16x32_bf16 v[74:77], v[168:171], v[212:215], v[74:77]
	v_mfma_f32_16x16x32_bf16 v[66:69], v[172:175], v[208:211], v[66:69]
	v_mfma_f32_16x16x32_bf16 v[66:69], v[176:179], v[212:215], v[66:69]
	s_setprio 0
	s_barrier
	s_add_i32 s38, s64, s33
	v_lshl_add_u64 v[204:205], v[204:205], 0, s[16:17]
	s_mov_b32 m0, s38
	ds_read_b128 v[180:183], v146 offset:49152
	ds_read_b128 v[184:187], v146 offset:50176
	ds_read_b128 v[188:191], v146 offset:51200
	ds_read_b128 v[192:195], v146 offset:52224
	ds_read_b128 v[196:199], v146 offset:53248
	ds_read_b128 v[200:203], v146 offset:54272
	ds_read_b128 v[208:211], v146 offset:55296
	ds_read_b128 v[212:215], v146 offset:56320
	global_load_lds_dwordx4 v[204:205], off
	s_add_i32 m0, s38, 0x2000
	s_add_u32 s2, s2, 0x100080
	v_lshl_add_u64 v[204:205], v[216:217], 0, s[16:17]
	s_addc_u32 s3, s3, 0
	s_add_i32 s38, s65, s33
	global_load_lds_dwordx4 v[204:205], off
	v_lshl_add_u64 v[204:205], s[2:3], 0, v[132:133]
	s_mov_b32 m0, s38
	s_nop 0
	global_load_lds_dwordx4 v[204:205], off
	v_lshl_add_u64 v[204:205], s[2:3], 0, v[136:137]
	s_add_i32 m0, s38, 0x2000
	s_nop 0
	global_load_lds_dwordx4 v[204:205], off
	v_lshl_add_u64 v[204:205], v[218:219], 0, s[16:17]
	s_mov_b32 m0, s44
	s_nop 0
	global_load_lds_dwordx4 v[204:205], off
	v_lshl_add_u64 v[204:205], v[220:221], 0, s[16:17]
	s_mov_b32 m0, s45
	s_nop 0
	global_load_lds_dwordx4 v[204:205], off
	s_waitcnt vmcnt(8)
	s_waitcnt lgkmcnt(0)
	s_barrier
	s_setprio 1
	s_waitcnt lgkmcnt(0)
	v_mfma_f32_16x16x32_bf16 v[62:65], v[148:151], v[180:183], v[62:65]
	v_mfma_f32_16x16x32_bf16 v[62:65], v[152:155], v[184:187], v[62:65]
	v_mfma_f32_16x16x32_bf16 v[54:57], v[156:159], v[180:183], v[54:57]
	v_mfma_f32_16x16x32_bf16 v[54:57], v[160:163], v[184:187], v[54:57]
	v_mfma_f32_16x16x32_bf16 v[46:49], v[148:151], v[188:191], v[46:49]
	v_mfma_f32_16x16x32_bf16 v[46:49], v[152:155], v[192:195], v[46:49]
	v_mfma_f32_16x16x32_bf16 v[38:41], v[156:159], v[188:191], v[38:41]
	v_mfma_f32_16x16x32_bf16 v[38:41], v[160:163], v[192:195], v[38:41]
	v_mfma_f32_16x16x32_bf16 v[30:33], v[148:151], v[196:199], v[30:33]
	v_mfma_f32_16x16x32_bf16 v[30:33], v[152:155], v[200:203], v[30:33]
	v_mfma_f32_16x16x32_bf16 v[22:25], v[156:159], v[196:199], v[22:25]
	v_mfma_f32_16x16x32_bf16 v[22:25], v[160:163], v[200:203], v[22:25]
	v_mfma_f32_16x16x32_bf16 v[14:17], v[148:151], v[208:211], v[14:17]
	v_mfma_f32_16x16x32_bf16 v[14:17], v[152:155], v[212:215], v[14:17]
	v_mfma_f32_16x16x32_bf16 v[6:9], v[156:159], v[208:211], v[6:9]
	v_mfma_f32_16x16x32_bf16 v[6:9], v[160:163], v[212:215], v[6:9]
	s_setprio 0
	s_setprio 1
	v_mfma_f32_16x16x32_bf16 v[58:61], v[164:167], v[180:183], v[58:61]
	v_mfma_f32_16x16x32_bf16 v[58:61], v[168:171], v[184:187], v[58:61]
	v_mfma_f32_16x16x32_bf16 v[50:53], v[172:175], v[180:183], v[50:53]
	v_mfma_f32_16x16x32_bf16 v[50:53], v[176:179], v[184:187], v[50:53]
	v_mfma_f32_16x16x32_bf16 v[42:45], v[164:167], v[188:191], v[42:45]
	v_mfma_f32_16x16x32_bf16 v[42:45], v[168:171], v[192:195], v[42:45]
	v_mfma_f32_16x16x32_bf16 v[34:37], v[172:175], v[188:191], v[34:37]
	v_mfma_f32_16x16x32_bf16 v[34:37], v[176:179], v[192:195], v[34:37]
	v_mfma_f32_16x16x32_bf16 v[26:29], v[164:167], v[196:199], v[26:29]
	v_mfma_f32_16x16x32_bf16 v[26:29], v[168:171], v[200:203], v[26:29]
	v_mfma_f32_16x16x32_bf16 v[18:21], v[172:175], v[196:199], v[18:21]
	v_mfma_f32_16x16x32_bf16 v[18:21], v[176:179], v[200:203], v[18:21]
	v_mfma_f32_16x16x32_bf16 v[10:13], v[164:167], v[208:211], v[10:13]
	v_mfma_f32_16x16x32_bf16 v[10:13], v[168:171], v[212:215], v[10:13]
	v_mfma_f32_16x16x32_bf16 v[2:5], v[172:175], v[208:211], v[2:5]
	v_mfma_f32_16x16x32_bf16 v[2:5], v[176:179], v[212:215], v[2:5]
	s_setprio 0
	s_barrier
	s_add_u32 s36, s36, 0x100
	s_addc_u32 s37, s37, 0
	s_add_u32 s59, s59, 0x100
	s_addc_u32 s60, s60, 0
	s_cmp_ge_i32 s61, s35
	s_mov_b32 s2, s61
	s_cbranch_scc0 .LBB0_800

.LBB0_959:
	s_lshl_b32 s0, s16, 20
	s_and_b32 s0, s0, 0xff00000
	v_readlane_b32 s12, v248, 20
	v_readlane_b32 s13, v248, 21
	s_add_u32 s0, s12, s0
	s_addc_u32 s1, s13, 0
	s_lshr_b32 s12, s16, 13
	s_and_b32 s12, s12, 0x7ff80
	s_add_u32 s0, s0, s12
	s_addc_u32 s1, s1, 0
	s_lshl_b32 s13, s16, 12
	s_and_b32 s13, s13, 0xff00000
	v_readlane_b32 s24, v248, 51
	s_add_u32 s13, s24, s13
	v_readlane_b32 s24, v248, 53
	s_addc_u32 s24, s24, 0
	s_add_u32 s12, s13, s12
	s_addc_u32 s13, s24, 0
	s_cmp_lt_i32 s19, 1
	v_cmp_gt_i64_e64 s[16:17], s[16:17], -1
	s_cbranch_scc1 .LBB0_976
	s_and_b64 s[36:37], s[16:17], exec
	s_cselect_b32 s24, s1, s35
	s_cselect_b32 s53, s0, s34
	s_cselect_b32 s56, s13, s3
	s_cselect_b32 s57, s12, s2
	s_add_i32 s58, s19, -2
	s_add_u32 s34, s34, 0x80080
	s_addc_u32 s35, s35, 0
	s_add_u32 s59, s2, 0x100
	s_addc_u32 s60, s3, 0
	s_mov_b32 s2, 0
	s_add_i32 s61, s2, 2
	s_add_u32 s3, s34, 0xfff80080
	s_addc_u32 s36, s35, -1
	s_add_i32 s64, 0, 0x10000
	s_cmp_eq_u32 s58, s2
	s_cselect_b32 s37, s24, s36
	s_cselect_b32 s36, s53, s3
	v_add_u32_e32 v142, s64, v131
	s_cselect_b32 s3, s56, s60
	s_cselect_b32 s2, s57, s59
	s_add_i32 s66, 0, 0x14000
	ds_read_b128 v[148:151], v142
	ds_read_b128 v[152:155], v142 offset:1024
	ds_read_b128 v[156:159], v142 offset:2048
	ds_read_b128 v[160:163], v142 offset:3072
	v_add_u32_e32 v142, s66, v131
	ds_read_b128 v[188:191], v142
	ds_read_b128 v[192:195], v142 offset:1024
	ds_read_b128 v[196:199], v142 offset:2048
	ds_read_b128 v[200:203], v142 offset:3072
	v_lshl_add_u64 v[236:237], s[34:35], 0, v[144:145]
	s_add_i32 m0, s40, 0xc000
	ds_read_b128 v[204:207], v186
	ds_read_b128 v[208:211], v186 offset:1024
	ds_read_b128 v[212:215], v186 offset:2048
	ds_read_b128 v[216:219], v186 offset:3072
	ds_read_b128 v[220:223], v186 offset:4096
	ds_read_b128 v[224:227], v186 offset:5120
	ds_read_b128 v[228:231], v186 offset:6144
	ds_read_b128 v[232:235], v186 offset:7168
	global_load_lds_dwordx4 v[236:237], off
	v_lshl_add_u64 v[236:237], s[34:35], 0, v[146:147]
	s_add_i32 m0, s40, 0xe000
	s_nop 0
	global_load_lds_dwordx4 v[236:237], off
	s_waitcnt vmcnt(8)
	s_waitcnt lgkmcnt(0)
	s_barrier
	s_setprio 1
	s_waitcnt lgkmcnt(0)
	v_mfma_i32_16x16x64_i8 v[126:129], v[148:151], v[204:207], 0
	v_mfma_i32_16x16x64_i8 v[126:129], v[152:155], v[208:211], v[126:129]
	v_mfma_i32_16x16x64_i8 v[122:125], v[156:159], v[204:207], 0
	v_mfma_i32_16x16x64_i8 v[122:125], v[160:163], v[208:211], v[122:125]
	v_mfma_i32_16x16x64_i8 v[118:121], v[148:151], v[212:215], 0
	v_mfma_i32_16x16x64_i8 v[118:121], v[152:155], v[216:219], v[118:121]
	v_mfma_i32_16x16x64_i8 v[114:117], v[156:159], v[212:215], 0
	v_mfma_i32_16x16x64_i8 v[114:117], v[160:163], v[216:219], v[114:117]
	v_mfma_i32_16x16x64_i8 v[110:113], v[148:151], v[220:223], 0
	v_mfma_i32_16x16x64_i8 v[110:113], v[152:155], v[224:227], v[110:113]
	v_mfma_i32_16x16x64_i8 v[106:109], v[156:159], v[220:223], 0
	v_mfma_i32_16x16x64_i8 v[106:109], v[160:163], v[224:227], v[106:109]
	v_mfma_i32_16x16x64_i8 v[102:105], v[148:151], v[228:231], 0
	v_mfma_i32_16x16x64_i8 v[102:105], v[152:155], v[232:235], v[102:105]
	v_mfma_i32_16x16x64_i8 v[98:101], v[156:159], v[228:231], 0
	v_mfma_i32_16x16x64_i8 v[98:101], v[160:163], v[232:235], v[98:101]
	s_setprio 0
	s_setprio 1
	v_mfma_i32_16x16x64_i8 v[94:97], v[188:191], v[204:207], 0
	v_mfma_i32_16x16x64_i8 v[94:97], v[192:195], v[208:211], v[94:97]
	v_mfma_i32_16x16x64_i8 v[90:93], v[196:199], v[204:207], 0
	v_mfma_i32_16x16x64_i8 v[90:93], v[200:203], v[208:211], v[90:93]
	v_mfma_i32_16x16x64_i8 v[86:89], v[188:191], v[212:215], 0
	v_mfma_i32_16x16x64_i8 v[86:89], v[192:195], v[216:219], v[86:89]
	v_mfma_i32_16x16x64_i8 v[82:85], v[196:199], v[212:215], 0
	v_mfma_i32_16x16x64_i8 v[82:85], v[200:203], v[216:219], v[82:85]
	v_mfma_i32_16x16x64_i8 v[78:81], v[188:191], v[220:223], 0
	v_mfma_i32_16x16x64_i8 v[78:81], v[192:195], v[224:227], v[78:81]
	v_mfma_i32_16x16x64_i8 v[74:77], v[196:199], v[220:223], 0
	v_mfma_i32_16x16x64_i8 v[74:77], v[200:203], v[224:227], v[74:77]
	v_mfma_i32_16x16x64_i8 v[70:73], v[188:191], v[228:231], 0
	v_mfma_i32_16x16x64_i8 v[70:73], v[192:195], v[232:235], v[70:73]
	v_mfma_i32_16x16x64_i8 v[66:69], v[196:199], v[228:231], 0
	v_mfma_i32_16x16x64_i8 v[66:69], v[200:203], v[232:235], v[66:69]
	s_setprio 0
	s_barrier
	s_add_i32 s64, s64, s39
	v_lshl_add_u64 v[236:237], s[2:3], 0, v[136:137]
	s_mov_b32 m0, s64
	ds_read_b128 v[204:207], v186 offset:16384
	ds_read_b128 v[208:211], v186 offset:17408
	ds_read_b128 v[212:215], v186 offset:18432
	ds_read_b128 v[216:219], v186 offset:19456
	ds_read_b128 v[220:223], v186 offset:20480
	ds_read_b128 v[224:227], v186 offset:21504
	ds_read_b128 v[228:231], v186 offset:22528
	ds_read_b128 v[232:235], v186 offset:23552
	global_load_lds_dwordx4 v[236:237], off
	s_add_i32 m0, s64, 0x2000
	s_add_u32 s64, s2, 0x80000
	v_lshl_add_u64 v[238:239], s[2:3], 0, v[140:141]
	s_addc_u32 s65, s3, 0
	s_add_i32 s66, s66, s39
	global_load_lds_dwordx4 v[238:239], off
	v_lshl_add_u64 v[240:241], s[64:65], 0, v[136:137]
	s_mov_b32 m0, s66
	v_lshl_add_u64 v[242:243], s[36:37], 0, v[138:139]
	global_load_lds_dwordx4 v[240:241], off
	v_lshl_add_u64 v[240:241], s[64:65], 0, v[140:141]
	s_add_i32 m0, s66, 0x2000
	s_nop 0
	global_load_lds_dwordx4 v[240:241], off
	v_lshl_add_u64 v[240:241], s[36:37], 0, v[134:135]
	s_mov_b32 m0, s40
	s_nop 0
	global_load_lds_dwordx4 v[240:241], off
	s_mov_b32 m0, s41
	s_nop 0
	global_load_lds_dwordx4 v[242:243], off
	s_waitcnt vmcnt(8)
	s_waitcnt lgkmcnt(0)
	s_barrier
	s_setprio 1
	s_waitcnt lgkmcnt(0)
	v_mfma_i32_16x16x64_i8 v[62:65], v[148:151], v[204:207], 0
	v_mfma_i32_16x16x64_i8 v[62:65], v[152:155], v[208:211], v[62:65]
	v_mfma_i32_16x16x64_i8 v[58:61], v[156:159], v[204:207], 0
	v_mfma_i32_16x16x64_i8 v[58:61], v[160:163], v[208:211], v[58:61]
	v_mfma_i32_16x16x64_i8 v[54:57], v[148:151], v[212:215], 0
	v_mfma_i32_16x16x64_i8 v[54:57], v[152:155], v[216:219], v[54:57]
	v_mfma_i32_16x16x64_i8 v[50:53], v[156:159], v[212:215], 0
	v_mfma_i32_16x16x64_i8 v[50:53], v[160:163], v[216:219], v[50:53]
	v_mfma_i32_16x16x64_i8 v[46:49], v[148:151], v[220:223], 0
	v_mfma_i32_16x16x64_i8 v[46:49], v[152:155], v[224:227], v[46:49]
	v_mfma_i32_16x16x64_i8 v[42:45], v[156:159], v[220:223], 0
	v_mfma_i32_16x16x64_i8 v[42:45], v[160:163], v[224:227], v[42:45]
	v_mfma_i32_16x16x64_i8 v[38:41], v[148:151], v[228:231], 0
	v_mfma_i32_16x16x64_i8 v[38:41], v[152:155], v[232:235], v[38:41]
	v_mfma_i32_16x16x64_i8 v[34:37], v[156:159], v[228:231], 0
	v_mfma_i32_16x16x64_i8 v[34:37], v[160:163], v[232:235], v[34:37]
	s_setprio 0
	s_setprio 1
	v_mfma_i32_16x16x64_i8 v[30:33], v[188:191], v[204:207], 0
	v_mfma_i32_16x16x64_i8 v[30:33], v[192:195], v[208:211], v[30:33]
	v_mfma_i32_16x16x64_i8 v[26:29], v[196:199], v[204:207], 0
	v_mfma_i32_16x16x64_i8 v[26:29], v[200:203], v[208:211], v[26:29]
	v_mfma_i32_16x16x64_i8 v[22:25], v[188:191], v[212:215], 0
	v_mfma_i32_16x16x64_i8 v[22:25], v[192:195], v[216:219], v[22:25]
	v_mfma_i32_16x16x64_i8 v[18:21], v[196:199], v[212:215], 0
	v_mfma_i32_16x16x64_i8 v[18:21], v[200:203], v[216:219], v[18:21]
	v_mfma_i32_16x16x64_i8 v[14:17], v[188:191], v[220:223], 0
	v_mfma_i32_16x16x64_i8 v[14:17], v[192:195], v[224:227], v[14:17]
	v_mfma_i32_16x16x64_i8 v[10:13], v[196:199], v[220:223], 0
	v_mfma_i32_16x16x64_i8 v[10:13], v[200:203], v[224:227], v[10:13]
	v_mfma_i32_16x16x64_i8 v[6:9], v[188:191], v[228:231], 0
	v_mfma_i32_16x16x64_i8 v[6:9], v[192:195], v[232:235], v[6:9]
	v_mfma_i32_16x16x64_i8 v[2:5], v[196:199], v[228:231], 0
	v_mfma_i32_16x16x64_i8 v[2:5], v[200:203], v[232:235], v[2:5]
	s_setprio 0
	s_barrier
	s_add_i32 s64, 0, 0x18000
	v_add_u32_e32 v142, s64, v131
	s_add_i32 s65, 0, 0x1c000
	ds_read_b128 v[148:151], v142
	ds_read_b128 v[152:155], v142 offset:1024
	ds_read_b128 v[156:159], v142 offset:2048
	ds_read_b128 v[160:163], v142 offset:3072
	v_add_u32_e32 v142, s65, v131
	ds_read_b128 v[188:191], v142
	ds_read_b128 v[192:195], v142 offset:1024
	ds_read_b128 v[196:199], v142 offset:2048
	ds_read_b128 v[200:203], v142 offset:3072
	s_add_u32 s36, s36, 0x80000
	s_addc_u32 s37, s37, 0
	s_mov_b32 m0, s42
	v_lshl_add_u64 v[244:245], s[36:37], 0, v[134:135]
	ds_read_b128 v[204:207], v186 offset:32768
	ds_read_b128 v[208:211], v186 offset:33792
	ds_read_b128 v[212:215], v186 offset:34816
	ds_read_b128 v[216:219], v186 offset:35840
	ds_read_b128 v[220:223], v186 offset:36864
	ds_read_b128 v[224:227], v186 offset:37888
	ds_read_b128 v[228:231], v186 offset:38912
	ds_read_b128 v[232:235], v186 offset:39936
	global_load_lds_dwordx4 v[244:245], off
	v_lshl_add_u64 v[244:245], s[36:37], 0, v[138:139]
	s_mov_b32 m0, s43
	s_nop 0
	global_load_lds_dwordx4 v[244:245], off
	s_waitcnt vmcnt(8)
	s_waitcnt lgkmcnt(0)
	s_barrier
	s_setprio 1
	s_waitcnt lgkmcnt(0)
	v_mfma_i32_16x16x64_i8 v[126:129], v[148:151], v[204:207], v[126:129]
	v_mfma_i32_16x16x64_i8 v[126:129], v[152:155], v[208:211], v[126:129]
	v_mfma_i32_16x16x64_i8 v[122:125], v[156:159], v[204:207], v[122:125]
	v_mfma_i32_16x16x64_i8 v[122:125], v[160:163], v[208:211], v[122:125]
	v_mfma_i32_16x16x64_i8 v[118:121], v[148:151], v[212:215], v[118:121]
	v_mfma_i32_16x16x64_i8 v[118:121], v[152:155], v[216:219], v[118:121]
	v_mfma_i32_16x16x64_i8 v[114:117], v[156:159], v[212:215], v[114:117]
	v_mfma_i32_16x16x64_i8 v[114:117], v[160:163], v[216:219], v[114:117]
	v_mfma_i32_16x16x64_i8 v[110:113], v[148:151], v[220:223], v[110:113]
	v_mfma_i32_16x16x64_i8 v[110:113], v[152:155], v[224:227], v[110:113]
	v_mfma_i32_16x16x64_i8 v[106:109], v[156:159], v[220:223], v[106:109]
	v_mfma_i32_16x16x64_i8 v[106:109], v[160:163], v[224:227], v[106:109]
	v_mfma_i32_16x16x64_i8 v[102:105], v[148:151], v[228:231], v[102:105]
	v_mfma_i32_16x16x64_i8 v[102:105], v[152:155], v[232:235], v[102:105]
	v_mfma_i32_16x16x64_i8 v[98:101], v[156:159], v[228:231], v[98:101]
	v_mfma_i32_16x16x64_i8 v[98:101], v[160:163], v[232:235], v[98:101]
	s_setprio 0
	s_setprio 1
	v_mfma_i32_16x16x64_i8 v[94:97], v[188:191], v[204:207], v[94:97]
	v_mfma_i32_16x16x64_i8 v[94:97], v[192:195], v[208:211], v[94:97]
	v_mfma_i32_16x16x64_i8 v[90:93], v[196:199], v[204:207], v[90:93]
	v_mfma_i32_16x16x64_i8 v[90:93], v[200:203], v[208:211], v[90:93]
	v_mfma_i32_16x16x64_i8 v[86:89], v[188:191], v[212:215], v[86:89]
	v_mfma_i32_16x16x64_i8 v[86:89], v[192:195], v[216:219], v[86:89]
	v_mfma_i32_16x16x64_i8 v[82:85], v[196:199], v[212:215], v[82:85]
	v_mfma_i32_16x16x64_i8 v[82:85], v[200:203], v[216:219], v[82:85]
	v_mfma_i32_16x16x64_i8 v[78:81], v[188:191], v[220:223], v[78:81]
	v_mfma_i32_16x16x64_i8 v[78:81], v[192:195], v[224:227], v[78:81]
	v_mfma_i32_16x16x64_i8 v[74:77], v[196:199], v[220:223], v[74:77]
	v_mfma_i32_16x16x64_i8 v[74:77], v[200:203], v[224:227], v[74:77]
	v_mfma_i32_16x16x64_i8 v[70:73], v[188:191], v[228:231], v[70:73]
	v_mfma_i32_16x16x64_i8 v[70:73], v[192:195], v[232:235], v[70:73]
	v_mfma_i32_16x16x64_i8 v[66:69], v[196:199], v[228:231], v[66:69]
	v_mfma_i32_16x16x64_i8 v[66:69], v[200:203], v[232:235], v[66:69]
	s_setprio 0
	s_barrier
	s_add_i32 s36, s64, s39
	v_lshl_add_u64 v[236:237], v[236:237], 0, s[28:29]
	s_mov_b32 m0, s36
	ds_read_b128 v[204:207], v186 offset:49152
	ds_read_b128 v[208:211], v186 offset:50176
	ds_read_b128 v[212:215], v186 offset:51200
	ds_read_b128 v[216:219], v186 offset:52224
	ds_read_b128 v[220:223], v186 offset:53248
	ds_read_b128 v[224:227], v186 offset:54272
	ds_read_b128 v[228:231], v186 offset:55296
	ds_read_b128 v[232:235], v186 offset:56320
	global_load_lds_dwordx4 v[236:237], off
	s_add_i32 m0, s36, 0x2000
	s_add_u32 s2, s2, 0x80080
	v_lshl_add_u64 v[236:237], v[238:239], 0, s[28:29]
	s_addc_u32 s3, s3, 0
	s_add_i32 s36, s65, s39
	global_load_lds_dwordx4 v[236:237], off
	v_lshl_add_u64 v[236:237], s[2:3], 0, v[136:137]
	s_mov_b32 m0, s36
	s_nop 0
	global_load_lds_dwordx4 v[236:237], off
	v_lshl_add_u64 v[236:237], s[2:3], 0, v[140:141]
	s_add_i32 m0, s36, 0x2000
	s_nop 0
	global_load_lds_dwordx4 v[236:237], off
	v_lshl_add_u64 v[236:237], v[240:241], 0, s[28:29]
	s_mov_b32 m0, s45
	s_nop 0
	global_load_lds_dwordx4 v[236:237], off
	v_lshl_add_u64 v[236:237], v[242:243], 0, s[28:29]
	s_mov_b32 m0, s52
	s_nop 0
	global_load_lds_dwordx4 v[236:237], off
	s_waitcnt vmcnt(8)
	s_waitcnt lgkmcnt(0)
	s_barrier
	s_setprio 1
	s_waitcnt lgkmcnt(0)
	v_mfma_i32_16x16x64_i8 v[62:65], v[148:151], v[204:207], v[62:65]
	v_mfma_i32_16x16x64_i8 v[62:65], v[152:155], v[208:211], v[62:65]
	v_mfma_i32_16x16x64_i8 v[58:61], v[156:159], v[204:207], v[58:61]
	v_mfma_i32_16x16x64_i8 v[58:61], v[160:163], v[208:211], v[58:61]
	v_mfma_i32_16x16x64_i8 v[54:57], v[148:151], v[212:215], v[54:57]
	v_mfma_i32_16x16x64_i8 v[54:57], v[152:155], v[216:219], v[54:57]
	v_mfma_i32_16x16x64_i8 v[50:53], v[156:159], v[212:215], v[50:53]
	v_mfma_i32_16x16x64_i8 v[50:53], v[160:163], v[216:219], v[50:53]
	v_mfma_i32_16x16x64_i8 v[46:49], v[148:151], v[220:223], v[46:49]
	v_mfma_i32_16x16x64_i8 v[46:49], v[152:155], v[224:227], v[46:49]
	v_mfma_i32_16x16x64_i8 v[42:45], v[156:159], v[220:223], v[42:45]
	v_mfma_i32_16x16x64_i8 v[42:45], v[160:163], v[224:227], v[42:45]
	v_mfma_i32_16x16x64_i8 v[38:41], v[148:151], v[228:231], v[38:41]
	v_mfma_i32_16x16x64_i8 v[38:41], v[152:155], v[232:235], v[38:41]
	v_mfma_i32_16x16x64_i8 v[34:37], v[156:159], v[228:231], v[34:37]
	v_mfma_i32_16x16x64_i8 v[34:37], v[160:163], v[232:235], v[34:37]
	s_setprio 0
	s_setprio 1
	v_mfma_i32_16x16x64_i8 v[30:33], v[188:191], v[204:207], v[30:33]
	v_mfma_i32_16x16x64_i8 v[30:33], v[192:195], v[208:211], v[30:33]
	v_mfma_i32_16x16x64_i8 v[26:29], v[196:199], v[204:207], v[26:29]
	v_mfma_i32_16x16x64_i8 v[26:29], v[200:203], v[208:211], v[26:29]
	v_mfma_i32_16x16x64_i8 v[22:25], v[188:191], v[212:215], v[22:25]
	v_mfma_i32_16x16x64_i8 v[22:25], v[192:195], v[216:219], v[22:25]
	v_mfma_i32_16x16x64_i8 v[18:21], v[196:199], v[212:215], v[18:21]
	v_mfma_i32_16x16x64_i8 v[18:21], v[200:203], v[216:219], v[18:21]
	v_mfma_i32_16x16x64_i8 v[14:17], v[188:191], v[220:223], v[14:17]
	v_mfma_i32_16x16x64_i8 v[14:17], v[192:195], v[224:227], v[14:17]
	v_mfma_i32_16x16x64_i8 v[10:13], v[196:199], v[220:223], v[10:13]
	v_mfma_i32_16x16x64_i8 v[10:13], v[200:203], v[224:227], v[10:13]
	v_mfma_i32_16x16x64_i8 v[6:9], v[188:191], v[228:231], v[6:9]
	v_mfma_i32_16x16x64_i8 v[6:9], v[192:195], v[232:235], v[6:9]
	v_mfma_i32_16x16x64_i8 v[2:5], v[196:199], v[228:231], v[2:5]
	v_mfma_i32_16x16x64_i8 v[2:5], v[200:203], v[232:235], v[2:5]
	s_setprio 0
	s_barrier
	s_add_u32 s34, s34, 0x100
	s_addc_u32 s35, s35, 0
	s_add_u32 s59, s59, 0x100
	s_addc_u32 s60, s60, 0
	s_cmp_ge_i32 s61, s19
	s_mov_b32 s2, s61
	s_cbranch_scc1 .Lkpeel_exit_5
.LBB0_961:
	s_add_i32 s61, s2, 2
	s_add_u32 s3, s34, 0xfff80080
	s_addc_u32 s36, s35, -1
	s_add_i32 s64, 0, 0x10000
	s_cmp_eq_u32 s58, s2
	s_cselect_b32 s37, s24, s36
	s_cselect_b32 s36, s53, s3
	v_add_u32_e32 v142, s64, v131
	s_cselect_b32 s3, s56, s60
	s_cselect_b32 s2, s57, s59
	s_add_i32 s66, 0, 0x14000
	ds_read_b128 v[148:151], v142
	ds_read_b128 v[152:155], v142 offset:1024
	ds_read_b128 v[156:159], v142 offset:2048
	ds_read_b128 v[160:163], v142 offset:3072
	v_add_u32_e32 v142, s66, v131
	ds_read_b128 v[188:191], v142
	ds_read_b128 v[192:195], v142 offset:1024
	ds_read_b128 v[196:199], v142 offset:2048
	ds_read_b128 v[200:203], v142 offset:3072
	v_lshl_add_u64 v[236:237], s[34:35], 0, v[144:145]
	s_add_i32 m0, s40, 0xc000
	ds_read_b128 v[204:207], v186
	ds_read_b128 v[208:211], v186 offset:1024
	ds_read_b128 v[212:215], v186 offset:2048
	ds_read_b128 v[216:219], v186 offset:3072
	ds_read_b128 v[220:223], v186 offset:4096
	ds_read_b128 v[224:227], v186 offset:5120
	ds_read_b128 v[228:231], v186 offset:6144
	ds_read_b128 v[232:235], v186 offset:7168
	global_load_lds_dwordx4 v[236:237], off
	v_lshl_add_u64 v[236:237], s[34:35], 0, v[146:147]
	s_add_i32 m0, s40, 0xe000
	s_nop 0
	global_load_lds_dwordx4 v[236:237], off
	s_waitcnt vmcnt(8)
	s_waitcnt lgkmcnt(0)
	s_barrier
	s_setprio 1
	s_waitcnt lgkmcnt(0)
	v_mfma_i32_16x16x64_i8 v[126:129], v[148:151], v[204:207], v[126:129]
	v_mfma_i32_16x16x64_i8 v[126:129], v[152:155], v[208:211], v[126:129]
	v_mfma_i32_16x16x64_i8 v[122:125], v[156:159], v[204:207], v[122:125]
	v_mfma_i32_16x16x64_i8 v[122:125], v[160:163], v[208:211], v[122:125]
	v_mfma_i32_16x16x64_i8 v[118:121], v[148:151], v[212:215], v[118:121]
	v_mfma_i32_16x16x64_i8 v[118:121], v[152:155], v[216:219], v[118:121]
	v_mfma_i32_16x16x64_i8 v[114:117], v[156:159], v[212:215], v[114:117]
	v_mfma_i32_16x16x64_i8 v[114:117], v[160:163], v[216:219], v[114:117]
	v_mfma_i32_16x16x64_i8 v[110:113], v[148:151], v[220:223], v[110:113]
	v_mfma_i32_16x16x64_i8 v[110:113], v[152:155], v[224:227], v[110:113]
	v_mfma_i32_16x16x64_i8 v[106:109], v[156:159], v[220:223], v[106:109]
	v_mfma_i32_16x16x64_i8 v[106:109], v[160:163], v[224:227], v[106:109]
	v_mfma_i32_16x16x64_i8 v[102:105], v[148:151], v[228:231], v[102:105]
	v_mfma_i32_16x16x64_i8 v[102:105], v[152:155], v[232:235], v[102:105]
	v_mfma_i32_16x16x64_i8 v[98:101], v[156:159], v[228:231], v[98:101]
	v_mfma_i32_16x16x64_i8 v[98:101], v[160:163], v[232:235], v[98:101]
	s_setprio 0
	s_setprio 1
	v_mfma_i32_16x16x64_i8 v[94:97], v[188:191], v[204:207], v[94:97]
	v_mfma_i32_16x16x64_i8 v[94:97], v[192:195], v[208:211], v[94:97]
	v_mfma_i32_16x16x64_i8 v[90:93], v[196:199], v[204:207], v[90:93]
	v_mfma_i32_16x16x64_i8 v[90:93], v[200:203], v[208:211], v[90:93]
	v_mfma_i32_16x16x64_i8 v[86:89], v[188:191], v[212:215], v[86:89]
	v_mfma_i32_16x16x64_i8 v[86:89], v[192:195], v[216:219], v[86:89]
	v_mfma_i32_16x16x64_i8 v[82:85], v[196:199], v[212:215], v[82:85]
	v_mfma_i32_16x16x64_i8 v[82:85], v[200:203], v[216:219], v[82:85]
	v_mfma_i32_16x16x64_i8 v[78:81], v[188:191], v[220:223], v[78:81]
	v_mfma_i32_16x16x64_i8 v[78:81], v[192:195], v[224:227], v[78:81]
	v_mfma_i32_16x16x64_i8 v[74:77], v[196:199], v[220:223], v[74:77]
	v_mfma_i32_16x16x64_i8 v[74:77], v[200:203], v[224:227], v[74:77]
	v_mfma_i32_16x16x64_i8 v[70:73], v[188:191], v[228:231], v[70:73]
	v_mfma_i32_16x16x64_i8 v[70:73], v[192:195], v[232:235], v[70:73]
	v_mfma_i32_16x16x64_i8 v[66:69], v[196:199], v[228:231], v[66:69]
	v_mfma_i32_16x16x64_i8 v[66:69], v[200:203], v[232:235], v[66:69]
	s_setprio 0
	s_barrier
	s_add_i32 s64, s64, s39
	v_lshl_add_u64 v[236:237], s[2:3], 0, v[136:137]
	s_mov_b32 m0, s64
	ds_read_b128 v[204:207], v186 offset:16384
	ds_read_b128 v[208:211], v186 offset:17408
	ds_read_b128 v[212:215], v186 offset:18432
	ds_read_b128 v[216:219], v186 offset:19456
	ds_read_b128 v[220:223], v186 offset:20480
	ds_read_b128 v[224:227], v186 offset:21504
	ds_read_b128 v[228:231], v186 offset:22528
	ds_read_b128 v[232:235], v186 offset:23552
	global_load_lds_dwordx4 v[236:237], off
	s_add_i32 m0, s64, 0x2000
	s_add_u32 s64, s2, 0x80000
	v_lshl_add_u64 v[238:239], s[2:3], 0, v[140:141]
	s_addc_u32 s65, s3, 0
	s_add_i32 s66, s66, s39
	global_load_lds_dwordx4 v[238:239], off
	v_lshl_add_u64 v[240:241], s[64:65], 0, v[136:137]
	s_mov_b32 m0, s66
	v_lshl_add_u64 v[242:243], s[36:37], 0, v[138:139]
	global_load_lds_dwordx4 v[240:241], off
	v_lshl_add_u64 v[240:241], s[64:65], 0, v[140:141]
	s_add_i32 m0, s66, 0x2000
	s_nop 0
	global_load_lds_dwordx4 v[240:241], off
	v_lshl_add_u64 v[240:241], s[36:37], 0, v[134:135]
	s_mov_b32 m0, s40
	s_nop 0
	global_load_lds_dwordx4 v[240:241], off
	s_mov_b32 m0, s41
	s_nop 0
	global_load_lds_dwordx4 v[242:243], off
	s_waitcnt vmcnt(8)
	s_waitcnt lgkmcnt(0)
	s_barrier
	s_setprio 1
	s_waitcnt lgkmcnt(0)
	v_mfma_i32_16x16x64_i8 v[62:65], v[148:151], v[204:207], v[62:65]
	v_mfma_i32_16x16x64_i8 v[62:65], v[152:155], v[208:211], v[62:65]
	v_mfma_i32_16x16x64_i8 v[58:61], v[156:159], v[204:207], v[58:61]
	v_mfma_i32_16x16x64_i8 v[58:61], v[160:163], v[208:211], v[58:61]
	v_mfma_i32_16x16x64_i8 v[54:57], v[148:151], v[212:215], v[54:57]
	v_mfma_i32_16x16x64_i8 v[54:57], v[152:155], v[216:219], v[54:57]
	v_mfma_i32_16x16x64_i8 v[50:53], v[156:159], v[212:215], v[50:53]
	v_mfma_i32_16x16x64_i8 v[50:53], v[160:163], v[216:219], v[50:53]
	v_mfma_i32_16x16x64_i8 v[46:49], v[148:151], v[220:223], v[46:49]
	v_mfma_i32_16x16x64_i8 v[46:49], v[152:155], v[224:227], v[46:49]
	v_mfma_i32_16x16x64_i8 v[42:45], v[156:159], v[220:223], v[42:45]
	v_mfma_i32_16x16x64_i8 v[42:45], v[160:163], v[224:227], v[42:45]
	v_mfma_i32_16x16x64_i8 v[38:41], v[148:151], v[228:231], v[38:41]
	v_mfma_i32_16x16x64_i8 v[38:41], v[152:155], v[232:235], v[38:41]
	v_mfma_i32_16x16x64_i8 v[34:37], v[156:159], v[228:231], v[34:37]
	v_mfma_i32_16x16x64_i8 v[34:37], v[160:163], v[232:235], v[34:37]
	s_setprio 0
	s_setprio 1
	v_mfma_i32_16x16x64_i8 v[30:33], v[188:191], v[204:207], v[30:33]
	v_mfma_i32_16x16x64_i8 v[30:33], v[192:195], v[208:211], v[30:33]
	v_mfma_i32_16x16x64_i8 v[26:29], v[196:199], v[204:207], v[26:29]
	v_mfma_i32_16x16x64_i8 v[26:29], v[200:203], v[208:211], v[26:29]
	v_mfma_i32_16x16x64_i8 v[22:25], v[188:191], v[212:215], v[22:25]
	v_mfma_i32_16x16x64_i8 v[22:25], v[192:195], v[216:219], v[22:25]
	v_mfma_i32_16x16x64_i8 v[18:21], v[196:199], v[212:215], v[18:21]
	v_mfma_i32_16x16x64_i8 v[18:21], v[200:203], v[216:219], v[18:21]
	v_mfma_i32_16x16x64_i8 v[14:17], v[188:191], v[220:223], v[14:17]
	v_mfma_i32_16x16x64_i8 v[14:17], v[192:195], v[224:227], v[14:17]
	v_mfma_i32_16x16x64_i8 v[10:13], v[196:199], v[220:223], v[10:13]
	v_mfma_i32_16x16x64_i8 v[10:13], v[200:203], v[224:227], v[10:13]
	v_mfma_i32_16x16x64_i8 v[6:9], v[188:191], v[228:231], v[6:9]
	v_mfma_i32_16x16x64_i8 v[6:9], v[192:195], v[232:235], v[6:9]
	v_mfma_i32_16x16x64_i8 v[2:5], v[196:199], v[228:231], v[2:5]
	v_mfma_i32_16x16x64_i8 v[2:5], v[200:203], v[232:235], v[2:5]
	s_setprio 0
	s_barrier
	s_add_i32 s64, 0, 0x18000
	v_add_u32_e32 v142, s64, v131
	s_add_i32 s65, 0, 0x1c000
	ds_read_b128 v[148:151], v142
	ds_read_b128 v[152:155], v142 offset:1024
	ds_read_b128 v[156:159], v142 offset:2048
	ds_read_b128 v[160:163], v142 offset:3072
	v_add_u32_e32 v142, s65, v131
	ds_read_b128 v[188:191], v142
	ds_read_b128 v[192:195], v142 offset:1024
	ds_read_b128 v[196:199], v142 offset:2048
	ds_read_b128 v[200:203], v142 offset:3072
	s_add_u32 s36, s36, 0x80000
	s_addc_u32 s37, s37, 0
	s_mov_b32 m0, s42
	v_lshl_add_u64 v[244:245], s[36:37], 0, v[134:135]
	ds_read_b128 v[204:207], v186 offset:32768
	ds_read_b128 v[208:211], v186 offset:33792
	ds_read_b128 v[212:215], v186 offset:34816
	ds_read_b128 v[216:219], v186 offset:35840
	ds_read_b128 v[220:223], v186 offset:36864
	ds_read_b128 v[224:227], v186 offset:37888
	ds_read_b128 v[228:231], v186 offset:38912
	ds_read_b128 v[232:235], v186 offset:39936
	global_load_lds_dwordx4 v[244:245], off
	v_lshl_add_u64 v[244:245], s[36:37], 0, v[138:139]
	s_mov_b32 m0, s43
	s_nop 0
	global_load_lds_dwordx4 v[244:245], off
	s_waitcnt vmcnt(8)
	s_waitcnt lgkmcnt(0)
	s_barrier
	s_setprio 1
	s_waitcnt lgkmcnt(0)
	v_mfma_i32_16x16x64_i8 v[126:129], v[148:151], v[204:207], v[126:129]
	v_mfma_i32_16x16x64_i8 v[126:129], v[152:155], v[208:211], v[126:129]
	v_mfma_i32_16x16x64_i8 v[122:125], v[156:159], v[204:207], v[122:125]
	v_mfma_i32_16x16x64_i8 v[122:125], v[160:163], v[208:211], v[122:125]
	v_mfma_i32_16x16x64_i8 v[118:121], v[148:151], v[212:215], v[118:121]
	v_mfma_i32_16x16x64_i8 v[118:121], v[152:155], v[216:219], v[118:121]
	v_mfma_i32_16x16x64_i8 v[114:117], v[156:159], v[212:215], v[114:117]
	v_mfma_i32_16x16x64_i8 v[114:117], v[160:163], v[216:219], v[114:117]
	v_mfma_i32_16x16x64_i8 v[110:113], v[148:151], v[220:223], v[110:113]
	v_mfma_i32_16x16x64_i8 v[110:113], v[152:155], v[224:227], v[110:113]
	v_mfma_i32_16x16x64_i8 v[106:109], v[156:159], v[220:223], v[106:109]
	v_mfma_i32_16x16x64_i8 v[106:109], v[160:163], v[224:227], v[106:109]
	v_mfma_i32_16x16x64_i8 v[102:105], v[148:151], v[228:231], v[102:105]
	v_mfma_i32_16x16x64_i8 v[102:105], v[152:155], v[232:235], v[102:105]
	v_mfma_i32_16x16x64_i8 v[98:101], v[156:159], v[228:231], v[98:101]
	v_mfma_i32_16x16x64_i8 v[98:101], v[160:163], v[232:235], v[98:101]
	s_setprio 0
	s_setprio 1
	v_mfma_i32_16x16x64_i8 v[94:97], v[188:191], v[204:207], v[94:97]
	v_mfma_i32_16x16x64_i8 v[94:97], v[192:195], v[208:211], v[94:97]
	v_mfma_i32_16x16x64_i8 v[90:93], v[196:199], v[204:207], v[90:93]
	v_mfma_i32_16x16x64_i8 v[90:93], v[200:203], v[208:211], v[90:93]
	v_mfma_i32_16x16x64_i8 v[86:89], v[188:191], v[212:215], v[86:89]
	v_mfma_i32_16x16x64_i8 v[86:89], v[192:195], v[216:219], v[86:89]
	v_mfma_i32_16x16x64_i8 v[82:85], v[196:199], v[212:215], v[82:85]
	v_mfma_i32_16x16x64_i8 v[82:85], v[200:203], v[216:219], v[82:85]
	v_mfma_i32_16x16x64_i8 v[78:81], v[188:191], v[220:223], v[78:81]
	v_mfma_i32_16x16x64_i8 v[78:81], v[192:195], v[224:227], v[78:81]
	v_mfma_i32_16x16x64_i8 v[74:77], v[196:199], v[220:223], v[74:77]
	v_mfma_i32_16x16x64_i8 v[74:77], v[200:203], v[224:227], v[74:77]
	v_mfma_i32_16x16x64_i8 v[70:73], v[188:191], v[228:231], v[70:73]
	v_mfma_i32_16x16x64_i8 v[70:73], v[192:195], v[232:235], v[70:73]
	v_mfma_i32_16x16x64_i8 v[66:69], v[196:199], v[228:231], v[66:69]
	v_mfma_i32_16x16x64_i8 v[66:69], v[200:203], v[232:235], v[66:69]
	s_setprio 0
	s_barrier
	s_add_i32 s36, s64, s39
	v_lshl_add_u64 v[236:237], v[236:237], 0, s[28:29]
	s_mov_b32 m0, s36
	ds_read_b128 v[204:207], v186 offset:49152
	ds_read_b128 v[208:211], v186 offset:50176
	ds_read_b128 v[212:215], v186 offset:51200
	ds_read_b128 v[216:219], v186 offset:52224
	ds_read_b128 v[220:223], v186 offset:53248
	ds_read_b128 v[224:227], v186 offset:54272
	ds_read_b128 v[228:231], v186 offset:55296
	ds_read_b128 v[232:235], v186 offset:56320
	global_load_lds_dwordx4 v[236:237], off
	s_add_i32 m0, s36, 0x2000
	s_add_u32 s2, s2, 0x80080
	v_lshl_add_u64 v[236:237], v[238:239], 0, s[28:29]
	s_addc_u32 s3, s3, 0
	s_add_i32 s36, s65, s39
	global_load_lds_dwordx4 v[236:237], off
	v_lshl_add_u64 v[236:237], s[2:3], 0, v[136:137]
	s_mov_b32 m0, s36
	s_nop 0
	global_load_lds_dwordx4 v[236:237], off
	v_lshl_add_u64 v[236:237], s[2:3], 0, v[140:141]
	s_add_i32 m0, s36, 0x2000
	s_nop 0
	global_load_lds_dwordx4 v[236:237], off
	v_lshl_add_u64 v[236:237], v[240:241], 0, s[28:29]
	s_mov_b32 m0, s45
	s_nop 0
	global_load_lds_dwordx4 v[236:237], off
	v_lshl_add_u64 v[236:237], v[242:243], 0, s[28:29]
	s_mov_b32 m0, s52
	s_nop 0
	global_load_lds_dwordx4 v[236:237], off
	s_waitcnt vmcnt(8)
	s_waitcnt lgkmcnt(0)
	s_barrier
	s_setprio 1
	s_waitcnt lgkmcnt(0)
	v_mfma_i32_16x16x64_i8 v[62:65], v[148:151], v[204:207], v[62:65]
	v_mfma_i32_16x16x64_i8 v[62:65], v[152:155], v[208:211], v[62:65]
	v_mfma_i32_16x16x64_i8 v[58:61], v[156:159], v[204:207], v[58:61]
	v_mfma_i32_16x16x64_i8 v[58:61], v[160:163], v[208:211], v[58:61]
	v_mfma_i32_16x16x64_i8 v[54:57], v[148:151], v[212:215], v[54:57]
	v_mfma_i32_16x16x64_i8 v[54:57], v[152:155], v[216:219], v[54:57]
	v_mfma_i32_16x16x64_i8 v[50:53], v[156:159], v[212:215], v[50:53]
	v_mfma_i32_16x16x64_i8 v[50:53], v[160:163], v[216:219], v[50:53]
	v_mfma_i32_16x16x64_i8 v[46:49], v[148:151], v[220:223], v[46:49]
	v_mfma_i32_16x16x64_i8 v[46:49], v[152:155], v[224:227], v[46:49]
	v_mfma_i32_16x16x64_i8 v[42:45], v[156:159], v[220:223], v[42:45]
	v_mfma_i32_16x16x64_i8 v[42:45], v[160:163], v[224:227], v[42:45]
	v_mfma_i32_16x16x64_i8 v[38:41], v[148:151], v[228:231], v[38:41]
	v_mfma_i32_16x16x64_i8 v[38:41], v[152:155], v[232:235], v[38:41]
	v_mfma_i32_16x16x64_i8 v[34:37], v[156:159], v[228:231], v[34:37]
	v_mfma_i32_16x16x64_i8 v[34:37], v[160:163], v[232:235], v[34:37]
	s_setprio 0
	s_setprio 1
	v_mfma_i32_16x16x64_i8 v[30:33], v[188:191], v[204:207], v[30:33]
	v_mfma_i32_16x16x64_i8 v[30:33], v[192:195], v[208:211], v[30:33]
	v_mfma_i32_16x16x64_i8 v[26:29], v[196:199], v[204:207], v[26:29]
	v_mfma_i32_16x16x64_i8 v[26:29], v[200:203], v[208:211], v[26:29]
	v_mfma_i32_16x16x64_i8 v[22:25], v[188:191], v[212:215], v[22:25]
	v_mfma_i32_16x16x64_i8 v[22:25], v[192:195], v[216:219], v[22:25]
	v_mfma_i32_16x16x64_i8 v[18:21], v[196:199], v[212:215], v[18:21]
	v_mfma_i32_16x16x64_i8 v[18:21], v[200:203], v[216:219], v[18:21]
	v_mfma_i32_16x16x64_i8 v[14:17], v[188:191], v[220:223], v[14:17]
	v_mfma_i32_16x16x64_i8 v[14:17], v[192:195], v[224:227], v[14:17]
	v_mfma_i32_16x16x64_i8 v[10:13], v[196:199], v[220:223], v[10:13]
	v_mfma_i32_16x16x64_i8 v[10:13], v[200:203], v[224:227], v[10:13]
	v_mfma_i32_16x16x64_i8 v[6:9], v[188:191], v[228:231], v[6:9]
	v_mfma_i32_16x16x64_i8 v[6:9], v[192:195], v[232:235], v[6:9]
	v_mfma_i32_16x16x64_i8 v[2:5], v[196:199], v[228:231], v[2:5]
	v_mfma_i32_16x16x64_i8 v[2:5], v[200:203], v[232:235], v[2:5]
	s_setprio 0
	s_barrier
	s_add_u32 s34, s34, 0x100
	s_addc_u32 s35, s35, 0
	s_add_u32 s59, s59, 0x100
	s_addc_u32 s60, s60, 0
	s_cmp_ge_i32 s61, s19
	s_mov_b32 s2, s61
	s_cbranch_scc0 .LBB0_961

.LBB0_1126:
	s_cmp_lt_i32 s29, 1
	s_cbranch_scc1 .LBB0_1148
	s_add_i32 s18, s29, -2
	s_add_u32 s30, s30, 0x2b0080
	s_addc_u32 s31, s31, 0
	s_add_u32 s28, s2, 0x100
	s_addc_u32 s52, s3, 0
	s_mov_b32 s2, 0
	ds_read_b128 v[148:151], v145
	ds_read_b128 v[152:155], v145 offset:1024
	ds_read_b128 v[156:159], v145 offset:2048
	ds_read_b128 v[160:163], v145 offset:3072
	ds_read_b128 v[164:167], v146
	ds_read_b128 v[170:173], v146 offset:1024
	ds_read_b128 v[174:177], v146 offset:2048
	ds_read_b128 v[178:181], v146 offset:3072
	s_add_i32 s53, s2, 2
	s_add_u32 s3, s30, 0xffd50080
	s_addc_u32 s34, s31, -1
	s_cmp_eq_u32 s18, s2
	s_cselect_b32 s2, s26, s28
	s_cselect_b32 s35, s25, s34
	s_cselect_b32 s34, s24, s3
	s_cselect_b32 s3, s27, s52
	v_lshl_add_u64 v[214:215], s[30:31], 0, v[140:141]
	s_add_i32 m0, s37, 0xc000
	ds_read_b128 v[182:185], v147
	ds_read_b128 v[186:189], v147 offset:1024
	ds_read_b128 v[190:193], v147 offset:2048
	ds_read_b128 v[194:197], v147 offset:3072
	ds_read_b128 v[198:201], v147 offset:4096
	ds_read_b128 v[202:205], v147 offset:5120
	ds_read_b128 v[206:209], v147 offset:6144
	ds_read_b128 v[210:213], v147 offset:7168
	global_load_lds_dwordx4 v[214:215], off
	v_lshl_add_u64 v[214:215], s[30:31], 0, v[142:143]
	s_add_i32 m0, s37, 0xe000
	s_nop 0
	global_load_lds_dwordx4 v[214:215], off
	s_waitcnt vmcnt(8)
	s_waitcnt lgkmcnt(0)
	s_barrier
	s_setprio 1
	s_waitcnt lgkmcnt(0)
	v_mfma_f32_16x16x32_bf16 v[124:127], v[148:151], v[182:185], 0
	v_mfma_f32_16x16x32_bf16 v[124:127], v[152:155], v[186:189], v[124:127]
	v_mfma_f32_16x16x32_bf16 v[120:123], v[156:159], v[182:185], 0
	v_mfma_f32_16x16x32_bf16 v[120:123], v[160:163], v[186:189], v[120:123]
	v_mfma_f32_16x16x32_bf16 v[108:111], v[148:151], v[190:193], 0
	v_mfma_f32_16x16x32_bf16 v[108:111], v[152:155], v[194:197], v[108:111]
	v_mfma_f32_16x16x32_bf16 v[100:103], v[156:159], v[190:193], 0
	v_mfma_f32_16x16x32_bf16 v[100:103], v[160:163], v[194:197], v[100:103]
	v_mfma_f32_16x16x32_bf16 v[92:95], v[148:151], v[198:201], 0
	v_mfma_f32_16x16x32_bf16 v[92:95], v[152:155], v[202:205], v[92:95]
	v_mfma_f32_16x16x32_bf16 v[84:87], v[156:159], v[198:201], 0
	v_mfma_f32_16x16x32_bf16 v[84:87], v[160:163], v[202:205], v[84:87]
	v_mfma_f32_16x16x32_bf16 v[76:79], v[148:151], v[206:209], 0
	v_mfma_f32_16x16x32_bf16 v[76:79], v[152:155], v[210:213], v[76:79]
	v_mfma_f32_16x16x32_bf16 v[68:71], v[156:159], v[206:209], 0
	v_mfma_f32_16x16x32_bf16 v[68:71], v[160:163], v[210:213], v[68:71]
	s_setprio 0
	s_setprio 1
	v_mfma_f32_16x16x32_bf16 v[116:119], v[164:167], v[182:185], 0
	v_mfma_f32_16x16x32_bf16 v[116:119], v[170:173], v[186:189], v[116:119]
	v_mfma_f32_16x16x32_bf16 v[112:115], v[174:177], v[182:185], 0
	v_mfma_f32_16x16x32_bf16 v[112:115], v[178:181], v[186:189], v[112:115]
	v_mfma_f32_16x16x32_bf16 v[104:107], v[164:167], v[190:193], 0
	v_mfma_f32_16x16x32_bf16 v[104:107], v[170:173], v[194:197], v[104:107]
	v_mfma_f32_16x16x32_bf16 v[96:99], v[174:177], v[190:193], 0
	v_mfma_f32_16x16x32_bf16 v[96:99], v[178:181], v[194:197], v[96:99]
	v_mfma_f32_16x16x32_bf16 v[88:91], v[164:167], v[198:201], 0
	v_mfma_f32_16x16x32_bf16 v[88:91], v[170:173], v[202:205], v[88:91]
	v_mfma_f32_16x16x32_bf16 v[80:83], v[174:177], v[198:201], 0
	v_mfma_f32_16x16x32_bf16 v[80:83], v[178:181], v[202:205], v[80:83]
	v_mfma_f32_16x16x32_bf16 v[72:75], v[164:167], v[206:209], 0
	v_mfma_f32_16x16x32_bf16 v[72:75], v[170:173], v[210:213], v[72:75]
	v_mfma_f32_16x16x32_bf16 v[64:67], v[174:177], v[206:209], 0
	v_mfma_f32_16x16x32_bf16 v[64:67], v[178:181], v[210:213], v[64:67]
	s_setprio 0
	s_barrier
	s_add_i32 s56, s46, s33
	v_lshl_add_u64 v[214:215], s[2:3], 0, v[134:135]
	s_mov_b32 m0, s56
	ds_read_b128 v[182:185], v147 offset:16384
	ds_read_b128 v[186:189], v147 offset:17408
	ds_read_b128 v[190:193], v147 offset:18432
	ds_read_b128 v[194:197], v147 offset:19456
	ds_read_b128 v[198:201], v147 offset:20480
	ds_read_b128 v[202:205], v147 offset:21504
	ds_read_b128 v[206:209], v147 offset:22528
	ds_read_b128 v[210:213], v147 offset:23552
	global_load_lds_dwordx4 v[214:215], off
	s_add_i32 m0, s56, 0x2000
	s_add_u32 s56, s2, 0x2b0000
	v_lshl_add_u64 v[216:217], s[2:3], 0, v[138:139]
	s_addc_u32 s57, s3, 0
	s_add_i32 s58, s47, s33
	global_load_lds_dwordx4 v[216:217], off
	v_lshl_add_u64 v[218:219], s[56:57], 0, v[134:135]
	s_mov_b32 m0, s58
	v_lshl_add_u64 v[220:221], s[34:35], 0, v[136:137]
	global_load_lds_dwordx4 v[218:219], off
	v_lshl_add_u64 v[218:219], s[56:57], 0, v[138:139]
	s_add_i32 m0, s58, 0x2000
	s_nop 0
	global_load_lds_dwordx4 v[218:219], off
	v_lshl_add_u64 v[218:219], s[34:35], 0, v[128:129]
	s_mov_b32 m0, s37
	s_nop 0
	global_load_lds_dwordx4 v[218:219], off
	s_mov_b32 m0, s38
	s_nop 0
	global_load_lds_dwordx4 v[220:221], off
	s_waitcnt vmcnt(8)
	s_waitcnt lgkmcnt(0)
	s_barrier
	s_setprio 1
	s_waitcnt lgkmcnt(0)
	v_mfma_f32_16x16x32_bf16 v[60:63], v[148:151], v[182:185], 0
	v_mfma_f32_16x16x32_bf16 v[60:63], v[152:155], v[186:189], v[60:63]
	v_mfma_f32_16x16x32_bf16 v[52:55], v[156:159], v[182:185], 0
	v_mfma_f32_16x16x32_bf16 v[52:55], v[160:163], v[186:189], v[52:55]
	v_mfma_f32_16x16x32_bf16 v[44:47], v[148:151], v[190:193], 0
	v_mfma_f32_16x16x32_bf16 v[44:47], v[152:155], v[194:197], v[44:47]
	v_mfma_f32_16x16x32_bf16 v[36:39], v[156:159], v[190:193], 0
	v_mfma_f32_16x16x32_bf16 v[36:39], v[160:163], v[194:197], v[36:39]
	v_mfma_f32_16x16x32_bf16 v[28:31], v[148:151], v[198:201], 0
	v_mfma_f32_16x16x32_bf16 v[28:31], v[152:155], v[202:205], v[28:31]
	v_mfma_f32_16x16x32_bf16 v[20:23], v[156:159], v[198:201], 0
	v_mfma_f32_16x16x32_bf16 v[20:23], v[160:163], v[202:205], v[20:23]
	v_mfma_f32_16x16x32_bf16 v[12:15], v[148:151], v[206:209], 0
	v_mfma_f32_16x16x32_bf16 v[12:15], v[152:155], v[210:213], v[12:15]
	v_mfma_f32_16x16x32_bf16 v[4:7], v[156:159], v[206:209], 0
	v_mfma_f32_16x16x32_bf16 v[4:7], v[160:163], v[210:213], v[4:7]
	s_setprio 0
	s_setprio 1
	v_mfma_f32_16x16x32_bf16 v[56:59], v[164:167], v[182:185], 0
	v_mfma_f32_16x16x32_bf16 v[56:59], v[170:173], v[186:189], v[56:59]
	v_mfma_f32_16x16x32_bf16 v[48:51], v[174:177], v[182:185], 0
	v_mfma_f32_16x16x32_bf16 v[48:51], v[178:181], v[186:189], v[48:51]
	v_mfma_f32_16x16x32_bf16 v[40:43], v[164:167], v[190:193], 0
	v_mfma_f32_16x16x32_bf16 v[40:43], v[170:173], v[194:197], v[40:43]
	v_mfma_f32_16x16x32_bf16 v[32:35], v[174:177], v[190:193], 0
	v_mfma_f32_16x16x32_bf16 v[32:35], v[178:181], v[194:197], v[32:35]
	v_mfma_f32_16x16x32_bf16 v[24:27], v[164:167], v[198:201], 0
	v_mfma_f32_16x16x32_bf16 v[24:27], v[170:173], v[202:205], v[24:27]
	v_mfma_f32_16x16x32_bf16 v[16:19], v[174:177], v[198:201], 0
	v_mfma_f32_16x16x32_bf16 v[16:19], v[178:181], v[202:205], v[16:19]
	v_mfma_f32_16x16x32_bf16 v[8:11], v[164:167], v[206:209], 0
	v_mfma_f32_16x16x32_bf16 v[8:11], v[170:173], v[210:213], v[8:11]
	v_mfma_f32_16x16x32_bf16 v[0:3], v[174:177], v[206:209], 0
	v_mfma_f32_16x16x32_bf16 v[0:3], v[178:181], v[210:213], v[0:3]
	s_setprio 0
	s_barrier
	s_add_i32 s56, 0, 0x18000
	s_add_i32 s57, 0, 0x1c000
	v_add_u32_e32 v160, s56, v133
	v_add_u32_e32 v168, s57, v133
	ds_read_b128 v[148:151], v160
	ds_read_b128 v[152:155], v160 offset:1024
	ds_read_b128 v[156:159], v160 offset:2048
	ds_read_b128 v[160:163], v160 offset:3072
	ds_read_b128 v[164:167], v168
	ds_read_b128 v[170:173], v168 offset:1024
	ds_read_b128 v[174:177], v168 offset:2048
	ds_read_b128 v[178:181], v168 offset:3072
	s_add_u32 s34, s34, 0x2b0000
	s_addc_u32 s35, s35, 0
	s_mov_b32 m0, s39
	v_lshl_add_u64 v[222:223], s[34:35], 0, v[128:129]
	ds_read_b128 v[182:185], v147 offset:32768
	ds_read_b128 v[186:189], v147 offset:33792
	ds_read_b128 v[190:193], v147 offset:34816
	ds_read_b128 v[194:197], v147 offset:35840
	ds_read_b128 v[198:201], v147 offset:36864
	ds_read_b128 v[202:205], v147 offset:37888
	ds_read_b128 v[206:209], v147 offset:38912
	ds_read_b128 v[210:213], v147 offset:39936
	global_load_lds_dwordx4 v[222:223], off
	v_lshl_add_u64 v[222:223], s[34:35], 0, v[136:137]
	s_mov_b32 m0, s40
	s_nop 0
	global_load_lds_dwordx4 v[222:223], off
	s_waitcnt vmcnt(8)
	s_waitcnt lgkmcnt(0)
	s_barrier
	s_setprio 1
	s_waitcnt lgkmcnt(0)
	v_mfma_f32_16x16x32_bf16 v[124:127], v[148:151], v[182:185], v[124:127]
	v_mfma_f32_16x16x32_bf16 v[124:127], v[152:155], v[186:189], v[124:127]
	v_mfma_f32_16x16x32_bf16 v[120:123], v[156:159], v[182:185], v[120:123]
	v_mfma_f32_16x16x32_bf16 v[120:123], v[160:163], v[186:189], v[120:123]
	v_mfma_f32_16x16x32_bf16 v[108:111], v[148:151], v[190:193], v[108:111]
	v_mfma_f32_16x16x32_bf16 v[108:111], v[152:155], v[194:197], v[108:111]
	v_mfma_f32_16x16x32_bf16 v[100:103], v[156:159], v[190:193], v[100:103]
	v_mfma_f32_16x16x32_bf16 v[100:103], v[160:163], v[194:197], v[100:103]
	v_mfma_f32_16x16x32_bf16 v[92:95], v[148:151], v[198:201], v[92:95]
	v_mfma_f32_16x16x32_bf16 v[92:95], v[152:155], v[202:205], v[92:95]
	v_mfma_f32_16x16x32_bf16 v[84:87], v[156:159], v[198:201], v[84:87]
	v_mfma_f32_16x16x32_bf16 v[84:87], v[160:163], v[202:205], v[84:87]
	v_mfma_f32_16x16x32_bf16 v[76:79], v[148:151], v[206:209], v[76:79]
	v_mfma_f32_16x16x32_bf16 v[76:79], v[152:155], v[210:213], v[76:79]
	v_mfma_f32_16x16x32_bf16 v[68:71], v[156:159], v[206:209], v[68:71]
	v_mfma_f32_16x16x32_bf16 v[68:71], v[160:163], v[210:213], v[68:71]
	s_setprio 0
	s_setprio 1
	v_mfma_f32_16x16x32_bf16 v[116:119], v[164:167], v[182:185], v[116:119]
	v_mfma_f32_16x16x32_bf16 v[116:119], v[170:173], v[186:189], v[116:119]
	v_mfma_f32_16x16x32_bf16 v[112:115], v[174:177], v[182:185], v[112:115]
	v_mfma_f32_16x16x32_bf16 v[112:115], v[178:181], v[186:189], v[112:115]
	v_mfma_f32_16x16x32_bf16 v[104:107], v[164:167], v[190:193], v[104:107]
	v_mfma_f32_16x16x32_bf16 v[104:107], v[170:173], v[194:197], v[104:107]
	v_mfma_f32_16x16x32_bf16 v[96:99], v[174:177], v[190:193], v[96:99]
	v_mfma_f32_16x16x32_bf16 v[96:99], v[178:181], v[194:197], v[96:99]
	v_mfma_f32_16x16x32_bf16 v[88:91], v[164:167], v[198:201], v[88:91]
	v_mfma_f32_16x16x32_bf16 v[88:91], v[170:173], v[202:205], v[88:91]
	v_mfma_f32_16x16x32_bf16 v[80:83], v[174:177], v[198:201], v[80:83]
	v_mfma_f32_16x16x32_bf16 v[80:83], v[178:181], v[202:205], v[80:83]
	v_mfma_f32_16x16x32_bf16 v[72:75], v[164:167], v[206:209], v[72:75]
	v_mfma_f32_16x16x32_bf16 v[72:75], v[170:173], v[210:213], v[72:75]
	v_mfma_f32_16x16x32_bf16 v[64:67], v[174:177], v[206:209], v[64:67]
	v_mfma_f32_16x16x32_bf16 v[64:67], v[178:181], v[210:213], v[64:67]
	s_setprio 0
	s_barrier
	s_add_i32 s34, s56, s33
	v_lshl_add_u64 v[214:215], v[214:215], 0, s[6:7]
	s_mov_b32 m0, s34
	ds_read_b128 v[182:185], v147 offset:49152
	ds_read_b128 v[186:189], v147 offset:50176
	ds_read_b128 v[190:193], v147 offset:51200
	ds_read_b128 v[194:197], v147 offset:52224
	ds_read_b128 v[198:201], v147 offset:53248
	ds_read_b128 v[202:205], v147 offset:54272
	ds_read_b128 v[206:209], v147 offset:55296
	ds_read_b128 v[210:213], v147 offset:56320
	global_load_lds_dwordx4 v[214:215], off
	s_add_i32 m0, s34, 0x2000
	s_add_u32 s2, s2, 0x2b0080
	v_lshl_add_u64 v[214:215], v[216:217], 0, s[6:7]
	s_addc_u32 s3, s3, 0
	s_add_i32 s34, s57, s33
	global_load_lds_dwordx4 v[214:215], off
	v_lshl_add_u64 v[214:215], s[2:3], 0, v[134:135]
	s_mov_b32 m0, s34
	s_nop 0
	global_load_lds_dwordx4 v[214:215], off
	v_lshl_add_u64 v[214:215], s[2:3], 0, v[138:139]
	s_add_i32 m0, s34, 0x2000
	s_nop 0
	global_load_lds_dwordx4 v[214:215], off
	v_lshl_add_u64 v[214:215], v[218:219], 0, s[6:7]
	s_mov_b32 m0, s42
	s_nop 0
	global_load_lds_dwordx4 v[214:215], off
	v_lshl_add_u64 v[214:215], v[220:221], 0, s[6:7]
	s_mov_b32 m0, s43
	s_nop 0
	global_load_lds_dwordx4 v[214:215], off
	s_waitcnt vmcnt(8)
	s_waitcnt lgkmcnt(0)
	s_barrier
	s_setprio 1
	s_waitcnt lgkmcnt(0)
	v_mfma_f32_16x16x32_bf16 v[60:63], v[148:151], v[182:185], v[60:63]
	v_mfma_f32_16x16x32_bf16 v[60:63], v[152:155], v[186:189], v[60:63]
	v_mfma_f32_16x16x32_bf16 v[52:55], v[156:159], v[182:185], v[52:55]
	v_mfma_f32_16x16x32_bf16 v[52:55], v[160:163], v[186:189], v[52:55]
	v_mfma_f32_16x16x32_bf16 v[44:47], v[148:151], v[190:193], v[44:47]
	v_mfma_f32_16x16x32_bf16 v[44:47], v[152:155], v[194:197], v[44:47]
	v_mfma_f32_16x16x32_bf16 v[36:39], v[156:159], v[190:193], v[36:39]
	v_mfma_f32_16x16x32_bf16 v[36:39], v[160:163], v[194:197], v[36:39]
	v_mfma_f32_16x16x32_bf16 v[28:31], v[148:151], v[198:201], v[28:31]
	v_mfma_f32_16x16x32_bf16 v[28:31], v[152:155], v[202:205], v[28:31]
	v_mfma_f32_16x16x32_bf16 v[20:23], v[156:159], v[198:201], v[20:23]
	v_mfma_f32_16x16x32_bf16 v[20:23], v[160:163], v[202:205], v[20:23]
	v_mfma_f32_16x16x32_bf16 v[12:15], v[148:151], v[206:209], v[12:15]
	v_mfma_f32_16x16x32_bf16 v[12:15], v[152:155], v[210:213], v[12:15]
	v_mfma_f32_16x16x32_bf16 v[4:7], v[156:159], v[206:209], v[4:7]
	v_mfma_f32_16x16x32_bf16 v[4:7], v[160:163], v[210:213], v[4:7]
	s_setprio 0
	s_setprio 1
	v_mfma_f32_16x16x32_bf16 v[56:59], v[164:167], v[182:185], v[56:59]
	v_mfma_f32_16x16x32_bf16 v[56:59], v[170:173], v[186:189], v[56:59]
	v_mfma_f32_16x16x32_bf16 v[48:51], v[174:177], v[182:185], v[48:51]
	v_mfma_f32_16x16x32_bf16 v[48:51], v[178:181], v[186:189], v[48:51]
	v_mfma_f32_16x16x32_bf16 v[40:43], v[164:167], v[190:193], v[40:43]
	v_mfma_f32_16x16x32_bf16 v[40:43], v[170:173], v[194:197], v[40:43]
	v_mfma_f32_16x16x32_bf16 v[32:35], v[174:177], v[190:193], v[32:35]
	v_mfma_f32_16x16x32_bf16 v[32:35], v[178:181], v[194:197], v[32:35]
	v_mfma_f32_16x16x32_bf16 v[24:27], v[164:167], v[198:201], v[24:27]
	v_mfma_f32_16x16x32_bf16 v[24:27], v[170:173], v[202:205], v[24:27]
	v_mfma_f32_16x16x32_bf16 v[16:19], v[174:177], v[198:201], v[16:19]
	v_mfma_f32_16x16x32_bf16 v[16:19], v[178:181], v[202:205], v[16:19]
	v_mfma_f32_16x16x32_bf16 v[8:11], v[164:167], v[206:209], v[8:11]
	v_mfma_f32_16x16x32_bf16 v[8:11], v[170:173], v[210:213], v[8:11]
	v_mfma_f32_16x16x32_bf16 v[0:3], v[174:177], v[206:209], v[0:3]
	v_mfma_f32_16x16x32_bf16 v[0:3], v[178:181], v[210:213], v[0:3]
	s_setprio 0
	s_barrier
	s_add_u32 s30, s30, 0x100
	s_addc_u32 s31, s31, 0
	s_add_u32 s28, s28, 0x100
	s_addc_u32 s52, s52, 0
	s_cmp_ge_i32 s53, s29
	s_mov_b32 s2, s53
	s_cbranch_scc1 .Lkpeel_exit_6
.LBB0_1128:
	ds_read_b128 v[148:151], v145
	ds_read_b128 v[152:155], v145 offset:1024
	ds_read_b128 v[156:159], v145 offset:2048
	ds_read_b128 v[160:163], v145 offset:3072
	ds_read_b128 v[164:167], v146
	ds_read_b128 v[170:173], v146 offset:1024
	ds_read_b128 v[174:177], v146 offset:2048
	ds_read_b128 v[178:181], v146 offset:3072
	s_add_i32 s53, s2, 2
	s_add_u32 s3, s30, 0xffd50080
	s_addc_u32 s34, s31, -1
	s_cmp_eq_u32 s18, s2
	s_cselect_b32 s2, s26, s28
	s_cselect_b32 s35, s25, s34
	s_cselect_b32 s34, s24, s3
	s_cselect_b32 s3, s27, s52
	v_lshl_add_u64 v[214:215], s[30:31], 0, v[140:141]
	s_add_i32 m0, s37, 0xc000
	ds_read_b128 v[182:185], v147
	ds_read_b128 v[186:189], v147 offset:1024
	ds_read_b128 v[190:193], v147 offset:2048
	ds_read_b128 v[194:197], v147 offset:3072
	ds_read_b128 v[198:201], v147 offset:4096
	ds_read_b128 v[202:205], v147 offset:5120
	ds_read_b128 v[206:209], v147 offset:6144
	ds_read_b128 v[210:213], v147 offset:7168
	global_load_lds_dwordx4 v[214:215], off
	v_lshl_add_u64 v[214:215], s[30:31], 0, v[142:143]
	s_add_i32 m0, s37, 0xe000
	s_nop 0
	global_load_lds_dwordx4 v[214:215], off
	s_waitcnt vmcnt(8)
	s_waitcnt lgkmcnt(0)
	s_barrier
	s_setprio 1
	s_waitcnt lgkmcnt(0)
	v_mfma_f32_16x16x32_bf16 v[124:127], v[148:151], v[182:185], v[124:127]
	v_mfma_f32_16x16x32_bf16 v[124:127], v[152:155], v[186:189], v[124:127]
	v_mfma_f32_16x16x32_bf16 v[120:123], v[156:159], v[182:185], v[120:123]
	v_mfma_f32_16x16x32_bf16 v[120:123], v[160:163], v[186:189], v[120:123]
	v_mfma_f32_16x16x32_bf16 v[108:111], v[148:151], v[190:193], v[108:111]
	v_mfma_f32_16x16x32_bf16 v[108:111], v[152:155], v[194:197], v[108:111]
	v_mfma_f32_16x16x32_bf16 v[100:103], v[156:159], v[190:193], v[100:103]
	v_mfma_f32_16x16x32_bf16 v[100:103], v[160:163], v[194:197], v[100:103]
	v_mfma_f32_16x16x32_bf16 v[92:95], v[148:151], v[198:201], v[92:95]
	v_mfma_f32_16x16x32_bf16 v[92:95], v[152:155], v[202:205], v[92:95]
	v_mfma_f32_16x16x32_bf16 v[84:87], v[156:159], v[198:201], v[84:87]
	v_mfma_f32_16x16x32_bf16 v[84:87], v[160:163], v[202:205], v[84:87]
	v_mfma_f32_16x16x32_bf16 v[76:79], v[148:151], v[206:209], v[76:79]
	v_mfma_f32_16x16x32_bf16 v[76:79], v[152:155], v[210:213], v[76:79]
	v_mfma_f32_16x16x32_bf16 v[68:71], v[156:159], v[206:209], v[68:71]
	v_mfma_f32_16x16x32_bf16 v[68:71], v[160:163], v[210:213], v[68:71]
	s_setprio 0
	s_setprio 1
	v_mfma_f32_16x16x32_bf16 v[116:119], v[164:167], v[182:185], v[116:119]
	v_mfma_f32_16x16x32_bf16 v[116:119], v[170:173], v[186:189], v[116:119]
	v_mfma_f32_16x16x32_bf16 v[112:115], v[174:177], v[182:185], v[112:115]
	v_mfma_f32_16x16x32_bf16 v[112:115], v[178:181], v[186:189], v[112:115]
	v_mfma_f32_16x16x32_bf16 v[104:107], v[164:167], v[190:193], v[104:107]
	v_mfma_f32_16x16x32_bf16 v[104:107], v[170:173], v[194:197], v[104:107]
	v_mfma_f32_16x16x32_bf16 v[96:99], v[174:177], v[190:193], v[96:99]
	v_mfma_f32_16x16x32_bf16 v[96:99], v[178:181], v[194:197], v[96:99]
	v_mfma_f32_16x16x32_bf16 v[88:91], v[164:167], v[198:201], v[88:91]
	v_mfma_f32_16x16x32_bf16 v[88:91], v[170:173], v[202:205], v[88:91]
	v_mfma_f32_16x16x32_bf16 v[80:83], v[174:177], v[198:201], v[80:83]
	v_mfma_f32_16x16x32_bf16 v[80:83], v[178:181], v[202:205], v[80:83]
	v_mfma_f32_16x16x32_bf16 v[72:75], v[164:167], v[206:209], v[72:75]
	v_mfma_f32_16x16x32_bf16 v[72:75], v[170:173], v[210:213], v[72:75]
	v_mfma_f32_16x16x32_bf16 v[64:67], v[174:177], v[206:209], v[64:67]
	v_mfma_f32_16x16x32_bf16 v[64:67], v[178:181], v[210:213], v[64:67]
	s_setprio 0
	s_barrier
	s_add_i32 s56, s46, s33
	v_lshl_add_u64 v[214:215], s[2:3], 0, v[134:135]
	s_mov_b32 m0, s56
	ds_read_b128 v[182:185], v147 offset:16384
	ds_read_b128 v[186:189], v147 offset:17408
	ds_read_b128 v[190:193], v147 offset:18432
	ds_read_b128 v[194:197], v147 offset:19456
	ds_read_b128 v[198:201], v147 offset:20480
	ds_read_b128 v[202:205], v147 offset:21504
	ds_read_b128 v[206:209], v147 offset:22528
	ds_read_b128 v[210:213], v147 offset:23552
	global_load_lds_dwordx4 v[214:215], off
	s_add_i32 m0, s56, 0x2000
	s_add_u32 s56, s2, 0x2b0000
	v_lshl_add_u64 v[216:217], s[2:3], 0, v[138:139]
	s_addc_u32 s57, s3, 0
	s_add_i32 s58, s47, s33
	global_load_lds_dwordx4 v[216:217], off
	v_lshl_add_u64 v[218:219], s[56:57], 0, v[134:135]
	s_mov_b32 m0, s58
	v_lshl_add_u64 v[220:221], s[34:35], 0, v[136:137]
	global_load_lds_dwordx4 v[218:219], off
	v_lshl_add_u64 v[218:219], s[56:57], 0, v[138:139]
	s_add_i32 m0, s58, 0x2000
	s_nop 0
	global_load_lds_dwordx4 v[218:219], off
	v_lshl_add_u64 v[218:219], s[34:35], 0, v[128:129]
	s_mov_b32 m0, s37
	s_nop 0
	global_load_lds_dwordx4 v[218:219], off
	s_mov_b32 m0, s38
	s_nop 0
	global_load_lds_dwordx4 v[220:221], off
	s_waitcnt vmcnt(8)
	s_waitcnt lgkmcnt(0)
	s_barrier
	s_setprio 1
	s_waitcnt lgkmcnt(0)
	v_mfma_f32_16x16x32_bf16 v[60:63], v[148:151], v[182:185], v[60:63]
	v_mfma_f32_16x16x32_bf16 v[60:63], v[152:155], v[186:189], v[60:63]
	v_mfma_f32_16x16x32_bf16 v[52:55], v[156:159], v[182:185], v[52:55]
	v_mfma_f32_16x16x32_bf16 v[52:55], v[160:163], v[186:189], v[52:55]
	v_mfma_f32_16x16x32_bf16 v[44:47], v[148:151], v[190:193], v[44:47]
	v_mfma_f32_16x16x32_bf16 v[44:47], v[152:155], v[194:197], v[44:47]
	v_mfma_f32_16x16x32_bf16 v[36:39], v[156:159], v[190:193], v[36:39]
	v_mfma_f32_16x16x32_bf16 v[36:39], v[160:163], v[194:197], v[36:39]
	v_mfma_f32_16x16x32_bf16 v[28:31], v[148:151], v[198:201], v[28:31]
	v_mfma_f32_16x16x32_bf16 v[28:31], v[152:155], v[202:205], v[28:31]
	v_mfma_f32_16x16x32_bf16 v[20:23], v[156:159], v[198:201], v[20:23]
	v_mfma_f32_16x16x32_bf16 v[20:23], v[160:163], v[202:205], v[20:23]
	v_mfma_f32_16x16x32_bf16 v[12:15], v[148:151], v[206:209], v[12:15]
	v_mfma_f32_16x16x32_bf16 v[12:15], v[152:155], v[210:213], v[12:15]
	v_mfma_f32_16x16x32_bf16 v[4:7], v[156:159], v[206:209], v[4:7]
	v_mfma_f32_16x16x32_bf16 v[4:7], v[160:163], v[210:213], v[4:7]
	s_setprio 0
	s_setprio 1
	v_mfma_f32_16x16x32_bf16 v[56:59], v[164:167], v[182:185], v[56:59]
	v_mfma_f32_16x16x32_bf16 v[56:59], v[170:173], v[186:189], v[56:59]
	v_mfma_f32_16x16x32_bf16 v[48:51], v[174:177], v[182:185], v[48:51]
	v_mfma_f32_16x16x32_bf16 v[48:51], v[178:181], v[186:189], v[48:51]
	v_mfma_f32_16x16x32_bf16 v[40:43], v[164:167], v[190:193], v[40:43]
	v_mfma_f32_16x16x32_bf16 v[40:43], v[170:173], v[194:197], v[40:43]
	v_mfma_f32_16x16x32_bf16 v[32:35], v[174:177], v[190:193], v[32:35]
	v_mfma_f32_16x16x32_bf16 v[32:35], v[178:181], v[194:197], v[32:35]
	v_mfma_f32_16x16x32_bf16 v[24:27], v[164:167], v[198:201], v[24:27]
	v_mfma_f32_16x16x32_bf16 v[24:27], v[170:173], v[202:205], v[24:27]
	v_mfma_f32_16x16x32_bf16 v[16:19], v[174:177], v[198:201], v[16:19]
	v_mfma_f32_16x16x32_bf16 v[16:19], v[178:181], v[202:205], v[16:19]
	v_mfma_f32_16x16x32_bf16 v[8:11], v[164:167], v[206:209], v[8:11]
	v_mfma_f32_16x16x32_bf16 v[8:11], v[170:173], v[210:213], v[8:11]
	v_mfma_f32_16x16x32_bf16 v[0:3], v[174:177], v[206:209], v[0:3]
	v_mfma_f32_16x16x32_bf16 v[0:3], v[178:181], v[210:213], v[0:3]
	s_setprio 0
	s_barrier
	s_add_i32 s56, 0, 0x18000
	s_add_i32 s57, 0, 0x1c000
	v_add_u32_e32 v160, s56, v133
	v_add_u32_e32 v168, s57, v133
	ds_read_b128 v[148:151], v160
	ds_read_b128 v[152:155], v160 offset:1024
	ds_read_b128 v[156:159], v160 offset:2048
	ds_read_b128 v[160:163], v160 offset:3072
	ds_read_b128 v[164:167], v168
	ds_read_b128 v[170:173], v168 offset:1024
	ds_read_b128 v[174:177], v168 offset:2048
	ds_read_b128 v[178:181], v168 offset:3072
	s_add_u32 s34, s34, 0x2b0000
	s_addc_u32 s35, s35, 0
	s_mov_b32 m0, s39
	v_lshl_add_u64 v[222:223], s[34:35], 0, v[128:129]
	ds_read_b128 v[182:185], v147 offset:32768
	ds_read_b128 v[186:189], v147 offset:33792
	ds_read_b128 v[190:193], v147 offset:34816
	ds_read_b128 v[194:197], v147 offset:35840
	ds_read_b128 v[198:201], v147 offset:36864
	ds_read_b128 v[202:205], v147 offset:37888
	ds_read_b128 v[206:209], v147 offset:38912
	ds_read_b128 v[210:213], v147 offset:39936
	global_load_lds_dwordx4 v[222:223], off
	v_lshl_add_u64 v[222:223], s[34:35], 0, v[136:137]
	s_mov_b32 m0, s40
	s_nop 0
	global_load_lds_dwordx4 v[222:223], off
	s_waitcnt vmcnt(8)
	s_waitcnt lgkmcnt(0)
	s_barrier
	s_setprio 1
	s_waitcnt lgkmcnt(0)
	v_mfma_f32_16x16x32_bf16 v[124:127], v[148:151], v[182:185], v[124:127]
	v_mfma_f32_16x16x32_bf16 v[124:127], v[152:155], v[186:189], v[124:127]
	v_mfma_f32_16x16x32_bf16 v[120:123], v[156:159], v[182:185], v[120:123]
	v_mfma_f32_16x16x32_bf16 v[120:123], v[160:163], v[186:189], v[120:123]
	v_mfma_f32_16x16x32_bf16 v[108:111], v[148:151], v[190:193], v[108:111]
	v_mfma_f32_16x16x32_bf16 v[108:111], v[152:155], v[194:197], v[108:111]
	v_mfma_f32_16x16x32_bf16 v[100:103], v[156:159], v[190:193], v[100:103]
	v_mfma_f32_16x16x32_bf16 v[100:103], v[160:163], v[194:197], v[100:103]
	v_mfma_f32_16x16x32_bf16 v[92:95], v[148:151], v[198:201], v[92:95]
	v_mfma_f32_16x16x32_bf16 v[92:95], v[152:155], v[202:205], v[92:95]
	v_mfma_f32_16x16x32_bf16 v[84:87], v[156:159], v[198:201], v[84:87]
	v_mfma_f32_16x16x32_bf16 v[84:87], v[160:163], v[202:205], v[84:87]
	v_mfma_f32_16x16x32_bf16 v[76:79], v[148:151], v[206:209], v[76:79]
	v_mfma_f32_16x16x32_bf16 v[76:79], v[152:155], v[210:213], v[76:79]
	v_mfma_f32_16x16x32_bf16 v[68:71], v[156:159], v[206:209], v[68:71]
	v_mfma_f32_16x16x32_bf16 v[68:71], v[160:163], v[210:213], v[68:71]
	s_setprio 0
	s_setprio 1
	v_mfma_f32_16x16x32_bf16 v[116:119], v[164:167], v[182:185], v[116:119]
	v_mfma_f32_16x16x32_bf16 v[116:119], v[170:173], v[186:189], v[116:119]
	v_mfma_f32_16x16x32_bf16 v[112:115], v[174:177], v[182:185], v[112:115]
	v_mfma_f32_16x16x32_bf16 v[112:115], v[178:181], v[186:189], v[112:115]
	v_mfma_f32_16x16x32_bf16 v[104:107], v[164:167], v[190:193], v[104:107]
	v_mfma_f32_16x16x32_bf16 v[104:107], v[170:173], v[194:197], v[104:107]
	v_mfma_f32_16x16x32_bf16 v[96:99], v[174:177], v[190:193], v[96:99]
	v_mfma_f32_16x16x32_bf16 v[96:99], v[178:181], v[194:197], v[96:99]
	v_mfma_f32_16x16x32_bf16 v[88:91], v[164:167], v[198:201], v[88:91]
	v_mfma_f32_16x16x32_bf16 v[88:91], v[170:173], v[202:205], v[88:91]
	v_mfma_f32_16x16x32_bf16 v[80:83], v[174:177], v[198:201], v[80:83]
	v_mfma_f32_16x16x32_bf16 v[80:83], v[178:181], v[202:205], v[80:83]
	v_mfma_f32_16x16x32_bf16 v[72:75], v[164:167], v[206:209], v[72:75]
	v_mfma_f32_16x16x32_bf16 v[72:75], v[170:173], v[210:213], v[72:75]
	v_mfma_f32_16x16x32_bf16 v[64:67], v[174:177], v[206:209], v[64:67]
	v_mfma_f32_16x16x32_bf16 v[64:67], v[178:181], v[210:213], v[64:67]
	s_setprio 0
	s_barrier
	s_add_i32 s34, s56, s33
	v_lshl_add_u64 v[214:215], v[214:215], 0, s[6:7]
	s_mov_b32 m0, s34
	ds_read_b128 v[182:185], v147 offset:49152
	ds_read_b128 v[186:189], v147 offset:50176
	ds_read_b128 v[190:193], v147 offset:51200
	ds_read_b128 v[194:197], v147 offset:52224
	ds_read_b128 v[198:201], v147 offset:53248
	ds_read_b128 v[202:205], v147 offset:54272
	ds_read_b128 v[206:209], v147 offset:55296
	ds_read_b128 v[210:213], v147 offset:56320
	global_load_lds_dwordx4 v[214:215], off
	s_add_i32 m0, s34, 0x2000
	s_add_u32 s2, s2, 0x2b0080
	v_lshl_add_u64 v[214:215], v[216:217], 0, s[6:7]
	s_addc_u32 s3, s3, 0
	s_add_i32 s34, s57, s33
	global_load_lds_dwordx4 v[214:215], off
	v_lshl_add_u64 v[214:215], s[2:3], 0, v[134:135]
	s_mov_b32 m0, s34
	s_nop 0
	global_load_lds_dwordx4 v[214:215], off
	v_lshl_add_u64 v[214:215], s[2:3], 0, v[138:139]
	s_add_i32 m0, s34, 0x2000
	s_nop 0
	global_load_lds_dwordx4 v[214:215], off
	v_lshl_add_u64 v[214:215], v[218:219], 0, s[6:7]
	s_mov_b32 m0, s42
	s_nop 0
	global_load_lds_dwordx4 v[214:215], off
	v_lshl_add_u64 v[214:215], v[220:221], 0, s[6:7]
	s_mov_b32 m0, s43
	s_nop 0
	global_load_lds_dwordx4 v[214:215], off
	s_waitcnt vmcnt(8)
	s_waitcnt lgkmcnt(0)
	s_barrier
	s_setprio 1
	s_waitcnt lgkmcnt(0)
	v_mfma_f32_16x16x32_bf16 v[60:63], v[148:151], v[182:185], v[60:63]
	v_mfma_f32_16x16x32_bf16 v[60:63], v[152:155], v[186:189], v[60:63]
	v_mfma_f32_16x16x32_bf16 v[52:55], v[156:159], v[182:185], v[52:55]
	v_mfma_f32_16x16x32_bf16 v[52:55], v[160:163], v[186:189], v[52:55]
	v_mfma_f32_16x16x32_bf16 v[44:47], v[148:151], v[190:193], v[44:47]
	v_mfma_f32_16x16x32_bf16 v[44:47], v[152:155], v[194:197], v[44:47]
	v_mfma_f32_16x16x32_bf16 v[36:39], v[156:159], v[190:193], v[36:39]
	v_mfma_f32_16x16x32_bf16 v[36:39], v[160:163], v[194:197], v[36:39]
	v_mfma_f32_16x16x32_bf16 v[28:31], v[148:151], v[198:201], v[28:31]
	v_mfma_f32_16x16x32_bf16 v[28:31], v[152:155], v[202:205], v[28:31]
	v_mfma_f32_16x16x32_bf16 v[20:23], v[156:159], v[198:201], v[20:23]
	v_mfma_f32_16x16x32_bf16 v[20:23], v[160:163], v[202:205], v[20:23]
	v_mfma_f32_16x16x32_bf16 v[12:15], v[148:151], v[206:209], v[12:15]
	v_mfma_f32_16x16x32_bf16 v[12:15], v[152:155], v[210:213], v[12:15]
	v_mfma_f32_16x16x32_bf16 v[4:7], v[156:159], v[206:209], v[4:7]
	v_mfma_f32_16x16x32_bf16 v[4:7], v[160:163], v[210:213], v[4:7]
	s_setprio 0
	s_setprio 1
	v_mfma_f32_16x16x32_bf16 v[56:59], v[164:167], v[182:185], v[56:59]
	v_mfma_f32_16x16x32_bf16 v[56:59], v[170:173], v[186:189], v[56:59]
	v_mfma_f32_16x16x32_bf16 v[48:51], v[174:177], v[182:185], v[48:51]
	v_mfma_f32_16x16x32_bf16 v[48:51], v[178:181], v[186:189], v[48:51]
	v_mfma_f32_16x16x32_bf16 v[40:43], v[164:167], v[190:193], v[40:43]
	v_mfma_f32_16x16x32_bf16 v[40:43], v[170:173], v[194:197], v[40:43]
	v_mfma_f32_16x16x32_bf16 v[32:35], v[174:177], v[190:193], v[32:35]
	v_mfma_f32_16x16x32_bf16 v[32:35], v[178:181], v[194:197], v[32:35]
	v_mfma_f32_16x16x32_bf16 v[24:27], v[164:167], v[198:201], v[24:27]
	v_mfma_f32_16x16x32_bf16 v[24:27], v[170:173], v[202:205], v[24:27]
	v_mfma_f32_16x16x32_bf16 v[16:19], v[174:177], v[198:201], v[16:19]
	v_mfma_f32_16x16x32_bf16 v[16:19], v[178:181], v[202:205], v[16:19]
	v_mfma_f32_16x16x32_bf16 v[8:11], v[164:167], v[206:209], v[8:11]
	v_mfma_f32_16x16x32_bf16 v[8:11], v[170:173], v[210:213], v[8:11]
	v_mfma_f32_16x16x32_bf16 v[0:3], v[174:177], v[206:209], v[0:3]
	v_mfma_f32_16x16x32_bf16 v[0:3], v[178:181], v[210:213], v[0:3]
	s_setprio 0
	s_barrier
	s_add_u32 s30, s30, 0x100
	s_addc_u32 s31, s31, 0
	s_add_u32 s28, s28, 0x100
	s_addc_u32 s52, s52, 0
	s_cmp_ge_i32 s53, s29
	s_mov_b32 s2, s53
	s_cbranch_scc0 .LBB0_1128
